# combo13 + slots B/D issue all four LDS-DMA loads before the 8 fragment reads
# speedup vs baseline: 1.0099x; 1.0047x over previous
; #define PG8_STAGE(bufoff, gbase, voff) do { _Pragma("unroll") for (int _i = 0; _i < 2; ++_i) \
;     __builtin_amdgcn_global_load_lds((const unsigned*)((const char*)(gbase) + (voff)[_i]), (LAS unsigned*)(lds + (bufoff) + ldsw + _i * 8192), 16, 0, 0); } while (0)
; #define PG8_LDA(dst, b, h) do { _Pragma("unroll") for (int m = 0; m < 4; ++m) _Pragma("unroll") for (int k = 0; k < 2; ++k) dst[m][k] = *(const LAS bf16x8*)(lds + PG8_SA(b, h) + aoff + m * 2048 + k * 1024); } while (0)
; #define PG8_LDB(dst, b, h) do { _Pragma("unroll") for (int n = 0; n < 2; ++n) _Pragma("unroll") for (int k = 0; k < 2; ++k) dst[n][k] = *(const LAS bf16x8*)(lds + PG8_SB(b, h) + boff + n * 2048 + k * 1024); } while (0)
; #define PG8_MMA(ai, bj, At, Bt) do { __builtin_amdgcn_s_setprio(1); _Pragma("unroll") for (int m = 0; m < 4; ++m) _Pragma("unroll") for (int n = 0; n < 2; ++n) _Pragma("unroll") for (int k = 0; k < 2; ++k) \
;     acc[ai][bj][m][n] = __builtin_amdgcn_mfma_f32_16x16x32_bf16(Bt[n][k], At[m][k], acc[ai][bj][m][n], 0, 0, 0); __builtin_amdgcn_s_setprio(0); } while (0)
; #define PG8_WAIT_V(n) asm volatile("s_waitcnt vmcnt(" #n ")" ::: "memory")
; #define PG8_WAIT_L(n) asm volatile("s_waitcnt lgkmcnt(" #n ")" ::: "memory")
; #define PG8_BAR __builtin_amdgcn_s_barrier()
; #define PG8_SCHED __builtin_amdgcn_sched_barrier(0)
; template <class Epi, class Sched = StaticOrder>
; DI void gemm_phase(LAS unsigned char* lds, const Gemm g, const Sched& S, const Epi& E) {
;     ...
;       PG8_LDB(B0, 0, 0); PG8_SCHED; PG8_LDA(At, 0, 0); PG8_STAGE(PG8_SA(1, 1), a1 + hstep, voffA);
;       PG8_WAIT_L(8); PG8_BAR; PG8_WAIT_L(0); PG8_MMA(0, 0, At, B0); PG8_BAR; PG8_SCHED;
;       PG8_LDB(B1, 0, 1); PG8_STAGE(PG8_SB(0, 0), b2, voffB);
;       PG8_BAR; PG8_WAIT_L(0); PG8_MMA(0, 1, At, B1); PG8_BAR;
;       PG8_LDA(At, 0, 1); PG8_STAGE(PG8_SA(0, 0), a2, voffA);
;       PG8_BAR; PG8_WAIT_L(0); PG8_MMA(1, 0, At, B0); PG8_BAR; PG8_SCHED;
;       PG8_STAGE(PG8_SB(0, 1), b2 + hstep, voffB);
;       PG8_WAIT_V(6); PG8_BAR; PG8_MMA(1, 1, At, B1); PG8_BAR;
.LBB0_346:
	ds_read_b128 v[128:131], v173
	ds_read_b128 v[132:135], v173 offset:1024
	ds_read_b128 v[154:157], v173 offset:2048
	ds_read_b128 v[158:161], v173 offset:3072
	s_add_u32 s8, s6, 0xfff80080
	s_addc_u32 s9, s7, -1
	s_cmp_eq_u32 s52, 28
	s_cselect_b32 s11, s31, s9
	s_cselect_b32 s10, s42, s8
	s_cselect_b32 s9, s29, s45
	s_cselect_b32 s8, s43, s44
	s_add_i32 m0, s48, 0xc000
	ds_read_b128 v[162:165], v174
	ds_read_b128 v[166:169], v174 offset:1024
	ds_read_b128 v[178:181], v174 offset:2048
	ds_read_b128 v[182:185], v174 offset:3072
	ds_read_b128 v[186:189], v174 offset:4096
	ds_read_b128 v[190:193], v174 offset:5120
	ds_read_b128 v[194:197], v174 offset:6144
	ds_read_b128 v[198:201], v174 offset:7168
	global_load_lds_dwordx4 v146, s[6:7]
	s_add_i32 m0, s48, 0xe000
	s_nop 0
	global_load_lds_dwordx4 v148, s[6:7]
	ds_read_b128 v[202:205], v175
	ds_read_b128 v[206:209], v175 offset:1024
	ds_read_b128 v[212:215], v175 offset:2048
	ds_read_b128 v[216:219], v175 offset:3072
	s_waitcnt vmcnt(8)
	s_waitcnt lgkmcnt(4)
	s_setprio 1
	s_barrier
	v_mfma_f32_16x16x32_bf16 v[124:127], v[128:131], v[162:165], v[124:127]
	v_mfma_f32_16x16x32_bf16 v[120:123], v[154:157], v[162:165], v[120:123]
	v_mfma_f32_16x16x32_bf16 v[108:111], v[128:131], v[178:181], v[108:111]
	v_mfma_f32_16x16x32_bf16 v[104:107], v[154:157], v[178:181], v[104:107]
	v_mfma_f32_16x16x32_bf16 v[100:103], v[128:131], v[186:189], v[100:103]
	v_mfma_f32_16x16x32_bf16 v[92:95], v[154:157], v[186:189], v[92:95]
	v_mfma_f32_16x16x32_bf16 v[84:87], v[128:131], v[194:197], v[84:87]
	v_mfma_f32_16x16x32_bf16 v[76:79], v[154:157], v[194:197], v[76:79]
	v_mfma_f32_16x16x32_bf16 v[124:127], v[132:135], v[166:169], v[124:127]
	v_mfma_f32_16x16x32_bf16 v[120:123], v[158:161], v[166:169], v[120:123]
	v_mfma_f32_16x16x32_bf16 v[108:111], v[132:135], v[182:185], v[108:111]
	v_mfma_f32_16x16x32_bf16 v[104:107], v[158:161], v[182:185], v[104:107]
	v_mfma_f32_16x16x32_bf16 v[100:103], v[132:135], v[190:193], v[100:103]
	v_mfma_f32_16x16x32_bf16 v[92:95], v[158:161], v[190:193], v[92:95]
	v_mfma_f32_16x16x32_bf16 v[84:87], v[132:135], v[198:201], v[84:87]
	v_mfma_f32_16x16x32_bf16 v[76:79], v[158:161], v[198:201], v[76:79]
	s_waitcnt lgkmcnt(0)
	v_mfma_f32_16x16x32_bf16 v[116:119], v[202:205], v[162:165], v[116:119]
	v_mfma_f32_16x16x32_bf16 v[112:115], v[212:215], v[162:165], v[112:115]
	v_mfma_f32_16x16x32_bf16 v[96:99], v[202:205], v[178:181], v[96:99]
	v_mfma_f32_16x16x32_bf16 v[88:91], v[212:215], v[178:181], v[88:91]
	v_mfma_f32_16x16x32_bf16 v[80:83], v[202:205], v[186:189], v[80:83]
	v_mfma_f32_16x16x32_bf16 v[72:75], v[212:215], v[186:189], v[72:75]
	v_mfma_f32_16x16x32_bf16 v[68:71], v[202:205], v[194:197], v[68:71]
	v_mfma_f32_16x16x32_bf16 v[64:67], v[212:215], v[194:197], v[64:67]
	v_mfma_f32_16x16x32_bf16 v[116:119], v[206:209], v[166:169], v[116:119]
	v_mfma_f32_16x16x32_bf16 v[112:115], v[216:219], v[166:169], v[112:115]
	v_mfma_f32_16x16x32_bf16 v[96:99], v[206:209], v[182:185], v[96:99]
	v_mfma_f32_16x16x32_bf16 v[88:91], v[216:219], v[182:185], v[88:91]
	v_mfma_f32_16x16x32_bf16 v[80:83], v[206:209], v[190:193], v[80:83]
	v_mfma_f32_16x16x32_bf16 v[72:75], v[216:219], v[190:193], v[72:75]
	v_mfma_f32_16x16x32_bf16 v[68:71], v[206:209], v[198:201], v[68:71]
	v_mfma_f32_16x16x32_bf16 v[64:67], v[216:219], v[198:201], v[64:67]
	s_barrier
	s_setprio 0
	s_add_i32 s53, s65, s41
	s_add_u32 s98, s8, 0x80
	s_addc_u32 s99, s9, 0
	s_add_u32 s100, s10, 0x80
	s_addc_u32 s101, s11, 0
	s_mov_b32 m0, s53
	s_nop 0
	global_load_lds_dwordx4 v140, s[8:9]
	s_add_i32 m0, s53, 0x2000
	s_nop 0
	global_load_lds_dwordx4 v136, s[8:9]
	s_mov_b32 m0, s48
	s_nop 0
	global_load_lds_dwordx4 v142, s[10:11]
	s_mov_b32 m0, s49
	s_nop 0
	global_load_lds_dwordx4 v138, s[10:11]
	ds_read_b128 v[162:165], v174 offset:16384
	ds_read_b128 v[166:169], v174 offset:17408
	ds_read_b128 v[178:181], v174 offset:18432
	ds_read_b128 v[182:185], v174 offset:19456
	ds_read_b128 v[186:189], v174 offset:20480
	ds_read_b128 v[190:193], v174 offset:21504
	ds_read_b128 v[194:197], v174 offset:22528
	ds_read_b128 v[198:201], v174 offset:23552
	s_add_u32 s54, s8, 0x80000
	s_addc_u32 s55, s9, 0
	s_add_i32 s53, s72, s41
	s_waitcnt vmcnt(6)
	s_waitcnt lgkmcnt(0)
	s_setprio 1
	s_barrier
	v_mfma_f32_16x16x32_bf16 v[60:63], v[128:131], v[162:165], v[60:63]
	s_mov_b32 m0, s53
	v_mfma_f32_16x16x32_bf16 v[56:59], v[154:157], v[162:165], v[56:59]
	global_load_lds_dwordx4 v140, s[54:55]
	v_mfma_f32_16x16x32_bf16 v[52:55], v[128:131], v[178:181], v[52:55]
	s_bitset1_b32 m0, 13
	v_mfma_f32_16x16x32_bf16 v[44:47], v[154:157], v[178:181], v[44:47]
	global_load_lds_dwordx4 v136, s[54:55]
	v_mfma_f32_16x16x32_bf16 v[36:39], v[128:131], v[186:189], v[36:39]
	v_mfma_f32_16x16x32_bf16 v[28:31], v[154:157], v[186:189], v[28:31]
	v_mfma_f32_16x16x32_bf16 v[20:23], v[128:131], v[194:197], v[20:23]
	v_mfma_f32_16x16x32_bf16 v[12:15], v[154:157], v[194:197], v[12:15]
	v_mfma_f32_16x16x32_bf16 v[60:63], v[132:135], v[166:169], v[60:63]
	v_mfma_f32_16x16x32_bf16 v[56:59], v[158:161], v[166:169], v[56:59]
	v_mfma_f32_16x16x32_bf16 v[52:55], v[132:135], v[182:185], v[52:55]
	v_mfma_f32_16x16x32_bf16 v[44:47], v[158:161], v[182:185], v[44:47]
	v_mfma_f32_16x16x32_bf16 v[36:39], v[132:135], v[190:193], v[36:39]
	v_mfma_f32_16x16x32_bf16 v[28:31], v[158:161], v[190:193], v[28:31]
	v_mfma_f32_16x16x32_bf16 v[20:23], v[132:135], v[198:201], v[20:23]
	v_mfma_f32_16x16x32_bf16 v[12:15], v[158:161], v[198:201], v[12:15]
	v_mfma_f32_16x16x32_bf16 v[48:51], v[202:205], v[162:165], v[48:51]
	v_mfma_f32_16x16x32_bf16 v[40:43], v[212:215], v[162:165], v[40:43]
	v_mfma_f32_16x16x32_bf16 v[32:35], v[202:205], v[178:181], v[32:35]
	v_mfma_f32_16x16x32_bf16 v[24:27], v[212:215], v[178:181], v[24:27]
	v_mfma_f32_16x16x32_bf16 v[16:19], v[202:205], v[186:189], v[16:19]
	v_mfma_f32_16x16x32_bf16 v[8:11], v[212:215], v[186:189], v[8:11]
	v_mfma_f32_16x16x32_bf16 v[4:7], v[202:205], v[194:197], v[4:7]
	v_mfma_f32_16x16x32_bf16 v[0:3], v[212:215], v[194:197], v[0:3]
	v_mfma_f32_16x16x32_bf16 v[48:51], v[206:209], v[166:169], v[48:51]
	v_mfma_f32_16x16x32_bf16 v[40:43], v[216:219], v[166:169], v[40:43]
	v_mfma_f32_16x16x32_bf16 v[32:35], v[206:209], v[182:185], v[32:35]
	v_mfma_f32_16x16x32_bf16 v[24:27], v[216:219], v[182:185], v[24:27]
	v_mfma_f32_16x16x32_bf16 v[16:19], v[206:209], v[190:193], v[16:19]
	v_mfma_f32_16x16x32_bf16 v[8:11], v[216:219], v[190:193], v[8:11]
	v_mfma_f32_16x16x32_bf16 v[4:7], v[206:209], v[198:201], v[4:7]
	v_mfma_f32_16x16x32_bf16 v[0:3], v[216:219], v[198:201], v[0:3]
	s_barrier
; #define PG8_STAGE(bufoff, gbase, voff) do { _Pragma("unroll") for (int _i = 0; _i < 2; ++_i) \
;     __builtin_amdgcn_global_load_lds((const unsigned*)((const char*)(gbase) + (voff)[_i]), (LAS unsigned*)(lds + (bufoff) + ldsw + _i * 8192), 16, 0, 0); } while (0)
; #define PG8_LDA(dst, b, h) do { _Pragma("unroll") for (int m = 0; m < 4; ++m) _Pragma("unroll") for (int k = 0; k < 2; ++k) dst[m][k] = *(const LAS bf16x8*)(lds + PG8_SA(b, h) + aoff + m * 2048 + k * 1024); } while (0)
; #define PG8_LDB(dst, b, h) do { _Pragma("unroll") for (int n = 0; n < 2; ++n) _Pragma("unroll") for (int k = 0; k < 2; ++k) dst[n][k] = *(const LAS bf16x8*)(lds + PG8_SB(b, h) + boff + n * 2048 + k * 1024); } while (0)
; #define PG8_MMA(ai, bj, At, Bt) do { __builtin_amdgcn_s_setprio(1); _Pragma("unroll") for (int m = 0; m < 4; ++m) _Pragma("unroll") for (int n = 0; n < 2; ++n) _Pragma("unroll") for (int k = 0; k < 2; ++k) \
;     acc[ai][bj][m][n] = __builtin_amdgcn_mfma_f32_16x16x32_bf16(Bt[n][k], At[m][k], acc[ai][bj][m][n], 0, 0, 0); __builtin_amdgcn_s_setprio(0); } while (0)
; #define PG8_WAIT_V(n) asm volatile("s_waitcnt vmcnt(" #n ")" ::: "memory")
; #define PG8_WAIT_L(n) asm volatile("s_waitcnt lgkmcnt(" #n ")" ::: "memory")
; #define PG8_BAR __builtin_amdgcn_s_barrier()
; #define PG8_SCHED __builtin_amdgcn_sched_barrier(0)
; template <class Epi, class Sched = StaticOrder>
; DI void gemm_phase(LAS unsigned char* lds, const Gemm g, const Sched& S, const Epi& E) {
;     ...
;       PG8_LDB(B0, 1, 0); PG8_SCHED; PG8_LDA(At, 1, 0); PG8_STAGE(PG8_SA(0, 1), a2 + hstep, voffA);
;       PG8_WAIT_L(8); PG8_BAR; PG8_WAIT_L(0); PG8_MMA(0, 0, At, B0); PG8_BAR; PG8_SCHED;
;       PG8_LDB(B1, 1, 1); PG8_STAGE(PG8_SB(1, 0), b3, voffB);
;       PG8_BAR; PG8_WAIT_L(0); PG8_MMA(0, 1, At, B1); PG8_BAR;
;       PG8_LDA(At, 1, 1); PG8_STAGE(PG8_SA(1, 0), a3, voffA);
;       PG8_BAR; PG8_WAIT_L(0); PG8_MMA(1, 0, At, B0); PG8_BAR; PG8_SCHED;
;       PG8_STAGE(PG8_SB(1, 1), b3 + hstep, voffB);
;       PG8_WAIT_V(6); PG8_BAR; PG8_MMA(1, 1, At, B1); PG8_BAR;
	s_setprio 0
	s_add_i32 s53, 0, 0x18000
	v_add_u32_e32 v158, s53, v171
	ds_read_b128 v[128:131], v158
	ds_read_b128 v[132:135], v158 offset:1024
	ds_read_b128 v[154:157], v158 offset:2048
	ds_read_b128 v[158:161], v158 offset:3072
	s_add_u32 s10, s10, 0x80000
	s_addc_u32 s11, s11, 0
	s_mov_b32 m0, s50
	ds_read_b128 v[162:165], v174 offset:32768
	ds_read_b128 v[166:169], v174 offset:33792
	ds_read_b128 v[178:181], v174 offset:34816
	ds_read_b128 v[182:185], v174 offset:35840
	ds_read_b128 v[186:189], v174 offset:36864
	ds_read_b128 v[190:193], v174 offset:37888
	ds_read_b128 v[194:197], v174 offset:38912
	ds_read_b128 v[198:201], v174 offset:39936
	global_load_lds_dwordx4 v142, s[10:11]
	s_mov_b32 m0, s51
	s_nop 0
	global_load_lds_dwordx4 v138, s[10:11]
	s_add_i32 s10, 0, 0x1c000
	v_add_u32_e32 v177, s10, v171
	ds_read_b128 v[202:205], v177
	ds_read_b128 v[206:209], v177 offset:1024
	ds_read_b128 v[212:215], v177 offset:2048
	ds_read_b128 v[216:219], v177 offset:3072
	s_waitcnt vmcnt(8)
	s_waitcnt lgkmcnt(4)
	s_setprio 1
	s_barrier
	v_mfma_f32_16x16x32_bf16 v[124:127], v[128:131], v[162:165], v[124:127]
	v_mfma_f32_16x16x32_bf16 v[120:123], v[154:157], v[162:165], v[120:123]
	v_mfma_f32_16x16x32_bf16 v[108:111], v[128:131], v[178:181], v[108:111]
	v_mfma_f32_16x16x32_bf16 v[104:107], v[154:157], v[178:181], v[104:107]
	v_mfma_f32_16x16x32_bf16 v[100:103], v[128:131], v[186:189], v[100:103]
	v_mfma_f32_16x16x32_bf16 v[92:95], v[154:157], v[186:189], v[92:95]
	v_mfma_f32_16x16x32_bf16 v[84:87], v[128:131], v[194:197], v[84:87]
	v_mfma_f32_16x16x32_bf16 v[76:79], v[154:157], v[194:197], v[76:79]
	v_mfma_f32_16x16x32_bf16 v[124:127], v[132:135], v[166:169], v[124:127]
	v_mfma_f32_16x16x32_bf16 v[120:123], v[158:161], v[166:169], v[120:123]
	v_mfma_f32_16x16x32_bf16 v[108:111], v[132:135], v[182:185], v[108:111]
	v_mfma_f32_16x16x32_bf16 v[104:107], v[158:161], v[182:185], v[104:107]
	v_mfma_f32_16x16x32_bf16 v[100:103], v[132:135], v[190:193], v[100:103]
	v_mfma_f32_16x16x32_bf16 v[92:95], v[158:161], v[190:193], v[92:95]
	v_mfma_f32_16x16x32_bf16 v[84:87], v[132:135], v[198:201], v[84:87]
	v_mfma_f32_16x16x32_bf16 v[76:79], v[158:161], v[198:201], v[76:79]
	s_waitcnt lgkmcnt(0)
	v_mfma_f32_16x16x32_bf16 v[116:119], v[202:205], v[162:165], v[116:119]
	v_mfma_f32_16x16x32_bf16 v[112:115], v[212:215], v[162:165], v[112:115]
	v_mfma_f32_16x16x32_bf16 v[96:99], v[202:205], v[178:181], v[96:99]
	v_mfma_f32_16x16x32_bf16 v[88:91], v[212:215], v[178:181], v[88:91]
	v_mfma_f32_16x16x32_bf16 v[80:83], v[202:205], v[186:189], v[80:83]
	v_mfma_f32_16x16x32_bf16 v[72:75], v[212:215], v[186:189], v[72:75]
	v_mfma_f32_16x16x32_bf16 v[68:71], v[202:205], v[194:197], v[68:71]
	v_mfma_f32_16x16x32_bf16 v[64:67], v[212:215], v[194:197], v[64:67]
	v_mfma_f32_16x16x32_bf16 v[116:119], v[206:209], v[166:169], v[116:119]
	v_mfma_f32_16x16x32_bf16 v[112:115], v[216:219], v[166:169], v[112:115]
	v_mfma_f32_16x16x32_bf16 v[96:99], v[206:209], v[182:185], v[96:99]
	v_mfma_f32_16x16x32_bf16 v[88:91], v[216:219], v[182:185], v[88:91]
	v_mfma_f32_16x16x32_bf16 v[80:83], v[206:209], v[190:193], v[80:83]
	v_mfma_f32_16x16x32_bf16 v[72:75], v[216:219], v[190:193], v[72:75]
	v_mfma_f32_16x16x32_bf16 v[68:71], v[206:209], v[198:201], v[68:71]
	v_mfma_f32_16x16x32_bf16 v[64:67], v[216:219], v[198:201], v[64:67]
	s_barrier
	s_setprio 0
	s_add_i32 s11, s53, s41
	s_mov_b32 m0, s11
	s_nop 0
	global_load_lds_dwordx4 v140, s[98:99]
	s_add_i32 m0, s11, 0x2000
	s_nop 0
	global_load_lds_dwordx4 v136, s[98:99]
	s_mov_b32 m0, s56
	s_nop 0
	global_load_lds_dwordx4 v142, s[100:101]
	s_mov_b32 m0, s57
	s_nop 0
	global_load_lds_dwordx4 v138, s[100:101]
	ds_read_b128 v[162:165], v174 offset:49152
	ds_read_b128 v[166:169], v174 offset:50176
	ds_read_b128 v[178:181], v174 offset:51200
	ds_read_b128 v[182:185], v174 offset:52224
	ds_read_b128 v[186:189], v174 offset:53248
	ds_read_b128 v[190:193], v174 offset:54272
	ds_read_b128 v[194:197], v174 offset:55296
	ds_read_b128 v[198:201], v174 offset:56320
	s_add_u32 s8, s8, 0x80080
	s_addc_u32 s9, s9, 0
	s_add_i32 s10, s10, s41
	s_add_i32 s52, s52, 2
	s_add_u32 s6, s6, 0x100
	s_addc_u32 s7, s7, 0
	s_add_u32 s44, s44, 0x100
	s_addc_u32 s45, s45, 0
	s_cmp_gt_u32 s52, 29
	s_waitcnt vmcnt(6)
	s_waitcnt lgkmcnt(0)
	s_setprio 1
	s_barrier
	v_mfma_f32_16x16x32_bf16 v[60:63], v[128:131], v[162:165], v[60:63]
	s_mov_b32 m0, s10
	v_mfma_f32_16x16x32_bf16 v[56:59], v[154:157], v[162:165], v[56:59]
	global_load_lds_dwordx4 v140, s[8:9]
	v_mfma_f32_16x16x32_bf16 v[52:55], v[128:131], v[178:181], v[52:55]
	s_bitset1_b32 m0, 13
	v_mfma_f32_16x16x32_bf16 v[44:47], v[154:157], v[178:181], v[44:47]
	global_load_lds_dwordx4 v136, s[8:9]
	v_mfma_f32_16x16x32_bf16 v[36:39], v[128:131], v[186:189], v[36:39]
	v_mfma_f32_16x16x32_bf16 v[28:31], v[154:157], v[186:189], v[28:31]
	v_mfma_f32_16x16x32_bf16 v[20:23], v[128:131], v[194:197], v[20:23]
	v_mfma_f32_16x16x32_bf16 v[12:15], v[154:157], v[194:197], v[12:15]
	v_mfma_f32_16x16x32_bf16 v[60:63], v[132:135], v[166:169], v[60:63]
	v_mfma_f32_16x16x32_bf16 v[56:59], v[158:161], v[166:169], v[56:59]
	v_mfma_f32_16x16x32_bf16 v[52:55], v[132:135], v[182:185], v[52:55]
	v_mfma_f32_16x16x32_bf16 v[44:47], v[158:161], v[182:185], v[44:47]
	v_mfma_f32_16x16x32_bf16 v[36:39], v[132:135], v[190:193], v[36:39]
	v_mfma_f32_16x16x32_bf16 v[28:31], v[158:161], v[190:193], v[28:31]
	v_mfma_f32_16x16x32_bf16 v[20:23], v[132:135], v[198:201], v[20:23]
	v_mfma_f32_16x16x32_bf16 v[12:15], v[158:161], v[198:201], v[12:15]
	v_mfma_f32_16x16x32_bf16 v[48:51], v[202:205], v[162:165], v[48:51]
	v_mfma_f32_16x16x32_bf16 v[40:43], v[212:215], v[162:165], v[40:43]
	v_mfma_f32_16x16x32_bf16 v[32:35], v[202:205], v[178:181], v[32:35]
	v_mfma_f32_16x16x32_bf16 v[24:27], v[212:215], v[178:181], v[24:27]
	v_mfma_f32_16x16x32_bf16 v[16:19], v[202:205], v[186:189], v[16:19]
	v_mfma_f32_16x16x32_bf16 v[8:11], v[212:215], v[186:189], v[8:11]
	v_mfma_f32_16x16x32_bf16 v[4:7], v[202:205], v[194:197], v[4:7]
	v_mfma_f32_16x16x32_bf16 v[0:3], v[212:215], v[194:197], v[0:3]
	v_mfma_f32_16x16x32_bf16 v[48:51], v[206:209], v[166:169], v[48:51]
	v_mfma_f32_16x16x32_bf16 v[40:43], v[216:219], v[166:169], v[40:43]
	v_mfma_f32_16x16x32_bf16 v[32:35], v[206:209], v[182:185], v[32:35]
	v_mfma_f32_16x16x32_bf16 v[24:27], v[216:219], v[182:185], v[24:27]
	v_mfma_f32_16x16x32_bf16 v[16:19], v[206:209], v[190:193], v[16:19]
	v_mfma_f32_16x16x32_bf16 v[8:11], v[216:219], v[190:193], v[8:11]
	v_mfma_f32_16x16x32_bf16 v[4:7], v[206:209], v[198:201], v[4:7]
	v_mfma_f32_16x16x32_bf16 v[0:3], v[216:219], v[198:201], v[0:3]
	s_barrier
; DI unsigned pack2(float lo, float hi) { f32x2 v = {lo, hi}; bf16v2 r = __builtin_convertvector(v, bf16v2); return __builtin_bit_cast(unsigned, r); }
; DI float row_rstd(const float* ssq, int row, int fq) {
;   const f32x4 a = *(const f32x4*)(ssq + (size_t)row * 32 + fq * 8), b = *(const f32x4*)(ssq + (size_t)row * 32 + fq * 8 + 4);
;   float sm = ((a[0] + a[1]) + (a[2] + a[3])) + ((b[0] + b[1]) + (b[2] + b[3]));
;   sm += __shfl_xor(sm, 16); sm += __shfl_xor(sm, 32);
;   return rsqrtf(sm * (1.0f / 2048.f) + 1e-6f);
; }
;   DI void operator()(const f32x4 (&acc)[2][2][4][2], const Unit& u, int wr, int wc, int fr, int fq) const {
;     const int row0 = u.pm * BM + wr * 64 + fr, col0 = u.pn * BM + wc * 32 + 8 * fq;
;     float rsv[2][4];
; #pragma unroll
;     for (int ai = 0; ai < 2; ++ai)
; #pragma unroll
;       for (int m = 0; m < 4; ++m) rsv[ai][m] = row_rstd(ssq, row0 + ai * HALF + m * 16, fq);
; #pragma unroll
;     for (int ai = 0; ai < 2; ++ai)
; #pragma unroll
;       for (int m = 0; m < 4; ++m) {
;         const int row = row0 + ai * HALF + m * 16;
;         const float rs = rsv[ai][m];
;         bf16_t* rowp = O + (size_t)row * ldc + col0;
; #pragma unroll
;         for (int bj = 0; bj < 2; ++bj) {
;           const f32x4 v0 = acc[ai][bj][m][0] * rs, v1 = acc[ai][bj][m][1] * rs;
;           u32x4 w; w.x = pack2(v0[0], v0[1]); w.y = pack2(v0[2], v0[3]); w.z = pack2(v1[0], v1[1]); w.w = pack2(v1[2], v1[3]);
;           *(u32x4*)(rowp + bj * HALF) = w;
;         }
;       }
;   }
	s_setprio 0
	s_cbranch_scc0 .LBB0_346
	v_lshl_add_u32 v168, s4, 8, v170
	v_ashrrev_i32_e32 v169, 31, v168
	v_or_b32_e32 v154, 16, v168
	v_lshlrev_b64 v[128:129], 7, v[168:169]
	v_ashrrev_i32_e32 v155, 31, v154
	v_lshl_add_u64 v[128:129], v[144:145], 0, v[128:129]
	v_lshlrev_b64 v[156:157], 7, v[154:155]
	global_load_dwordx4 v[132:135], v[128:129], off
	s_nop 0
	global_load_dwordx4 v[128:131], v[128:129], off offset:16
	v_lshl_add_u64 v[156:157], v[144:145], 0, v[156:157]
	global_load_dwordx4 v[178:181], v[156:157], off
	global_load_dwordx4 v[182:185], v[156:157], off offset:16
	v_or_b32_e32 v160, 32, v168
	v_ashrrev_i32_e32 v161, 31, v160
	v_lshlrev_b64 v[156:157], 7, v[160:161]
	v_lshl_add_u64 v[156:157], v[144:145], 0, v[156:157]
	global_load_dwordx4 v[186:189], v[156:157], off
	global_load_dwordx4 v[190:193], v[156:157], off offset:16
	v_or_b32_e32 v156, 48, v168
	v_ashrrev_i32_e32 v157, 31, v156
	v_lshlrev_b64 v[158:159], 7, v[156:157]
	v_lshl_add_u64 v[158:159], v[144:145], 0, v[158:159]
	global_load_dwordx4 v[194:197], v[158:159], off
	global_load_dwordx4 v[198:201], v[158:159], off offset:16
	v_add_u32_e32 v164, 0x80, v168
	v_ashrrev_i32_e32 v165, 31, v164
	v_lshlrev_b64 v[158:159], 7, v[164:165]
	v_lshl_add_u64 v[158:159], v[144:145], 0, v[158:159]
	global_load_dwordx4 v[202:205], v[158:159], off
	global_load_dwordx4 v[206:209], v[158:159], off offset:16
	v_add_u32_e32 v158, 0x90, v168
	v_ashrrev_i32_e32 v159, 31, v158
	v_lshlrev_b64 v[162:163], 7, v[158:159]
	v_lshl_add_u64 v[162:163], v[144:145], 0, v[162:163]
	global_load_dwordx4 v[212:215], v[162:163], off
	global_load_dwordx4 v[216:219], v[162:163], off offset:16
	v_add_u32_e32 v166, 0xa0, v168
	v_ashrrev_i32_e32 v167, 31, v166
	v_lshlrev_b64 v[162:163], 7, v[166:167]
	v_lshl_add_u64 v[162:163], v[144:145], 0, v[162:163]
	global_load_dwordx4 v[220:223], v[162:163], off
	global_load_dwordx4 v[224:227], v[162:163], off offset:16
	v_add_u32_e32 v162, 0xb0, v168
	v_ashrrev_i32_e32 v163, 31, v162
	v_lshlrev_b64 v[228:229], 7, v[162:163]
	v_lshl_add_u64 v[232:233], v[144:145], 0, v[228:229]
	global_load_dwordx4 v[228:231], v[232:233], off
	s_nop 0
	global_load_dwordx4 v[232:235], v[232:233], off offset:16
	s_waitcnt vmcnt(0)
	v_mov_b32_e32 v236, v132
	v_mov_b32_e32 v237, v128
	v_mov_b32_e32 v128, v133
	v_mov_b32_e32 v132, v134
	v_mov_b32_e32 v133, v130
	v_mov_b32_e32 v130, v135
	v_pk_add_f32 v[130:131], v[132:133], v[130:131]
	v_mov_b32_e32 v132, v178
	v_mov_b32_e32 v133, v182
	v_mov_b32_e32 v182, v179
	v_mov_b32_e32 v134, v180
	v_mov_b32_e32 v135, v184
	v_mov_b32_e32 v184, v181
	v_pk_add_f32 v[128:129], v[236:237], v[128:129]
	v_pk_add_f32 v[132:133], v[132:133], v[182:183]
	v_pk_add_f32 v[134:135], v[134:135], v[184:185]
	v_pk_add_f32 v[128:129], v[128:129], v[130:131]
	v_pk_add_f32 v[130:131], v[132:133], v[134:135]
	v_mov_b32_e32 v133, v128
	v_mov_b32_e32 v132, v130
	v_and_b32_e32 v130, 64, v176
	v_add_u32_e32 v155, 64, v130
	v_xor_b32_e32 v130, 16, v176
	v_cmp_lt_i32_e32 vcc, v130, v155
	v_mov_b32_e32 v128, v131
	v_pk_add_f32 v[128:129], v[132:133], v[128:129]
	v_cndmask_b32_e32 v130, v176, v130, vcc
	v_lshlrev_b32_e32 v157, 2, v130
	ds_bpermute_b32 v131, v157, v129
	ds_bpermute_b32 v130, v157, v128
	v_mov_b32_e32 v178, v186
	v_mov_b32_e32 v179, v190
	v_mov_b32_e32 v190, v187
	v_mov_b32_e32 v186, v194
	s_waitcnt lgkmcnt(0)
	v_pk_add_f32 v[128:129], v[128:129], v[130:131]
	v_xor_b32_e32 v130, 32, v176
	v_cmp_lt_i32_e32 vcc, v130, v155
	v_mov_b32_e32 v187, v198
	v_mov_b32_e32 v198, v195
	v_cndmask_b32_e32 v130, v176, v130, vcc
	v_lshlrev_b32_e32 v155, 2, v130
	ds_bpermute_b32 v131, v155, v129
	ds_bpermute_b32 v130, v155, v128
	v_pk_add_f32 v[182:183], v[186:187], v[198:199]
	v_mov_b32_e32 v180, v188
	v_mov_b32_e32 v181, v192
	v_mov_b32_e32 v192, v189
	s_waitcnt lgkmcnt(0)
	v_pk_add_f32 v[128:129], v[128:129], v[130:131]
	v_mov_b64_e32 v[130:131], s[26:27]
	v_pk_fma_f32 v[128:129], v[128:129], s[24:25], v[130:131] op_sel_hi:[1,0,0]
	v_mov_b32_e32 v188, v196
	v_mul_f32_e32 v159, 0x4b800000, v129
	v_cmp_gt_f32_e32 vcc, s73, v129
	v_mov_b32_e32 v189, v200
	v_mov_b32_e32 v200, v197
	v_cndmask_b32_e32 v129, v129, v159, vcc
	v_rsq_f32_e32 v129, v129
	v_pk_add_f32 v[178:179], v[178:179], v[190:191]
	v_pk_add_f32 v[180:181], v[180:181], v[192:193]
	v_pk_add_f32 v[184:185], v[188:189], v[200:201]
	v_mul_f32_e32 v159, 0x45800000, v129
	v_cndmask_b32_e32 v198, v129, v159, vcc
	v_pk_mul_f32 v[126:127], v[126:127], v[198:199] op_sel_hi:[1,0]
	v_pk_mul_f32 v[124:125], v[124:125], v[198:199] op_sel_hi:[1,0]
	v_pk_mul_f32 v[122:123], v[122:123], v[198:199] op_sel_hi:[1,0]
	v_pk_mul_f32 v[120:121], v[120:121], v[198:199] op_sel_hi:[1,0]
	v_cvt_pk_bf16_f32 v124, v124, v125
	v_cvt_pk_bf16_f32 v125, v126, v127
	v_cvt_pk_bf16_f32 v127, v122, v123
	v_lshl_or_b32 v122, s5, 8, v172
	v_cvt_pk_bf16_f32 v126, v120, v121
	v_ashrrev_i32_e32 v123, 31, v122
	v_mov_b64_e32 v[120:121], s[2:3]
	v_mad_i64_i32 v[168:169], s[4:5], v168, s76, v[120:121]
	v_lshlrev_b64 v[122:123], 1, v[122:123]
	v_lshl_add_u64 v[168:169], v[168:169], 0, v[122:123]
	global_store_dwordx4 v[168:169], v[124:127], off
	v_mov_b32_e32 v194, v202
	v_mov_b32_e32 v195, v206
	v_pk_add_f32 v[124:125], v[178:179], v[180:181]
	v_pk_add_f32 v[126:127], v[182:183], v[184:185]
	v_mov_b32_e32 v179, v124
	v_mov_b32_e32 v178, v126
	v_mov_b32_e32 v124, v127
	v_pk_add_f32 v[124:125], v[178:179], v[124:125]
	ds_bpermute_b32 v127, v157, v125
	ds_bpermute_b32 v126, v157, v124
	v_mov_b32_e32 v206, v203
	v_mov_b32_e32 v196, v204
	v_mov_b32_e32 v197, v208
	v_mov_b32_e32 v208, v205
	v_mov_b32_e32 v202, v212
	v_mov_b32_e32 v203, v216
	v_mov_b32_e32 v216, v213
	v_mov_b32_e32 v204, v214
	v_mov_b32_e32 v205, v218
	v_mov_b32_e32 v218, v215
	v_pk_add_f32 v[186:187], v[194:195], v[206:207]
	v_pk_add_f32 v[188:189], v[196:197], v[208:209]
	v_pk_add_f32 v[190:191], v[202:203], v[216:217]
	v_pk_add_f32 v[192:193], v[204:205], v[218:219]
	v_pk_mul_f32 v[178:179], v[114:115], v[198:199] op_sel_hi:[1,0]
	s_waitcnt lgkmcnt(0)
; DI unsigned pack2(float lo, float hi) { f32x2 v = {lo, hi}; bf16v2 r = __builtin_convertvector(v, bf16v2); return __builtin_bit_cast(unsigned, r); }
;   DI void operator()(const f32x4 (&acc)[2][2][4][2], const Unit& u, int wr, int wc, int fr, int fq) const {
;     ...
;       for (int m = 0; m < 4; ++m) rsv[ai][m] = row_rstd(ssq, row0 + ai * HALF + m * 16, fq);
; #pragma unroll
;     for (int ai = 0; ai < 2; ++ai)
; #pragma unroll
;       for (int m = 0; m < 4; ++m) {
;         const int row = row0 + ai * HALF + m * 16;
;         const float rs = rsv[ai][m];
;         bf16_t* rowp = O + (size_t)row * ldc + col0;
; #pragma unroll
;         for (int bj = 0; bj < 2; ++bj) {
;           const f32x4 v0 = acc[ai][bj][m][0] * rs, v1 = acc[ai][bj][m][1] * rs;
;           u32x4 w; w.x = pack2(v0[0], v0[1]); w.y = pack2(v0[2], v0[3]); w.z = pack2(v1[0], v1[1]); w.w = pack2(v1[2], v1[3]);
;           *(u32x4*)(rowp + bj * HALF) = w;
;         }
	v_pk_add_f32 v[114:115], v[124:125], v[126:127]
	v_pk_add_f32 v[126:127], v[186:187], v[188:189]
	v_pk_add_f32 v[180:181], v[190:191], v[192:193]
	v_mov_b32_e32 v183, v126
	v_mov_b32_e32 v182, v180
	v_mov_b32_e32 v126, v181
	v_pk_add_f32 v[126:127], v[182:183], v[126:127]
	ds_bpermute_b32 v125, v155, v115
	ds_bpermute_b32 v124, v155, v114
	ds_bpermute_b32 v181, v157, v127
	ds_bpermute_b32 v180, v157, v126
	v_mul_f32_e32 v129, 0x4b800000, v128
	v_cmp_gt_f32_e32 vcc, s73, v128
	s_waitcnt lgkmcnt(2)
	v_pk_add_f32 v[114:115], v[114:115], v[124:125]
	v_mov_b32_e32 v194, v220
	s_waitcnt lgkmcnt(0)
	v_pk_add_f32 v[124:125], v[126:127], v[180:181]
	ds_bpermute_b32 v127, v155, v125
	ds_bpermute_b32 v126, v155, v124
	v_pk_fma_f32 v[114:115], v[114:115], s[24:25], v[130:131] op_sel_hi:[1,0,0]
	v_cndmask_b32_e32 v159, v128, v129, vcc
	v_mul_f32_e32 v128, 0x4b800000, v115
	v_cmp_gt_f32_e64 s[4:5], s73, v115
	v_cmp_gt_f32_e64 s[6:7], s73, v114
	v_mov_b32_e32 v195, v224
	v_cndmask_b32_e64 v161, v115, v128, s[4:5]
	v_mul_f32_e32 v115, 0x4b800000, v114
	v_mov_b32_e32 v224, v221
	v_mov_b32_e32 v196, v222
	v_mov_b32_e32 v197, v226
	v_mov_b32_e32 v226, v223
	v_cndmask_b32_e64 v163, v114, v115, s[6:7]
	s_waitcnt lgkmcnt(0)
	v_pk_add_f32 v[114:115], v[124:125], v[126:127]
	v_pk_add_f32 v[132:133], v[194:195], v[224:225]
	v_pk_add_f32 v[134:135], v[196:197], v[226:227]
	v_mov_b32_e32 v194, v228
	v_mov_b32_e32 v195, v232
	v_mov_b32_e32 v232, v229
	v_mov_b32_e32 v196, v230
	v_mov_b32_e32 v197, v234
	v_mov_b32_e32 v234, v231
	v_pk_fma_f32 v[114:115], v[114:115], s[24:25], v[130:131] op_sel_hi:[1,0,0]
	v_pk_add_f32 v[194:195], v[194:195], v[232:233]
	v_pk_add_f32 v[196:197], v[196:197], v[234:235]
	v_mul_f32_e32 v124, 0x4b800000, v115
	v_cmp_gt_f32_e64 s[8:9], s73, v115
	v_pk_add_f32 v[126:127], v[194:195], v[196:197]
	v_cmp_gt_f32_e64 s[10:11], s73, v114
	v_cndmask_b32_e64 v165, v115, v124, s[8:9]
	v_pk_add_f32 v[124:125], v[132:133], v[134:135]
	v_mov_b32_e32 v128, v126
	v_mov_b32_e32 v129, v124
	v_mov_b32_e32 v124, v127
	v_pk_add_f32 v[124:125], v[128:129], v[124:125]
	ds_bpermute_b32 v127, v157, v125
	ds_bpermute_b32 v126, v157, v124
	v_rsq_f32_e32 v128, v159
	v_mul_f32_e32 v115, 0x4b800000, v114
	v_cndmask_b32_e64 v129, v114, v115, s[10:11]
	v_pk_mul_f32 v[116:117], v[116:117], v[198:199] op_sel_hi:[1,0]
	s_waitcnt lgkmcnt(0)
	v_pk_add_f32 v[114:115], v[124:125], v[126:127]
	ds_bpermute_b32 v125, v155, v115
	ds_bpermute_b32 v124, v155, v114
	v_mul_f32_e32 v126, 0x45800000, v128
	v_rsq_f32_e32 v127, v161
	v_cndmask_b32_e32 v126, v128, v126, vcc
	v_rsq_f32_e32 v128, v163
	s_waitcnt lgkmcnt(0)
	v_pk_add_f32 v[114:115], v[114:115], v[124:125]
	v_mul_f32_e32 v124, 0x45800000, v127
	v_cndmask_b32_e64 v124, v127, v124, s[4:5]
	v_mul_f32_e32 v127, 0x45800000, v128
	v_pk_fma_f32 v[114:115], v[114:115], s[24:25], v[130:131] op_sel_hi:[1,0,0]
	v_rsq_f32_e32 v125, v165
	v_cndmask_b32_e64 v128, v128, v127, s[6:7]
	v_rsq_f32_e32 v127, v129
	v_mul_f32_e32 v129, 0x4b800000, v115
	v_cmp_gt_f32_e32 vcc, s73, v115
	v_cmp_gt_f32_e64 s[4:5], s73, v114
	v_pk_mul_f32 v[118:119], v[118:119], v[198:199] op_sel_hi:[1,0]
	v_cndmask_b32_e32 v129, v115, v129, vcc
	v_mul_f32_e32 v115, 0x4b800000, v114
	v_cndmask_b32_e64 v131, v114, v115, s[4:5]
	v_cvt_pk_bf16_f32 v114, v116, v117
	v_rsq_f32_e32 v117, v129
	v_cvt_pk_bf16_f32 v115, v118, v119
	v_rsq_f32_e32 v119, v131
	v_mul_f32_e32 v116, 0x45800000, v125
	v_pk_mul_f32 v[112:113], v[112:113], v[198:199] op_sel_hi:[1,0]
	v_cndmask_b32_e64 v118, v125, v116, s[8:9]
	v_mul_f32_e32 v116, 0x45800000, v127
	v_cndmask_b32_e64 v130, v127, v116, s[10:11]
	v_cvt_pk_bf16_f32 v116, v112, v113
	v_mul_f32_e32 v112, 0x45800000, v117
	v_cndmask_b32_e32 v132, v117, v112, vcc
	v_mul_f32_e32 v112, 0x45800000, v119
	v_cvt_pk_bf16_f32 v117, v178, v179
	v_cndmask_b32_e64 v112, v119, v112, s[4:5]
	global_store_dwordx4 v[168:169], v[114:117], off offset:256
	v_pk_mul_f32 v[110:111], v[110:111], v[126:127] op_sel_hi:[1,0]
	v_pk_mul_f32 v[108:109], v[108:109], v[126:127] op_sel_hi:[1,0]
	v_mad_i64_i32 v[114:115], s[4:5], v154, s76, v[120:121]
	v_pk_mul_f32 v[116:117], v[106:107], v[126:127] op_sel_hi:[1,0]
	v_pk_mul_f32 v[106:107], v[104:105], v[126:127] op_sel_hi:[1,0]
	v_lshl_add_u64 v[114:115], v[114:115], 0, v[122:123]
	v_cvt_pk_bf16_f32 v104, v108, v109
	v_cvt_pk_bf16_f32 v105, v110, v111
	v_cvt_pk_bf16_f32 v106, v106, v107
	v_cvt_pk_bf16_f32 v107, v116, v117
	global_store_dwordx4 v[114:115], v[104:107], off
	v_pk_mul_f32 v[98:99], v[98:99], v[126:127] op_sel_hi:[1,0]
	v_pk_mul_f32 v[96:97], v[96:97], v[126:127] op_sel_hi:[1,0]
	v_pk_mul_f32 v[104:105], v[90:91], v[126:127] op_sel_hi:[1,0]
	v_pk_mul_f32 v[90:91], v[88:89], v[126:127] op_sel_hi:[1,0]
	v_cvt_pk_bf16_f32 v88, v96, v97
	v_cvt_pk_bf16_f32 v89, v98, v99
	v_cvt_pk_bf16_f32 v90, v90, v91
	v_cvt_pk_bf16_f32 v91, v104, v105
	global_store_dwordx4 v[114:115], v[88:91], off offset:256
	v_pk_mul_f32 v[94:95], v[94:95], v[124:125] op_sel_hi:[1,0]
	v_pk_mul_f32 v[92:93], v[92:93], v[124:125] op_sel_hi:[1,0]
	v_mad_i64_i32 v[88:89], s[4:5], v160, s76, v[120:121]
	v_lshl_add_u64 v[96:97], v[88:89], 0, v[122:123]
	v_pk_mul_f32 v[90:91], v[102:103], v[124:125] op_sel_hi:[1,0]
	v_pk_mul_f32 v[88:89], v[100:101], v[124:125] op_sel_hi:[1,0]
	v_pk_mul_f32 v[82:83], v[82:83], v[124:125] op_sel_hi:[1,0]
	v_cvt_pk_bf16_f32 v88, v88, v89
	v_cvt_pk_bf16_f32 v89, v90, v91
	v_cvt_pk_bf16_f32 v90, v92, v93
; DI unsigned pack2(float lo, float hi) { f32x2 v = {lo, hi}; bf16v2 r = __builtin_convertvector(v, bf16v2); return __builtin_bit_cast(unsigned, r); }
; #define PG8_WAIT_V(n) asm volatile("s_waitcnt vmcnt(" #n ")" ::: "memory")
; #define PG8_BAR __builtin_amdgcn_s_barrier()
;   DI void operator()(const f32x4 (&acc)[2][2][4][2], const Unit& u, int wr, int wc, int fr, int fq) const {
;     ...
;     for (int ai = 0; ai < 2; ++ai)
; #pragma unroll
;       for (int m = 0; m < 4; ++m) {
;         const int row = row0 + ai * HALF + m * 16;
;         const float rs = rsv[ai][m];
;         bf16_t* rowp = O + (size_t)row * ldc + col0;
; #pragma unroll
;         for (int bj = 0; bj < 2; ++bj) {
;           const f32x4 v0 = acc[ai][bj][m][0] * rs, v1 = acc[ai][bj][m][1] * rs;
;           u32x4 w; w.x = pack2(v0[0], v0[1]); w.y = pack2(v0[2], v0[3]); w.z = pack2(v1[0], v1[1]); w.w = pack2(v1[2], v1[3]);
;           *(u32x4*)(rowp + bj * HALF) = w;
;         }
;       }
;   }
; template <class Epi, class Sched = StaticOrder>
; DI void gemm_phase(LAS unsigned char* lds, const Gemm g, const Sched& S, const Epi& E) {
;     ...
;     E(acc, cur, wr, wc, fr, fq);
;     if (!has_next) break;
; #pragma unroll
;     for (int a = 0; a < 2; ++a)
; #pragma unroll
;       for (int b = 0; b < 2; ++b)
; #pragma unroll
;         for (int m = 0; m < 4; ++m)
; #pragma unroll
;           for (int n = 0; n < 2; ++n) acc[a][b][m][n] = (f32x4){0.f, 0.f, 0.f, 0.f};
;     cur = nxt; cA = nA; cB = nB; ++ui;
;   }
;   PG8_WAIT_V(0);
;   if (wr == 0) PG8_BAR;
;   PG8_BAR;
	v_cvt_pk_bf16_f32 v91, v94, v95
	global_store_dwordx4 v[96:97], v[88:91], off
	v_pk_mul_f32 v[80:81], v[80:81], v[124:125] op_sel_hi:[1,0]
	v_pk_mul_f32 v[78:79], v[78:79], v[128:129] op_sel_hi:[1,0]
	v_pk_mul_f32 v[88:89], v[74:75], v[124:125] op_sel_hi:[1,0]
	v_pk_mul_f32 v[74:75], v[72:73], v[124:125] op_sel_hi:[1,0]
	v_cvt_pk_bf16_f32 v72, v80, v81
	v_cvt_pk_bf16_f32 v73, v82, v83
	v_cvt_pk_bf16_f32 v74, v74, v75
	v_cvt_pk_bf16_f32 v75, v88, v89
	global_store_dwordx4 v[96:97], v[72:75], off offset:256
	v_pk_mul_f32 v[76:77], v[76:77], v[128:129] op_sel_hi:[1,0]
	v_pk_mul_f32 v[70:71], v[70:71], v[128:129] op_sel_hi:[1,0]
	v_mad_i64_i32 v[72:73], s[4:5], v156, s76, v[120:121]
	v_lshl_add_u64 v[80:81], v[72:73], 0, v[122:123]
	v_pk_mul_f32 v[74:75], v[86:87], v[128:129] op_sel_hi:[1,0]
	v_pk_mul_f32 v[72:73], v[84:85], v[128:129] op_sel_hi:[1,0]
	v_pk_mul_f32 v[68:69], v[68:69], v[128:129] op_sel_hi:[1,0]
	v_cvt_pk_bf16_f32 v72, v72, v73
	v_cvt_pk_bf16_f32 v73, v74, v75
	v_cvt_pk_bf16_f32 v74, v76, v77
	v_cvt_pk_bf16_f32 v75, v78, v79
	global_store_dwordx4 v[80:81], v[72:75], off
	v_pk_mul_f32 v[62:63], v[62:63], v[118:119] op_sel_hi:[1,0]
	v_pk_mul_f32 v[60:61], v[60:61], v[118:119] op_sel_hi:[1,0]
	v_pk_mul_f32 v[72:73], v[66:67], v[128:129] op_sel_hi:[1,0]
	v_pk_mul_f32 v[66:67], v[64:65], v[128:129] op_sel_hi:[1,0]
	v_cvt_pk_bf16_f32 v64, v68, v69
	v_cvt_pk_bf16_f32 v65, v70, v71
	v_cvt_pk_bf16_f32 v66, v66, v67
	v_cvt_pk_bf16_f32 v67, v72, v73
	global_store_dwordx4 v[80:81], v[64:67], off offset:256
	v_pk_mul_f32 v[50:51], v[50:51], v[118:119] op_sel_hi:[1,0]
	v_pk_mul_f32 v[48:49], v[48:49], v[118:119] op_sel_hi:[1,0]
	v_mad_i64_i32 v[64:65], s[4:5], v164, s76, v[120:121]
	v_pk_mul_f32 v[66:67], v[58:59], v[118:119] op_sel_hi:[1,0]
	v_pk_mul_f32 v[58:59], v[56:57], v[118:119] op_sel_hi:[1,0]
	v_lshl_add_u64 v[64:65], v[64:65], 0, v[122:123]
	v_cvt_pk_bf16_f32 v56, v60, v61
	v_cvt_pk_bf16_f32 v57, v62, v63
	v_cvt_pk_bf16_f32 v58, v58, v59
	v_cvt_pk_bf16_f32 v59, v66, v67
	global_store_dwordx4 v[64:65], v[56:59], off
	v_pk_mul_f32 v[46:47], v[46:47], v[130:131] op_sel_hi:[1,0]
	v_pk_mul_f32 v[44:45], v[44:45], v[130:131] op_sel_hi:[1,0]
	v_pk_mul_f32 v[56:57], v[42:43], v[118:119] op_sel_hi:[1,0]
	v_pk_mul_f32 v[42:43], v[40:41], v[118:119] op_sel_hi:[1,0]
	v_cvt_pk_bf16_f32 v40, v48, v49
	v_cvt_pk_bf16_f32 v41, v50, v51
	v_cvt_pk_bf16_f32 v42, v42, v43
	v_cvt_pk_bf16_f32 v43, v56, v57
	global_store_dwordx4 v[64:65], v[40:43], off offset:256
	v_pk_mul_f32 v[34:35], v[34:35], v[130:131] op_sel_hi:[1,0]
	v_pk_mul_f32 v[32:33], v[32:33], v[130:131] op_sel_hi:[1,0]
	v_mad_i64_i32 v[40:41], s[4:5], v158, s76, v[120:121]
	v_lshl_add_u64 v[48:49], v[40:41], 0, v[122:123]
	v_pk_mul_f32 v[42:43], v[54:55], v[130:131] op_sel_hi:[1,0]
	v_pk_mul_f32 v[40:41], v[52:53], v[130:131] op_sel_hi:[1,0]
	v_pk_mul_f32 v[30:31], v[30:31], v[132:133] op_sel_hi:[1,0]
	v_cvt_pk_bf16_f32 v40, v40, v41
	v_cvt_pk_bf16_f32 v41, v42, v43
	v_cvt_pk_bf16_f32 v42, v44, v45
	v_cvt_pk_bf16_f32 v43, v46, v47
	global_store_dwordx4 v[48:49], v[40:43], off
	v_pk_mul_f32 v[28:29], v[28:29], v[132:133] op_sel_hi:[1,0]
	v_pk_mul_f32 v[18:19], v[18:19], v[132:133] op_sel_hi:[1,0]
	v_pk_mul_f32 v[40:41], v[26:27], v[130:131] op_sel_hi:[1,0]
	v_pk_mul_f32 v[26:27], v[24:25], v[130:131] op_sel_hi:[1,0]
	v_cvt_pk_bf16_f32 v24, v32, v33
	v_cvt_pk_bf16_f32 v25, v34, v35
	v_cvt_pk_bf16_f32 v26, v26, v27
	v_cvt_pk_bf16_f32 v27, v40, v41
	global_store_dwordx4 v[48:49], v[24:27], off offset:256
	v_pk_mul_f32 v[16:17], v[16:17], v[132:133] op_sel_hi:[1,0]
	v_pk_mul_f32 v[14:15], v[14:15], v[112:113] op_sel_hi:[1,0]
	v_mad_i64_i32 v[24:25], s[4:5], v166, s76, v[120:121]
	v_lshl_add_u64 v[32:33], v[24:25], 0, v[122:123]
	v_pk_mul_f32 v[26:27], v[38:39], v[132:133] op_sel_hi:[1,0]
	v_pk_mul_f32 v[24:25], v[36:37], v[132:133] op_sel_hi:[1,0]
	v_pk_mul_f32 v[12:13], v[12:13], v[112:113] op_sel_hi:[1,0]
	v_cvt_pk_bf16_f32 v24, v24, v25
	v_cvt_pk_bf16_f32 v25, v26, v27
	v_cvt_pk_bf16_f32 v26, v28, v29
	v_cvt_pk_bf16_f32 v27, v30, v31
	global_store_dwordx4 v[32:33], v[24:27], off
	v_pk_mul_f32 v[6:7], v[6:7], v[112:113] op_sel_hi:[1,0]
	v_pk_mul_f32 v[4:5], v[4:5], v[112:113] op_sel_hi:[1,0]
	v_pk_mul_f32 v[24:25], v[10:11], v[132:133] op_sel_hi:[1,0]
	v_pk_mul_f32 v[10:11], v[8:9], v[132:133] op_sel_hi:[1,0]
	v_cvt_pk_bf16_f32 v8, v16, v17
	v_cvt_pk_bf16_f32 v9, v18, v19
	v_cvt_pk_bf16_f32 v10, v10, v11
	v_cvt_pk_bf16_f32 v11, v24, v25
	global_store_dwordx4 v[32:33], v[8:11], off offset:256
	s_and_b64 vcc, exec, s[0:1]
	s_mov_b64 s[8:9], s[36:37]
	v_mad_i64_i32 v[8:9], s[4:5], v162, s76, v[120:121]
	v_lshl_add_u64 v[16:17], v[8:9], 0, v[122:123]
	v_pk_mul_f32 v[10:11], v[22:23], v[112:113] op_sel_hi:[1,0]
	v_pk_mul_f32 v[8:9], v[20:21], v[112:113] op_sel_hi:[1,0]
	s_mov_b32 s5, s28
	v_cvt_pk_bf16_f32 v8, v8, v9
	v_cvt_pk_bf16_f32 v9, v10, v11
	v_cvt_pk_bf16_f32 v10, v12, v13
	v_cvt_pk_bf16_f32 v11, v14, v15
	global_store_dwordx4 v[16:17], v[8:11], off
	s_mov_b32 s4, s30
	s_mov_b64 s[6:7], s[34:35]
	v_pk_mul_f32 v[8:9], v[2:3], v[112:113] op_sel_hi:[1,0]
	v_pk_mul_f32 v[2:3], v[0:1], v[112:113] op_sel_hi:[1,0]
	v_cvt_pk_bf16_f32 v0, v4, v5
	v_cvt_pk_bf16_f32 v1, v6, v7
	v_cvt_pk_bf16_f32 v2, v2, v3
	v_cvt_pk_bf16_f32 v3, v8, v9
	global_store_dwordx4 v[16:17], v[0:3], off offset:256
	s_cbranch_vccz .LBB0_343
	s_waitcnt vmcnt(0)
	s_cmpk_gt_u32 s27, 0xff
	s_cbranch_scc1 .LBB0_350
	s_barrier

; #define PG8_STAGE(bufoff, gbase, voff) do { _Pragma("unroll") for (int _i = 0; _i < 2; ++_i) \
;     __builtin_amdgcn_global_load_lds((const unsigned*)((const char*)(gbase) + (voff)[_i]), (LAS unsigned*)(lds + (bufoff) + ldsw + _i * 8192), 16, 0, 0); } while (0)
; #define PG8_LDA(dst, b, h) do { _Pragma("unroll") for (int m = 0; m < 4; ++m) _Pragma("unroll") for (int k = 0; k < 2; ++k) dst[m][k] = *(const LAS bf16x8*)(lds + PG8_SA(b, h) + aoff + m * 2048 + k * 1024); } while (0)
; #define PG8_LDB(dst, b, h) do { _Pragma("unroll") for (int n = 0; n < 2; ++n) _Pragma("unroll") for (int k = 0; k < 2; ++k) dst[n][k] = *(const LAS bf16x8*)(lds + PG8_SB(b, h) + boff + n * 2048 + k * 1024); } while (0)
; #define PG8_MMA(ai, bj, At, Bt) do { __builtin_amdgcn_s_setprio(1); _Pragma("unroll") for (int m = 0; m < 4; ++m) _Pragma("unroll") for (int n = 0; n < 2; ++n) _Pragma("unroll") for (int k = 0; k < 2; ++k) \
;     acc[ai][bj][m][n] = __builtin_amdgcn_mfma_f32_16x16x32_bf16(Bt[n][k], At[m][k], acc[ai][bj][m][n], 0, 0, 0); __builtin_amdgcn_s_setprio(0); } while (0)
; #define PG8_WAIT_V(n) asm volatile("s_waitcnt vmcnt(" #n ")" ::: "memory")
; #define PG8_WAIT_L(n) asm volatile("s_waitcnt lgkmcnt(" #n ")" ::: "memory")
; #define PG8_BAR __builtin_amdgcn_s_barrier()
; #define PG8_SCHED __builtin_amdgcn_sched_barrier(0)
; template <class Epi, class Sched = StaticOrder>
; DI void gemm_phase(LAS unsigned char* lds, const Gemm g, const Sched& S, const Epi& E) {
;     ...
;       PG8_LDB(B0, 0, 0); PG8_SCHED; PG8_LDA(At, 0, 0); PG8_STAGE(PG8_SA(1, 1), a1 + hstep, voffA);
;       PG8_WAIT_L(8); PG8_BAR; PG8_WAIT_L(0); PG8_MMA(0, 0, At, B0); PG8_BAR; PG8_SCHED;
;       PG8_LDB(B1, 0, 1); PG8_STAGE(PG8_SB(0, 0), b2, voffB);
;       PG8_BAR; PG8_WAIT_L(0); PG8_MMA(0, 1, At, B1); PG8_BAR;
;       PG8_LDA(At, 0, 1); PG8_STAGE(PG8_SA(0, 0), a2, voffA);
;       PG8_BAR; PG8_WAIT_L(0); PG8_MMA(1, 0, At, B0); PG8_BAR; PG8_SCHED;
;       PG8_STAGE(PG8_SB(0, 1), b2 + hstep, voffB);
;       PG8_WAIT_V(6); PG8_BAR; PG8_MMA(1, 1, At, B1); PG8_BAR;
.LBB0_728:
	ds_read_b128 v[128:131], v207
	ds_read_b128 v[132:135], v207 offset:1024
	ds_read_b128 v[136:139], v207 offset:2048
	ds_read_b128 v[140:143], v207 offset:3072
	s_add_u32 s24, s22, 0xfff80080
	s_addc_u32 s25, s23, -1
	s_cmp_eq_u32 s53, 28
	s_cselect_b32 s27, s17, s25
	s_cselect_b32 s26, s43, s24
	s_cselect_b32 s25, s15, s52
	s_cselect_b32 s24, s44, s45
	s_add_i32 m0, s37, 0xc000
	ds_read_b128 v[144:147], v208
	ds_read_b128 v[148:151], v208 offset:1024
	ds_read_b128 v[152:155], v208 offset:2048
	ds_read_b128 v[156:159], v208 offset:3072
	ds_read_b128 v[160:163], v208 offset:4096
	ds_read_b128 v[164:167], v208 offset:5120
	ds_read_b128 v[168:171], v208 offset:6144
	ds_read_b128 v[172:175], v208 offset:7168
	global_load_lds_dwordx4 v184, s[22:23]
	s_add_i32 m0, s37, 0xe000
	s_nop 0
	global_load_lds_dwordx4 v186, s[22:23]
	ds_read_b128 v[192:195], v209
	ds_read_b128 v[196:199], v209 offset:1024
	ds_read_b128 v[200:203], v209 offset:2048
	ds_read_b128 v[212:215], v209 offset:3072
	s_waitcnt vmcnt(8)
	s_waitcnt lgkmcnt(4)
	s_setprio 1
	s_barrier
	v_mfma_f32_16x16x32_bf16 v[124:127], v[128:131], v[144:147], v[124:127]
	v_mfma_f32_16x16x32_bf16 v[120:123], v[136:139], v[144:147], v[120:123]
	v_mfma_f32_16x16x32_bf16 v[108:111], v[128:131], v[152:155], v[108:111]
	v_mfma_f32_16x16x32_bf16 v[104:107], v[136:139], v[152:155], v[104:107]
	v_mfma_f32_16x16x32_bf16 v[92:95], v[128:131], v[160:163], v[92:95]
	v_mfma_f32_16x16x32_bf16 v[88:91], v[136:139], v[160:163], v[88:91]
	v_mfma_f32_16x16x32_bf16 v[76:79], v[128:131], v[168:171], v[76:79]
	v_mfma_f32_16x16x32_bf16 v[72:75], v[136:139], v[168:171], v[72:75]
	v_mfma_f32_16x16x32_bf16 v[124:127], v[132:135], v[148:151], v[124:127]
	v_mfma_f32_16x16x32_bf16 v[120:123], v[140:143], v[148:151], v[120:123]
	v_mfma_f32_16x16x32_bf16 v[108:111], v[132:135], v[156:159], v[108:111]
	v_mfma_f32_16x16x32_bf16 v[104:107], v[140:143], v[156:159], v[104:107]
	v_mfma_f32_16x16x32_bf16 v[92:95], v[132:135], v[164:167], v[92:95]
	v_mfma_f32_16x16x32_bf16 v[88:91], v[140:143], v[164:167], v[88:91]
	v_mfma_f32_16x16x32_bf16 v[76:79], v[132:135], v[172:175], v[76:79]
	v_mfma_f32_16x16x32_bf16 v[72:75], v[140:143], v[172:175], v[72:75]
	s_waitcnt lgkmcnt(0)
	v_mfma_f32_16x16x32_bf16 v[116:119], v[192:195], v[144:147], v[116:119]
	v_mfma_f32_16x16x32_bf16 v[112:115], v[200:203], v[144:147], v[112:115]
	v_mfma_f32_16x16x32_bf16 v[100:103], v[192:195], v[152:155], v[100:103]
	v_mfma_f32_16x16x32_bf16 v[96:99], v[200:203], v[152:155], v[96:99]
	v_mfma_f32_16x16x32_bf16 v[84:87], v[192:195], v[160:163], v[84:87]
	v_mfma_f32_16x16x32_bf16 v[80:83], v[200:203], v[160:163], v[80:83]
	v_mfma_f32_16x16x32_bf16 v[68:71], v[192:195], v[168:171], v[68:71]
	v_mfma_f32_16x16x32_bf16 v[64:67], v[200:203], v[168:171], v[64:67]
	v_mfma_f32_16x16x32_bf16 v[116:119], v[196:199], v[148:151], v[116:119]
	v_mfma_f32_16x16x32_bf16 v[112:115], v[212:215], v[148:151], v[112:115]
	v_mfma_f32_16x16x32_bf16 v[100:103], v[196:199], v[156:159], v[100:103]
	v_mfma_f32_16x16x32_bf16 v[96:99], v[212:215], v[156:159], v[96:99]
	v_mfma_f32_16x16x32_bf16 v[84:87], v[196:199], v[164:167], v[84:87]
	v_mfma_f32_16x16x32_bf16 v[80:83], v[212:215], v[164:167], v[80:83]
	v_mfma_f32_16x16x32_bf16 v[68:71], v[196:199], v[172:175], v[68:71]
	v_mfma_f32_16x16x32_bf16 v[64:67], v[212:215], v[172:175], v[64:67]
	s_barrier
	s_setprio 0
	s_add_i32 s54, s50, s35
	s_add_u32 s98, s24, 0x80
	s_addc_u32 s99, s25, 0
	s_add_u32 s100, s26, 0x80
	s_addc_u32 s101, s27, 0
	s_mov_b32 m0, s54
	s_nop 0
	global_load_lds_dwordx4 v180, s[24:25]
	s_add_i32 m0, s54, 0x2000
	s_nop 0
	global_load_lds_dwordx4 v176, s[24:25]
	s_mov_b32 m0, s37
	s_nop 0
	global_load_lds_dwordx4 v182, s[26:27]
	s_mov_b32 m0, s38
	s_nop 0
	global_load_lds_dwordx4 v178, s[26:27]
	ds_read_b128 v[144:147], v208 offset:16384
	ds_read_b128 v[148:151], v208 offset:17408
	ds_read_b128 v[152:155], v208 offset:18432
	ds_read_b128 v[156:159], v208 offset:19456
	ds_read_b128 v[160:163], v208 offset:20480
	ds_read_b128 v[164:167], v208 offset:21504
	ds_read_b128 v[168:171], v208 offset:22528
	ds_read_b128 v[172:175], v208 offset:23552
	s_add_u32 s54, s24, 0x80000
	s_addc_u32 s55, s25, 0
	s_add_i32 s57, s51, s35
	s_waitcnt vmcnt(6)
	s_waitcnt lgkmcnt(0)
	s_setprio 1
	s_barrier
	v_mfma_f32_16x16x32_bf16 v[60:63], v[128:131], v[144:147], v[60:63]
	s_mov_b32 m0, s57
	v_mfma_f32_16x16x32_bf16 v[56:59], v[136:139], v[144:147], v[56:59]
	global_load_lds_dwordx4 v180, s[54:55]
	v_mfma_f32_16x16x32_bf16 v[44:47], v[128:131], v[152:155], v[44:47]
	s_bitset1_b32 m0, 13
	v_mfma_f32_16x16x32_bf16 v[40:43], v[136:139], v[152:155], v[40:43]
	global_load_lds_dwordx4 v176, s[54:55]
	v_mfma_f32_16x16x32_bf16 v[28:31], v[128:131], v[160:163], v[28:31]
	v_mfma_f32_16x16x32_bf16 v[24:27], v[136:139], v[160:163], v[24:27]
	v_mfma_f32_16x16x32_bf16 v[12:15], v[128:131], v[168:171], v[12:15]
	v_mfma_f32_16x16x32_bf16 v[8:11], v[136:139], v[168:171], v[8:11]
	v_mfma_f32_16x16x32_bf16 v[60:63], v[132:135], v[148:151], v[60:63]
	v_mfma_f32_16x16x32_bf16 v[56:59], v[140:143], v[148:151], v[56:59]
	v_mfma_f32_16x16x32_bf16 v[44:47], v[132:135], v[156:159], v[44:47]
	v_mfma_f32_16x16x32_bf16 v[40:43], v[140:143], v[156:159], v[40:43]
	v_mfma_f32_16x16x32_bf16 v[28:31], v[132:135], v[164:167], v[28:31]
	v_mfma_f32_16x16x32_bf16 v[24:27], v[140:143], v[164:167], v[24:27]
	v_mfma_f32_16x16x32_bf16 v[12:15], v[132:135], v[172:175], v[12:15]
	v_mfma_f32_16x16x32_bf16 v[8:11], v[140:143], v[172:175], v[8:11]
	v_mfma_f32_16x16x32_bf16 v[52:55], v[192:195], v[144:147], v[52:55]
	v_mfma_f32_16x16x32_bf16 v[48:51], v[200:203], v[144:147], v[48:51]
	v_mfma_f32_16x16x32_bf16 v[36:39], v[192:195], v[152:155], v[36:39]
	v_mfma_f32_16x16x32_bf16 v[32:35], v[200:203], v[152:155], v[32:35]
	v_mfma_f32_16x16x32_bf16 v[20:23], v[192:195], v[160:163], v[20:23]
	v_mfma_f32_16x16x32_bf16 v[16:19], v[200:203], v[160:163], v[16:19]
	v_mfma_f32_16x16x32_bf16 v[4:7], v[192:195], v[168:171], v[4:7]
	v_mfma_f32_16x16x32_bf16 v[0:3], v[200:203], v[168:171], v[0:3]
	v_mfma_f32_16x16x32_bf16 v[52:55], v[196:199], v[148:151], v[52:55]
	v_mfma_f32_16x16x32_bf16 v[48:51], v[212:215], v[148:151], v[48:51]
	v_mfma_f32_16x16x32_bf16 v[36:39], v[196:199], v[156:159], v[36:39]
	v_mfma_f32_16x16x32_bf16 v[32:35], v[212:215], v[156:159], v[32:35]
	v_mfma_f32_16x16x32_bf16 v[20:23], v[196:199], v[164:167], v[20:23]
	v_mfma_f32_16x16x32_bf16 v[16:19], v[212:215], v[164:167], v[16:19]
	v_mfma_f32_16x16x32_bf16 v[4:7], v[196:199], v[172:175], v[4:7]
	v_mfma_f32_16x16x32_bf16 v[0:3], v[212:215], v[172:175], v[0:3]
	s_barrier
; #define PG8_STAGE(bufoff, gbase, voff) do { _Pragma("unroll") for (int _i = 0; _i < 2; ++_i) \
;     __builtin_amdgcn_global_load_lds((const unsigned*)((const char*)(gbase) + (voff)[_i]), (LAS unsigned*)(lds + (bufoff) + ldsw + _i * 8192), 16, 0, 0); } while (0)
; #define PG8_LDA(dst, b, h) do { _Pragma("unroll") for (int m = 0; m < 4; ++m) _Pragma("unroll") for (int k = 0; k < 2; ++k) dst[m][k] = *(const LAS bf16x8*)(lds + PG8_SA(b, h) + aoff + m * 2048 + k * 1024); } while (0)
; #define PG8_LDB(dst, b, h) do { _Pragma("unroll") for (int n = 0; n < 2; ++n) _Pragma("unroll") for (int k = 0; k < 2; ++k) dst[n][k] = *(const LAS bf16x8*)(lds + PG8_SB(b, h) + boff + n * 2048 + k * 1024); } while (0)
; #define PG8_MMA(ai, bj, At, Bt) do { __builtin_amdgcn_s_setprio(1); _Pragma("unroll") for (int m = 0; m < 4; ++m) _Pragma("unroll") for (int n = 0; n < 2; ++n) _Pragma("unroll") for (int k = 0; k < 2; ++k) \
;     acc[ai][bj][m][n] = __builtin_amdgcn_mfma_f32_16x16x32_bf16(Bt[n][k], At[m][k], acc[ai][bj][m][n], 0, 0, 0); __builtin_amdgcn_s_setprio(0); } while (0)
; #define PG8_WAIT_V(n) asm volatile("s_waitcnt vmcnt(" #n ")" ::: "memory")
; #define PG8_WAIT_L(n) asm volatile("s_waitcnt lgkmcnt(" #n ")" ::: "memory")
; #define PG8_BAR __builtin_amdgcn_s_barrier()
; #define PG8_SCHED __builtin_amdgcn_sched_barrier(0)
; template <class Epi, class Sched = StaticOrder>
; DI void gemm_phase(LAS unsigned char* lds, const Gemm g, const Sched& S, const Epi& E) {
;     ...
;       PG8_LDB(B0, 1, 0); PG8_SCHED; PG8_LDA(At, 1, 0); PG8_STAGE(PG8_SA(0, 1), a2 + hstep, voffA);
;       PG8_WAIT_L(8); PG8_BAR; PG8_WAIT_L(0); PG8_MMA(0, 0, At, B0); PG8_BAR; PG8_SCHED;
;       PG8_LDB(B1, 1, 1); PG8_STAGE(PG8_SB(1, 0), b3, voffB);
;       PG8_BAR; PG8_WAIT_L(0); PG8_MMA(0, 1, At, B1); PG8_BAR;
;       PG8_LDA(At, 1, 1); PG8_STAGE(PG8_SA(1, 0), a3, voffA);
;       PG8_BAR; PG8_WAIT_L(0); PG8_MMA(1, 0, At, B0); PG8_BAR; PG8_SCHED;
;       PG8_STAGE(PG8_SB(1, 1), b3 + hstep, voffB);
;       PG8_WAIT_V(6); PG8_BAR; PG8_MMA(1, 1, At, B1); PG8_BAR;
	s_setprio 0
	s_add_i32 s54, 0, 0x18000
	v_add_u32_e32 v140, s54, v205
	ds_read_b128 v[128:131], v140
	ds_read_b128 v[132:135], v140 offset:1024
	ds_read_b128 v[136:139], v140 offset:2048
	ds_read_b128 v[140:143], v140 offset:3072
	s_add_u32 s26, s26, 0x80000
	s_addc_u32 s27, s27, 0
	s_mov_b32 m0, s39
	ds_read_b128 v[144:147], v208 offset:32768
	ds_read_b128 v[148:151], v208 offset:33792
	ds_read_b128 v[152:155], v208 offset:34816
	ds_read_b128 v[156:159], v208 offset:35840
	ds_read_b128 v[160:163], v208 offset:36864
	ds_read_b128 v[164:167], v208 offset:37888
	ds_read_b128 v[168:171], v208 offset:38912
	ds_read_b128 v[172:175], v208 offset:39936
	global_load_lds_dwordx4 v182, s[26:27]
	s_mov_b32 m0, s40
	s_nop 0
	global_load_lds_dwordx4 v178, s[26:27]
	s_add_i32 s26, 0, 0x1c000
	v_add_u32_e32 v212, s26, v205
	ds_read_b128 v[192:195], v212
	ds_read_b128 v[196:199], v212 offset:1024
	ds_read_b128 v[200:203], v212 offset:2048
	ds_read_b128 v[212:215], v212 offset:3072
	s_waitcnt vmcnt(8)
	s_waitcnt lgkmcnt(4)
	s_setprio 1
	s_barrier
	v_mfma_f32_16x16x32_bf16 v[124:127], v[128:131], v[144:147], v[124:127]
	v_mfma_f32_16x16x32_bf16 v[120:123], v[136:139], v[144:147], v[120:123]
	v_mfma_f32_16x16x32_bf16 v[108:111], v[128:131], v[152:155], v[108:111]
	v_mfma_f32_16x16x32_bf16 v[104:107], v[136:139], v[152:155], v[104:107]
	v_mfma_f32_16x16x32_bf16 v[92:95], v[128:131], v[160:163], v[92:95]
	v_mfma_f32_16x16x32_bf16 v[88:91], v[136:139], v[160:163], v[88:91]
	v_mfma_f32_16x16x32_bf16 v[76:79], v[128:131], v[168:171], v[76:79]
	v_mfma_f32_16x16x32_bf16 v[72:75], v[136:139], v[168:171], v[72:75]
	v_mfma_f32_16x16x32_bf16 v[124:127], v[132:135], v[148:151], v[124:127]
	v_mfma_f32_16x16x32_bf16 v[120:123], v[140:143], v[148:151], v[120:123]
	v_mfma_f32_16x16x32_bf16 v[108:111], v[132:135], v[156:159], v[108:111]
	v_mfma_f32_16x16x32_bf16 v[104:107], v[140:143], v[156:159], v[104:107]
	v_mfma_f32_16x16x32_bf16 v[92:95], v[132:135], v[164:167], v[92:95]
	v_mfma_f32_16x16x32_bf16 v[88:91], v[140:143], v[164:167], v[88:91]
	v_mfma_f32_16x16x32_bf16 v[76:79], v[132:135], v[172:175], v[76:79]
	v_mfma_f32_16x16x32_bf16 v[72:75], v[140:143], v[172:175], v[72:75]
	s_waitcnt lgkmcnt(0)
	v_mfma_f32_16x16x32_bf16 v[116:119], v[192:195], v[144:147], v[116:119]
	v_mfma_f32_16x16x32_bf16 v[112:115], v[200:203], v[144:147], v[112:115]
	v_mfma_f32_16x16x32_bf16 v[100:103], v[192:195], v[152:155], v[100:103]
	v_mfma_f32_16x16x32_bf16 v[96:99], v[200:203], v[152:155], v[96:99]
	v_mfma_f32_16x16x32_bf16 v[84:87], v[192:195], v[160:163], v[84:87]
	v_mfma_f32_16x16x32_bf16 v[80:83], v[200:203], v[160:163], v[80:83]
	v_mfma_f32_16x16x32_bf16 v[68:71], v[192:195], v[168:171], v[68:71]
	v_mfma_f32_16x16x32_bf16 v[64:67], v[200:203], v[168:171], v[64:67]
	v_mfma_f32_16x16x32_bf16 v[116:119], v[196:199], v[148:151], v[116:119]
	v_mfma_f32_16x16x32_bf16 v[112:115], v[212:215], v[148:151], v[112:115]
	v_mfma_f32_16x16x32_bf16 v[100:103], v[196:199], v[156:159], v[100:103]
	v_mfma_f32_16x16x32_bf16 v[96:99], v[212:215], v[156:159], v[96:99]
	v_mfma_f32_16x16x32_bf16 v[84:87], v[196:199], v[164:167], v[84:87]
	v_mfma_f32_16x16x32_bf16 v[80:83], v[212:215], v[164:167], v[80:83]
	v_mfma_f32_16x16x32_bf16 v[68:71], v[196:199], v[172:175], v[68:71]
	v_mfma_f32_16x16x32_bf16 v[64:67], v[212:215], v[172:175], v[64:67]
	s_barrier
	s_setprio 0
	s_add_i32 s27, s54, s35
	s_mov_b32 m0, s27
	s_nop 0
	global_load_lds_dwordx4 v180, s[98:99]
	s_add_i32 m0, s27, 0x2000
	s_nop 0
	global_load_lds_dwordx4 v176, s[98:99]
	s_mov_b32 m0, s46
	s_nop 0
	global_load_lds_dwordx4 v182, s[100:101]
	s_mov_b32 m0, s47
	s_nop 0
	global_load_lds_dwordx4 v178, s[100:101]
	ds_read_b128 v[144:147], v208 offset:49152
	ds_read_b128 v[148:151], v208 offset:50176
	ds_read_b128 v[152:155], v208 offset:51200
	ds_read_b128 v[156:159], v208 offset:52224
	ds_read_b128 v[160:163], v208 offset:53248
	ds_read_b128 v[164:167], v208 offset:54272
	ds_read_b128 v[168:171], v208 offset:55296
	ds_read_b128 v[172:175], v208 offset:56320
	s_add_u32 s24, s24, 0x80080
	s_addc_u32 s25, s25, 0
	s_add_i32 s26, s26, s35
	s_add_i32 s53, s53, 2
	s_add_u32 s22, s22, 0x100
	s_addc_u32 s23, s23, 0
	s_add_u32 s45, s45, 0x100
	s_addc_u32 s52, s52, 0
	s_cmp_gt_u32 s53, 29
	s_waitcnt vmcnt(6)
	s_waitcnt lgkmcnt(0)
	s_setprio 1
	s_barrier
	v_mfma_f32_16x16x32_bf16 v[60:63], v[128:131], v[144:147], v[60:63]
	s_mov_b32 m0, s26
	v_mfma_f32_16x16x32_bf16 v[56:59], v[136:139], v[144:147], v[56:59]
	global_load_lds_dwordx4 v180, s[24:25]
	v_mfma_f32_16x16x32_bf16 v[44:47], v[128:131], v[152:155], v[44:47]
	s_bitset1_b32 m0, 13
	v_mfma_f32_16x16x32_bf16 v[40:43], v[136:139], v[152:155], v[40:43]
	global_load_lds_dwordx4 v176, s[24:25]
	v_mfma_f32_16x16x32_bf16 v[28:31], v[128:131], v[160:163], v[28:31]
	v_mfma_f32_16x16x32_bf16 v[24:27], v[136:139], v[160:163], v[24:27]
	v_mfma_f32_16x16x32_bf16 v[12:15], v[128:131], v[168:171], v[12:15]
	v_mfma_f32_16x16x32_bf16 v[8:11], v[136:139], v[168:171], v[8:11]
	v_mfma_f32_16x16x32_bf16 v[60:63], v[132:135], v[148:151], v[60:63]
	v_mfma_f32_16x16x32_bf16 v[56:59], v[140:143], v[148:151], v[56:59]
	v_mfma_f32_16x16x32_bf16 v[44:47], v[132:135], v[156:159], v[44:47]
	v_mfma_f32_16x16x32_bf16 v[40:43], v[140:143], v[156:159], v[40:43]
	v_mfma_f32_16x16x32_bf16 v[28:31], v[132:135], v[164:167], v[28:31]
	v_mfma_f32_16x16x32_bf16 v[24:27], v[140:143], v[164:167], v[24:27]
	v_mfma_f32_16x16x32_bf16 v[12:15], v[132:135], v[172:175], v[12:15]
	v_mfma_f32_16x16x32_bf16 v[8:11], v[140:143], v[172:175], v[8:11]
	v_mfma_f32_16x16x32_bf16 v[52:55], v[192:195], v[144:147], v[52:55]
	v_mfma_f32_16x16x32_bf16 v[48:51], v[200:203], v[144:147], v[48:51]
	v_mfma_f32_16x16x32_bf16 v[36:39], v[192:195], v[152:155], v[36:39]
	v_mfma_f32_16x16x32_bf16 v[32:35], v[200:203], v[152:155], v[32:35]
	v_mfma_f32_16x16x32_bf16 v[20:23], v[192:195], v[160:163], v[20:23]
	v_mfma_f32_16x16x32_bf16 v[16:19], v[200:203], v[160:163], v[16:19]
	v_mfma_f32_16x16x32_bf16 v[4:7], v[192:195], v[168:171], v[4:7]
	v_mfma_f32_16x16x32_bf16 v[0:3], v[200:203], v[168:171], v[0:3]
	v_mfma_f32_16x16x32_bf16 v[52:55], v[196:199], v[148:151], v[52:55]
	v_mfma_f32_16x16x32_bf16 v[48:51], v[212:215], v[148:151], v[48:51]
	v_mfma_f32_16x16x32_bf16 v[36:39], v[196:199], v[156:159], v[36:39]
	v_mfma_f32_16x16x32_bf16 v[32:35], v[212:215], v[156:159], v[32:35]
	v_mfma_f32_16x16x32_bf16 v[20:23], v[196:199], v[164:167], v[20:23]
	v_mfma_f32_16x16x32_bf16 v[16:19], v[212:215], v[164:167], v[16:19]
	v_mfma_f32_16x16x32_bf16 v[4:7], v[196:199], v[172:175], v[4:7]
	v_mfma_f32_16x16x32_bf16 v[0:3], v[212:215], v[172:175], v[0:3]
	s_barrier
; DI unsigned pack2(float lo, float hi) { f32x2 v = {lo, hi}; bf16v2 r = __builtin_convertvector(v, bf16v2); return __builtin_bit_cast(unsigned, r); }
;   DI void operator()(const f32x4 (&acc)[2][2][4][2], const Unit& u, int wr, int wc, int fr, int fq) const {
;     const int row0 = u.pm * BM + wr * 64 + fr, col0 = u.pn * BM + wc * 32 + 8 * fq;
; #pragma unroll
;     for (int ai = 0; ai < 2; ++ai) {
;       f32x4 bv[4][2][2];
; #pragma unroll
;       for (int m = 0; m < 4; ++m)
; #pragma unroll
;         for (int bj = 0; bj < 2; ++bj) {
;           const float* bp = base + (size_t)(row0 + ai * HALF + m * 16) * 2048 + col0 + bj * HALF;
;           bv[m][bj][0] = *(const f32x4*)bp; bv[m][bj][1] = *(const f32x4*)(bp + 4);
;         }
; #pragma unroll
;       for (int m = 0; m < 4; ++m) {
;         const int row = row0 + ai * HALF + m * 16;
;         const size_t off = (size_t)row * 2048 + col0;
;         float ss = 0.f;
; #pragma unroll
;         for (int bj = 0; bj < 2; ++bj) {
;           const f32x4 v0 = acc[ai][bj][m][0] + bv[m][bj][0], v1 = acc[ai][bj][m][1] + bv[m][bj][1];
;           *(f32x4*)(C + off + bj * HALF) = v0; *(f32x4*)(C + off + bj * HALF + 4) = v1;
;           if (xb) {
;             u32x4 w; w.x = pack2(v0[0], v0[1]); w.y = pack2(v0[2], v0[3]); w.z = pack2(v1[0], v1[1]); w.w = pack2(v1[2], v1[3]);
;             *(u32x4*)(xb + off + bj * HALF) = w;
;             ss += v0[0] * v0[0] + v0[1] * v0[1] + v0[2] * v0[2] + v0[3] * v0[3] + v1[0] * v1[0] + v1[1] * v1[1] + v1[2] * v1[2] + v1[3] * v1[3];
;           }
;         }
;         if (xb) {
;           ss += __shfl_xor(ss, 16); ss += __shfl_xor(ss, 32);
;           if (fq == 0) ssq[(size_t)row * 32 + u.pn * 4 + wc] = ss;
	s_setprio 0
	s_cbranch_scc0 .LBB0_728
	v_lshl_add_u32 v196, s12, 8, v204
	v_lshl_or_b32 v192, s42, 8, v206
	v_ashrrev_i32_e32 v193, 31, v192
	v_ashrrev_i32_e32 v197, 31, v196
	v_lshl_add_u64 v[194:195], v[192:193], 2, s[60:61]
	v_lshlrev_b64 v[128:129], 13, v[196:197]
	v_lshl_add_u64 v[128:129], v[194:195], 0, v[128:129]
	global_load_dwordx4 v[214:217], v[128:129], off
	global_load_dwordx4 v[218:221], v[128:129], off offset:16
	global_load_dwordx4 v[222:225], v[128:129], off offset:512
	global_load_dwordx4 v[226:229], v[128:129], off offset:528
	v_or_b32_e32 v202, 16, v196
	v_or_b32_e32 v200, 32, v196
	v_or_b32_e32 v198, 48, v196
	v_ashrrev_i32_e32 v203, 31, v202
	v_ashrrev_i32_e32 v201, 31, v200
	v_ashrrev_i32_e32 v199, 31, v198
	v_lshlrev_b64 v[128:129], 13, v[202:203]
	v_lshlrev_b64 v[130:131], 13, v[200:201]
	v_lshlrev_b64 v[132:133], 13, v[198:199]
	v_lshl_add_u64 v[128:129], v[194:195], 0, v[128:129]
	v_lshl_add_u64 v[130:131], v[194:195], 0, v[130:131]
	v_lshl_add_u64 v[132:133], v[194:195], 0, v[132:133]
	global_load_dwordx4 v[168:171], v[128:129], off offset:16
	global_load_dwordx4 v[172:175], v[128:129], off
	global_load_dwordx4 v[160:163], v[128:129], off offset:528
	global_load_dwordx4 v[164:167], v[128:129], off offset:512
	global_load_dwordx4 v[152:155], v[130:131], off offset:16
	global_load_dwordx4 v[156:159], v[130:131], off
	global_load_dwordx4 v[144:147], v[130:131], off offset:528
	global_load_dwordx4 v[148:151], v[130:131], off offset:512
	global_load_dwordx4 v[136:139], v[132:133], off offset:16
	global_load_dwordx4 v[140:143], v[132:133], off
	s_nop 0
	global_load_dwordx4 v[128:131], v[132:133], off offset:528
	s_nop 0
	global_load_dwordx4 v[132:135], v[132:133], off offset:512
	v_and_b32_e32 v212, 64, v211
	v_xor_b32_e32 v230, 16, v211
	v_add_u32_e32 v232, 64, v212
	v_xor_b32_e32 v231, 32, v211
	v_cmp_lt_i32_e32 vcc, v230, v232
	v_lshlrev_b64 v[212:213], 11, v[196:197]
	v_readlane_b32 s64, v243, 3
	v_cndmask_b32_e32 v233, v211, v230, vcc
	v_cmp_lt_i32_e32 vcc, v231, v232
	v_readlane_b32 s78, v243, 17
	v_readlane_b32 s79, v243, 18
	v_cndmask_b32_e32 v234, v211, v231, vcc
	v_lshl_add_u64 v[230:231], v[212:213], 0, v[192:193]
	v_lshlrev_b32_e32 v212, 2, v233
	v_lshl_add_u64 v[232:233], v[230:231], 2, s[78:79]
	v_lshl_add_u64 v[230:231], v[230:231], 1, s[2:3]
	s_lshl_b32 s22, s42, 2
	s_ashr_i32 s23, s22, 31
	v_readlane_b32 s65, v243, 4
	v_readlane_b32 s66, v243, 5
	v_readlane_b32 s67, v243, 6
	v_readlane_b32 s68, v243, 7
	v_readlane_b32 s69, v243, 8
	v_readlane_b32 s70, v243, 9
	v_readlane_b32 s71, v243, 10
	v_readlane_b32 s72, v243, 11
	v_readlane_b32 s73, v243, 12
	v_readlane_b32 s74, v243, 13
	v_readlane_b32 s75, v243, 14
	v_readlane_b32 s76, v243, 15
	v_readlane_b32 s77, v243, 16
	s_waitcnt vmcnt(0)
	v_pk_add_f32 v[126:127], v[126:127], v[216:217]
	v_pk_add_f32 v[124:125], v[124:125], v[214:215]
	v_pk_add_f32 v[116:117], v[116:117], v[222:223]
	v_pk_add_f32 v[122:123], v[122:123], v[220:221]
	v_pk_add_f32 v[120:121], v[120:121], v[218:219]
	v_pk_add_f32 v[214:215], v[112:113], v[226:227]
	global_store_dwordx4 v[232:233], v[124:127], off
	global_store_dwordx4 v[232:233], v[120:123], off offset:16
	v_cvt_pk_bf16_f32 v112, v124, v125
	v_mul_f32_e32 v125, v125, v125
	v_mul_f32_e32 v213, v117, v117
	v_pk_add_f32 v[118:119], v[118:119], v[224:225]
	v_fmac_f32_e32 v125, v124, v124
	v_fmac_f32_e32 v213, v116, v116
	v_fmac_f32_e32 v125, v126, v126
	v_fmac_f32_e32 v213, v118, v118
	v_fmac_f32_e32 v125, v127, v127
	v_fmac_f32_e32 v213, v119, v119
	v_fmac_f32_e32 v125, v120, v120
	v_fmac_f32_e32 v213, v214, v214
	v_pk_add_f32 v[216:217], v[114:115], v[228:229]
	v_fmac_f32_e32 v125, v121, v121
	v_fmac_f32_e32 v213, v215, v215
	v_fmac_f32_e32 v125, v122, v122
	v_fmac_f32_e32 v213, v216, v216
	v_fmac_f32_e32 v125, v123, v123
	v_fmac_f32_e32 v213, v217, v217
	v_cvt_pk_bf16_f32 v114, v120, v121
	v_add_f32_e32 v120, v125, v213
	ds_bpermute_b32 v121, v212, v120
	v_cvt_pk_bf16_f32 v113, v126, v127
	v_cvt_pk_bf16_f32 v115, v122, v123
	global_store_dwordx4 v[230:231], v[112:115], off
	global_store_dwordx4 v[232:233], v[116:119], off offset:512
	global_store_dwordx4 v[232:233], v[214:217], off offset:528
	v_cvt_pk_bf16_f32 v122, v116, v117
	s_waitcnt lgkmcnt(0)
	v_add_f32_e32 v112, v120, v121
	v_lshlrev_b32_e32 v120, 2, v234
	ds_bpermute_b32 v113, v120, v112
	v_cvt_pk_bf16_f32 v123, v118, v119
	v_cvt_pk_bf16_f32 v124, v214, v215
	v_cvt_pk_bf16_f32 v125, v216, v217
	global_store_dwordx4 v[230:231], v[122:125], off offset:256
	s_and_saveexec_b64 s[24:25], s[0:1]
	s_cbranch_execz .LBB0_731
	s_waitcnt lgkmcnt(0)
	v_add_f32_e32 v114, v112, v113
	v_lshlrev_b64 v[112:113], 7, v[196:197]
	v_lshl_add_u64 v[112:113], s[8:9], 0, v[112:113]
	v_lshl_add_u64 v[112:113], s[22:23], 2, v[112:113]
	s_lshl_b32 s12, s41, 2
	v_lshl_add_u64 v[112:113], v[112:113], 0, s[12:13]
	global_store_dword v[112:113], v114, off

; #define PG8_STAGE(bufoff, gbase, voff) do { _Pragma("unroll") for (int _i = 0; _i < 2; ++_i) \
;     __builtin_amdgcn_global_load_lds((const unsigned*)((const char*)(gbase) + (voff)[_i]), (LAS unsigned*)(lds + (bufoff) + ldsw + _i * 8192), 16, 0, 0); } while (0)
; #define PG8_LDA(dst, b, h) do { _Pragma("unroll") for (int m = 0; m < 4; ++m) _Pragma("unroll") for (int k = 0; k < 2; ++k) dst[m][k] = *(const LAS bf16x8*)(lds + PG8_SA(b, h) + aoff + m * 2048 + k * 1024); } while (0)
; #define PG8_LDB(dst, b, h) do { _Pragma("unroll") for (int n = 0; n < 2; ++n) _Pragma("unroll") for (int k = 0; k < 2; ++k) dst[n][k] = *(const LAS bf16x8*)(lds + PG8_SB(b, h) + boff + n * 2048 + k * 1024); } while (0)
; #define PG8_MMA(ai, bj, At, Bt) do { __builtin_amdgcn_s_setprio(1); _Pragma("unroll") for (int m = 0; m < 4; ++m) _Pragma("unroll") for (int n = 0; n < 2; ++n) _Pragma("unroll") for (int k = 0; k < 2; ++k) \
;     acc[ai][bj][m][n] = __builtin_amdgcn_mfma_f32_16x16x32_bf16(Bt[n][k], At[m][k], acc[ai][bj][m][n], 0, 0, 0); __builtin_amdgcn_s_setprio(0); } while (0)
; #define PG8_WAIT_V(n) asm volatile("s_waitcnt vmcnt(" #n ")" ::: "memory")
; #define PG8_WAIT_L(n) asm volatile("s_waitcnt lgkmcnt(" #n ")" ::: "memory")
; #define PG8_BAR __builtin_amdgcn_s_barrier()
; #define PG8_SCHED __builtin_amdgcn_sched_barrier(0)
; template <class Epi, class Sched = StaticOrder>
; DI void gemm_phase(LAS unsigned char* lds, const Gemm g, const Sched& S, const Epi& E) {
;     ...
;       PG8_LDB(B0, 0, 0); PG8_SCHED; PG8_LDA(At, 0, 0); PG8_STAGE(PG8_SA(1, 1), a1 + hstep, voffA);
;       PG8_WAIT_L(8); PG8_BAR; PG8_WAIT_L(0); PG8_MMA(0, 0, At, B0); PG8_BAR; PG8_SCHED;
;       PG8_LDB(B1, 0, 1); PG8_STAGE(PG8_SB(0, 0), b2, voffB);
;       PG8_BAR; PG8_WAIT_L(0); PG8_MMA(0, 1, At, B1); PG8_BAR;
;       PG8_LDA(At, 0, 1); PG8_STAGE(PG8_SA(0, 0), a2, voffA);
;       PG8_BAR; PG8_WAIT_L(0); PG8_MMA(1, 0, At, B0); PG8_BAR; PG8_SCHED;
;       PG8_STAGE(PG8_SB(0, 1), b2 + hstep, voffB);
;       PG8_WAIT_V(6); PG8_BAR; PG8_MMA(1, 1, At, B1); PG8_BAR;
.LBB0_811:
	ds_read_b128 v[64:67], v201
	ds_read_b128 v[68:71], v201 offset:1024
	ds_read_b128 v[72:75], v201 offset:2048
	ds_read_b128 v[76:79], v201 offset:3072
	s_add_u32 s46, s14, 0xfff80080
	s_addc_u32 s47, s15, -1
	s_cmp_eq_u32 s52, 28
	s_cselect_b32 s49, s37, s47
	s_cselect_b32 s48, s42, s46
	s_cselect_b32 s47, s35, s45
	s_cselect_b32 s46, s43, s44
	s_add_i32 m0, s62, 0xc000
	ds_read_b128 v[80:83], v202
	ds_read_b128 v[84:87], v202 offset:1024
	ds_read_b128 v[92:95], v202 offset:2048
	ds_read_b128 v[96:99], v202 offset:3072
	ds_read_b128 v[180:183], v202 offset:4096
	ds_read_b128 v[184:187], v202 offset:5120
	ds_read_b128 v[188:191], v202 offset:6144
	ds_read_b128 v[192:195], v202 offset:7168
	global_load_lds_dwordx4 v170, s[14:15]
	s_add_i32 m0, s62, 0xe000
	s_nop 0
	global_load_lds_dwordx4 v172, s[14:15]
	ds_read_b128 v[206:209], v203
	ds_read_b128 v[212:215], v203 offset:1024
	ds_read_b128 v[216:219], v203 offset:2048
	ds_read_b128 v[220:223], v203 offset:3072
	s_waitcnt vmcnt(8)
	s_waitcnt lgkmcnt(4)
	s_setprio 1
	s_barrier
	v_mfma_f32_16x16x32_bf16 v[156:159], v[64:67], v[80:83], v[156:159]
	v_mfma_f32_16x16x32_bf16 v[144:147], v[72:75], v[80:83], v[144:147]
	v_mfma_f32_16x16x32_bf16 v[140:143], v[64:67], v[92:95], v[140:143]
	v_mfma_f32_16x16x32_bf16 v[132:135], v[72:75], v[92:95], v[132:135]
	v_mfma_f32_16x16x32_bf16 v[124:127], v[64:67], v[180:183], v[124:127]
	v_mfma_f32_16x16x32_bf16 v[116:119], v[72:75], v[180:183], v[116:119]
	v_mfma_f32_16x16x32_bf16 v[112:115], v[64:67], v[188:191], v[112:115]
	v_mfma_f32_16x16x32_bf16 v[108:111], v[72:75], v[188:191], v[108:111]
	v_mfma_f32_16x16x32_bf16 v[156:159], v[68:71], v[84:87], v[156:159]
	v_mfma_f32_16x16x32_bf16 v[144:147], v[76:79], v[84:87], v[144:147]
	v_mfma_f32_16x16x32_bf16 v[140:143], v[68:71], v[96:99], v[140:143]
	v_mfma_f32_16x16x32_bf16 v[132:135], v[76:79], v[96:99], v[132:135]
	v_mfma_f32_16x16x32_bf16 v[124:127], v[68:71], v[184:187], v[124:127]
	v_mfma_f32_16x16x32_bf16 v[116:119], v[76:79], v[184:187], v[116:119]
	v_mfma_f32_16x16x32_bf16 v[112:115], v[68:71], v[192:195], v[112:115]
	v_mfma_f32_16x16x32_bf16 v[108:111], v[76:79], v[192:195], v[108:111]
	s_waitcnt lgkmcnt(0)
	v_mfma_f32_16x16x32_bf16 v[152:155], v[206:209], v[80:83], v[152:155]
	v_mfma_f32_16x16x32_bf16 v[80:83], v[216:219], v[80:83], v[148:151]
	v_mfma_f32_16x16x32_bf16 v[152:155], v[212:215], v[84:87], v[152:155]
	v_mfma_f32_16x16x32_bf16 v[80:83], v[220:223], v[84:87], v[80:83]
	v_mfma_f32_16x16x32_bf16 v[84:87], v[206:209], v[92:95], v[136:139]
	v_mfma_f32_16x16x32_bf16 v[92:95], v[216:219], v[92:95], v[128:131]
	v_mfma_f32_16x16x32_bf16 v[104:107], v[216:219], v[180:183], v[104:107]
	v_mfma_f32_16x16x32_bf16 v[100:103], v[206:209], v[188:191], v[100:103]
	v_mfma_f32_16x16x32_bf16 v[88:91], v[216:219], v[188:191], v[88:91]
	v_mfma_f32_16x16x32_bf16 v[84:87], v[212:215], v[96:99], v[84:87]
	v_mfma_f32_16x16x32_bf16 v[92:95], v[220:223], v[96:99], v[92:95]
	v_mfma_f32_16x16x32_bf16 v[96:99], v[206:209], v[180:183], v[120:123]
	v_mfma_f32_16x16x32_bf16 v[104:107], v[220:223], v[184:187], v[104:107]
	v_mfma_f32_16x16x32_bf16 v[100:103], v[212:215], v[192:195], v[100:103]
	v_mfma_f32_16x16x32_bf16 v[88:91], v[220:223], v[192:195], v[88:91]
	v_mfma_f32_16x16x32_bf16 v[96:99], v[212:215], v[184:187], v[96:99]
	s_barrier
	s_setprio 0
	s_add_i32 s53, s72, s60
	s_add_u32 s98, s46, 0x80
	s_addc_u32 s99, s47, 0
	s_add_u32 s100, s48, 0x80
	s_addc_u32 s101, s49, 0
	s_mov_b32 m0, s53
	s_nop 0
	global_load_lds_dwordx4 v164, s[46:47]
	s_add_i32 m0, s53, 0x2000
	s_nop 0
	global_load_lds_dwordx4 v160, s[46:47]
	s_mov_b32 m0, s62
	s_nop 0
	global_load_lds_dwordx4 v166, s[48:49]
	s_mov_b32 m0, s63
	s_nop 0
	global_load_lds_dwordx4 v162, s[48:49]
	ds_read_b128 v[120:123], v202 offset:16384
	ds_read_b128 v[128:131], v202 offset:17408
	ds_read_b128 v[136:139], v202 offset:18432
	ds_read_b128 v[148:151], v202 offset:19456
	ds_read_b128 v[180:183], v202 offset:20480
	ds_read_b128 v[184:187], v202 offset:21504
	ds_read_b128 v[188:191], v202 offset:22528
	ds_read_b128 v[192:195], v202 offset:23552
	s_add_u32 s54, s46, 0x80000
	s_addc_u32 s55, s47, 0
	s_add_i32 s53, s73, s60
	s_waitcnt vmcnt(6)
	s_waitcnt lgkmcnt(0)
	s_setprio 1
	s_barrier
	v_mfma_f32_16x16x32_bf16 v[60:63], v[64:67], v[120:123], v[60:63]
	s_mov_b32 m0, s53
	v_mfma_f32_16x16x32_bf16 v[48:51], v[72:75], v[120:123], v[48:51]
	global_load_lds_dwordx4 v164, s[54:55]
	v_mfma_f32_16x16x32_bf16 v[44:47], v[64:67], v[136:139], v[44:47]
	s_bitset1_b32 m0, 13
	v_mfma_f32_16x16x32_bf16 v[36:39], v[72:75], v[136:139], v[36:39]
	global_load_lds_dwordx4 v160, s[54:55]
	v_mfma_f32_16x16x32_bf16 v[28:31], v[64:67], v[180:183], v[28:31]
	v_mfma_f32_16x16x32_bf16 v[20:23], v[72:75], v[180:183], v[20:23]
	v_mfma_f32_16x16x32_bf16 v[16:19], v[64:67], v[188:191], v[16:19]
	v_mfma_f32_16x16x32_bf16 v[12:15], v[72:75], v[188:191], v[12:15]
	v_mfma_f32_16x16x32_bf16 v[60:63], v[68:71], v[128:131], v[60:63]
	v_mfma_f32_16x16x32_bf16 v[48:51], v[76:79], v[128:131], v[48:51]
	v_mfma_f32_16x16x32_bf16 v[44:47], v[68:71], v[148:151], v[44:47]
	v_mfma_f32_16x16x32_bf16 v[36:39], v[76:79], v[148:151], v[36:39]
	v_mfma_f32_16x16x32_bf16 v[28:31], v[68:71], v[184:187], v[28:31]
	v_mfma_f32_16x16x32_bf16 v[20:23], v[76:79], v[184:187], v[20:23]
	v_mfma_f32_16x16x32_bf16 v[16:19], v[68:71], v[192:195], v[16:19]
	v_mfma_f32_16x16x32_bf16 v[12:15], v[76:79], v[192:195], v[12:15]
	v_mfma_f32_16x16x32_bf16 v[56:59], v[206:209], v[120:123], v[56:59]
	v_mfma_f32_16x16x32_bf16 v[52:55], v[216:219], v[120:123], v[52:55]
	v_mfma_f32_16x16x32_bf16 v[40:43], v[206:209], v[136:139], v[40:43]
	v_mfma_f32_16x16x32_bf16 v[32:35], v[216:219], v[136:139], v[32:35]
	v_mfma_f32_16x16x32_bf16 v[24:27], v[206:209], v[180:183], v[24:27]
	v_mfma_f32_16x16x32_bf16 v[8:11], v[216:219], v[180:183], v[8:11]
	v_mfma_f32_16x16x32_bf16 v[4:7], v[206:209], v[188:191], v[4:7]
	v_mfma_f32_16x16x32_bf16 v[0:3], v[216:219], v[188:191], v[0:3]
	v_mfma_f32_16x16x32_bf16 v[56:59], v[212:215], v[128:131], v[56:59]
	v_mfma_f32_16x16x32_bf16 v[52:55], v[220:223], v[128:131], v[52:55]
	v_mfma_f32_16x16x32_bf16 v[40:43], v[212:215], v[148:151], v[40:43]
	v_mfma_f32_16x16x32_bf16 v[32:35], v[220:223], v[148:151], v[32:35]
	v_mfma_f32_16x16x32_bf16 v[24:27], v[212:215], v[184:187], v[24:27]
	v_mfma_f32_16x16x32_bf16 v[8:11], v[220:223], v[184:187], v[8:11]
	v_mfma_f32_16x16x32_bf16 v[4:7], v[212:215], v[192:195], v[4:7]
	v_mfma_f32_16x16x32_bf16 v[0:3], v[220:223], v[192:195], v[0:3]
	s_barrier
; #define PG8_STAGE(bufoff, gbase, voff) do { _Pragma("unroll") for (int _i = 0; _i < 2; ++_i) \
;     __builtin_amdgcn_global_load_lds((const unsigned*)((const char*)(gbase) + (voff)[_i]), (LAS unsigned*)(lds + (bufoff) + ldsw + _i * 8192), 16, 0, 0); } while (0)
; #define PG8_LDA(dst, b, h) do { _Pragma("unroll") for (int m = 0; m < 4; ++m) _Pragma("unroll") for (int k = 0; k < 2; ++k) dst[m][k] = *(const LAS bf16x8*)(lds + PG8_SA(b, h) + aoff + m * 2048 + k * 1024); } while (0)
; #define PG8_LDB(dst, b, h) do { _Pragma("unroll") for (int n = 0; n < 2; ++n) _Pragma("unroll") for (int k = 0; k < 2; ++k) dst[n][k] = *(const LAS bf16x8*)(lds + PG8_SB(b, h) + boff + n * 2048 + k * 1024); } while (0)
; #define PG8_MMA(ai, bj, At, Bt) do { __builtin_amdgcn_s_setprio(1); _Pragma("unroll") for (int m = 0; m < 4; ++m) _Pragma("unroll") for (int n = 0; n < 2; ++n) _Pragma("unroll") for (int k = 0; k < 2; ++k) \
;     acc[ai][bj][m][n] = __builtin_amdgcn_mfma_f32_16x16x32_bf16(Bt[n][k], At[m][k], acc[ai][bj][m][n], 0, 0, 0); __builtin_amdgcn_s_setprio(0); } while (0)
; #define PG8_WAIT_V(n) asm volatile("s_waitcnt vmcnt(" #n ")" ::: "memory")
; #define PG8_WAIT_L(n) asm volatile("s_waitcnt lgkmcnt(" #n ")" ::: "memory")
; #define PG8_BAR __builtin_amdgcn_s_barrier()
; #define PG8_SCHED __builtin_amdgcn_sched_barrier(0)
; template <class Epi, class Sched = StaticOrder>
; DI void gemm_phase(LAS unsigned char* lds, const Gemm g, const Sched& S, const Epi& E) {
;     ...
;       PG8_LDB(B0, 1, 0); PG8_SCHED; PG8_LDA(At, 1, 0); PG8_STAGE(PG8_SA(0, 1), a2 + hstep, voffA);
;       PG8_WAIT_L(8); PG8_BAR; PG8_WAIT_L(0); PG8_MMA(0, 0, At, B0); PG8_BAR; PG8_SCHED;
;       PG8_LDB(B1, 1, 1); PG8_STAGE(PG8_SB(1, 0), b3, voffB);
;       PG8_BAR; PG8_WAIT_L(0); PG8_MMA(0, 1, At, B1); PG8_BAR;
;       PG8_LDA(At, 1, 1); PG8_STAGE(PG8_SA(1, 0), a3, voffA);
;       PG8_BAR; PG8_WAIT_L(0); PG8_MMA(1, 0, At, B0); PG8_BAR; PG8_SCHED;
;       PG8_STAGE(PG8_SB(1, 1), b3 + hstep, voffB);
;       PG8_WAIT_V(6); PG8_BAR; PG8_MMA(1, 1, At, B1); PG8_BAR;
	s_setprio 0
	s_add_i32 s53, 0, 0x18000
	v_add_u32_e32 v76, s53, v198
	ds_read_b128 v[64:67], v76
	ds_read_b128 v[68:71], v76 offset:1024
	ds_read_b128 v[72:75], v76 offset:2048
	ds_read_b128 v[76:79], v76 offset:3072
	s_add_u32 s48, s48, 0x80000
	s_addc_u32 s49, s49, 0
	s_mov_b32 m0, s64
	ds_read_b128 v[120:123], v202 offset:32768
	ds_read_b128 v[128:131], v202 offset:33792
	ds_read_b128 v[180:183], v202 offset:34816
	ds_read_b128 v[184:187], v202 offset:35840
	ds_read_b128 v[188:191], v202 offset:36864
	ds_read_b128 v[192:195], v202 offset:37888
	ds_read_b128 v[206:209], v202 offset:38912
	ds_read_b128 v[212:215], v202 offset:39936
	global_load_lds_dwordx4 v166, s[48:49]
	s_mov_b32 m0, s65
	s_nop 0
	global_load_lds_dwordx4 v162, s[48:49]
	s_add_i32 s48, 0, 0x1c000
	v_add_u32_e32 v244, s48, v198
	ds_read_b128 v[216:219], v244
	ds_read_b128 v[220:223], v244 offset:1024
	ds_read_b128 v[224:227], v244 offset:2048
	ds_read_b128 v[228:231], v244 offset:3072
	s_waitcnt vmcnt(8)
	s_waitcnt lgkmcnt(4)
	s_setprio 1
	s_barrier
	v_mfma_f32_16x16x32_bf16 v[136:139], v[64:67], v[120:123], v[156:159]
	v_mfma_f32_16x16x32_bf16 v[156:159], v[68:71], v[128:131], v[136:139]
	v_mfma_f32_16x16x32_bf16 v[136:139], v[72:75], v[120:123], v[144:147]
	v_mfma_f32_16x16x32_bf16 v[144:147], v[76:79], v[128:131], v[136:139]
	v_mfma_f32_16x16x32_bf16 v[136:139], v[64:67], v[180:183], v[140:143]
	v_mfma_f32_16x16x32_bf16 v[132:135], v[72:75], v[180:183], v[132:135]
	v_mfma_f32_16x16x32_bf16 v[124:127], v[64:67], v[188:191], v[124:127]
	v_mfma_f32_16x16x32_bf16 v[116:119], v[72:75], v[188:191], v[116:119]
	v_mfma_f32_16x16x32_bf16 v[112:115], v[64:67], v[206:209], v[112:115]
	v_mfma_f32_16x16x32_bf16 v[108:111], v[72:75], v[206:209], v[108:111]
	v_mfma_f32_16x16x32_bf16 v[140:143], v[68:71], v[184:187], v[136:139]
	v_mfma_f32_16x16x32_bf16 v[132:135], v[76:79], v[184:187], v[132:135]
	v_mfma_f32_16x16x32_bf16 v[124:127], v[68:71], v[192:195], v[124:127]
	v_mfma_f32_16x16x32_bf16 v[116:119], v[76:79], v[192:195], v[116:119]
	v_mfma_f32_16x16x32_bf16 v[112:115], v[68:71], v[212:215], v[112:115]
	v_mfma_f32_16x16x32_bf16 v[108:111], v[76:79], v[212:215], v[108:111]
	s_waitcnt lgkmcnt(0)
	v_mfma_f32_16x16x32_bf16 v[80:83], v[224:227], v[120:123], v[80:83]
	v_mfma_f32_16x16x32_bf16 v[136:139], v[216:219], v[120:123], v[152:155]
	v_mfma_f32_16x16x32_bf16 v[148:151], v[228:231], v[128:131], v[80:83]
	v_mfma_f32_16x16x32_bf16 v[80:83], v[216:219], v[180:183], v[84:87]
	v_mfma_f32_16x16x32_bf16 v[152:155], v[220:223], v[128:131], v[136:139]
	v_mfma_f32_16x16x32_bf16 v[136:139], v[220:223], v[184:187], v[80:83]
	v_mfma_f32_16x16x32_bf16 v[80:83], v[224:227], v[180:183], v[92:95]
	v_mfma_f32_16x16x32_bf16 v[128:131], v[228:231], v[184:187], v[80:83]
	v_mfma_f32_16x16x32_bf16 v[80:83], v[216:219], v[188:191], v[96:99]
	v_mfma_f32_16x16x32_bf16 v[120:123], v[220:223], v[192:195], v[80:83]
	v_mfma_f32_16x16x32_bf16 v[80:83], v[224:227], v[188:191], v[104:107]
	v_mfma_f32_16x16x32_bf16 v[104:107], v[228:231], v[192:195], v[80:83]
	v_mfma_f32_16x16x32_bf16 v[80:83], v[216:219], v[206:209], v[100:103]
	v_mfma_f32_16x16x32_bf16 v[100:103], v[220:223], v[212:215], v[80:83]
	v_mfma_f32_16x16x32_bf16 v[80:83], v[224:227], v[206:209], v[88:91]
	v_mfma_f32_16x16x32_bf16 v[88:91], v[228:231], v[212:215], v[80:83]
	s_barrier
	s_setprio 0
	s_add_i32 s49, s53, s60
	s_mov_b32 m0, s49
	s_nop 0
	global_load_lds_dwordx4 v164, s[98:99]
	s_add_i32 m0, s49, 0x2000
	s_nop 0
	global_load_lds_dwordx4 v160, s[98:99]
	s_mov_b32 m0, s67
	s_nop 0
	global_load_lds_dwordx4 v166, s[100:101]
	s_mov_b32 m0, s68
	s_nop 0
	global_load_lds_dwordx4 v162, s[100:101]
	s_nop 2
	ds_read_b128 v[80:83], v202 offset:49152
	ds_read_b128 v[84:87], v202 offset:50176
	ds_read_b128 v[92:95], v202 offset:51200
	ds_read_b128 v[96:99], v202 offset:52224
	ds_read_b128 v[180:183], v202 offset:53248
	ds_read_b128 v[184:187], v202 offset:54272
	ds_read_b128 v[188:191], v202 offset:55296
	ds_read_b128 v[192:195], v202 offset:56320
	s_add_u32 s46, s46, 0x80080
	s_addc_u32 s47, s47, 0
	s_add_i32 s48, s48, s60
	s_add_i32 s52, s52, 2
	s_add_u32 s14, s14, 0x100
	s_addc_u32 s15, s15, 0
	s_add_u32 s44, s44, 0x100
	s_addc_u32 s45, s45, 0
	s_cmp_gt_u32 s52, 29
	s_waitcnt vmcnt(6)
	s_waitcnt lgkmcnt(0)
	s_setprio 1
	s_barrier
	v_mfma_f32_16x16x32_bf16 v[60:63], v[64:67], v[80:83], v[60:63]
	s_mov_b32 m0, s48
	v_mfma_f32_16x16x32_bf16 v[48:51], v[72:75], v[80:83], v[48:51]
	global_load_lds_dwordx4 v164, s[46:47]
	v_mfma_f32_16x16x32_bf16 v[44:47], v[64:67], v[92:95], v[44:47]
	s_bitset1_b32 m0, 13
	v_mfma_f32_16x16x32_bf16 v[36:39], v[72:75], v[92:95], v[36:39]
	global_load_lds_dwordx4 v160, s[46:47]
	v_mfma_f32_16x16x32_bf16 v[28:31], v[64:67], v[180:183], v[28:31]
	v_mfma_f32_16x16x32_bf16 v[20:23], v[72:75], v[180:183], v[20:23]
	v_mfma_f32_16x16x32_bf16 v[16:19], v[64:67], v[188:191], v[16:19]
	v_mfma_f32_16x16x32_bf16 v[12:15], v[72:75], v[188:191], v[12:15]
	v_mfma_f32_16x16x32_bf16 v[60:63], v[68:71], v[84:87], v[60:63]
	v_mfma_f32_16x16x32_bf16 v[48:51], v[76:79], v[84:87], v[48:51]
	v_mfma_f32_16x16x32_bf16 v[44:47], v[68:71], v[96:99], v[44:47]
	v_mfma_f32_16x16x32_bf16 v[36:39], v[76:79], v[96:99], v[36:39]
	v_mfma_f32_16x16x32_bf16 v[28:31], v[68:71], v[184:187], v[28:31]
	v_mfma_f32_16x16x32_bf16 v[20:23], v[76:79], v[184:187], v[20:23]
	v_mfma_f32_16x16x32_bf16 v[16:19], v[68:71], v[192:195], v[16:19]
	v_mfma_f32_16x16x32_bf16 v[12:15], v[76:79], v[192:195], v[12:15]
	v_mfma_f32_16x16x32_bf16 v[56:59], v[216:219], v[80:83], v[56:59]
	v_mfma_f32_16x16x32_bf16 v[52:55], v[224:227], v[80:83], v[52:55]
	v_mfma_f32_16x16x32_bf16 v[40:43], v[216:219], v[92:95], v[40:43]
	v_mfma_f32_16x16x32_bf16 v[32:35], v[224:227], v[92:95], v[32:35]
	v_mfma_f32_16x16x32_bf16 v[24:27], v[216:219], v[180:183], v[24:27]
	v_mfma_f32_16x16x32_bf16 v[8:11], v[224:227], v[180:183], v[8:11]
	v_mfma_f32_16x16x32_bf16 v[4:7], v[216:219], v[188:191], v[4:7]
	v_mfma_f32_16x16x32_bf16 v[0:3], v[224:227], v[188:191], v[0:3]
	v_mfma_f32_16x16x32_bf16 v[56:59], v[220:223], v[84:87], v[56:59]
	v_mfma_f32_16x16x32_bf16 v[52:55], v[228:231], v[84:87], v[52:55]
	v_mfma_f32_16x16x32_bf16 v[40:43], v[220:223], v[96:99], v[40:43]
	v_mfma_f32_16x16x32_bf16 v[32:35], v[228:231], v[96:99], v[32:35]
	v_mfma_f32_16x16x32_bf16 v[24:27], v[220:223], v[184:187], v[24:27]
	v_mfma_f32_16x16x32_bf16 v[8:11], v[228:231], v[184:187], v[8:11]
	v_mfma_f32_16x16x32_bf16 v[4:7], v[220:223], v[192:195], v[4:7]
	v_mfma_f32_16x16x32_bf16 v[0:3], v[228:231], v[192:195], v[0:3]
	s_barrier
; DI float row_rstd(const float* ssq, int row, int fq) {
;   const f32x4 a = *(const f32x4*)(ssq + (size_t)row * 32 + fq * 8), b = *(const f32x4*)(ssq + (size_t)row * 32 + fq * 8 + 4);
;   float sm = ((a[0] + a[1]) + (a[2] + a[3])) + ((b[0] + b[1]) + (b[2] + b[3]));
;   sm += __shfl_xor(sm, 16); sm += __shfl_xor(sm, 32);
;   return rsqrtf(sm * (1.0f / 2048.f) + 1e-6f);
; }
;   DI void operator()(const f32x4 (&acc)[2][2][4][2], const Unit& u, int wr, int wc, int fr, int fq) const {
;     const int col = u.pn * 128 + wc * 32 + 8 * fq;
;     float w0[8], w1[8], w2[8], bb[8];
; #pragma unroll
;     for (int e = 0; e < 8; ++e) { w0[e] = cw[col + e]; w1[e] = cw[5632 + col + e]; w2[e] = cw[2 * 5632 + col + e]; bb[e] = cb[col + e]; }
; #pragma unroll
;     for (int ai = 0; ai < 2; ++ai) {
;       const int row0 = u.pm * BM + ai * HALF + wr * 64, span = row0 >> 6;
;       float rsv[4];
; #pragma unroll
;       for (int m = 0; m < 4; ++m) rsv[m] = row_rstd(ssq, row0 + 16 * m + fr, fq);
	s_setprio 0
	s_cbranch_scc0 .LBB0_811
	s_lshl_b32 s35, s12, 8
	s_add_i32 s35, s35, s66
	v_or_b32_e32 v190, s35, v179
	v_ashrrev_i32_e32 v191, 31, v190
	v_lshlrev_b64 v[64:65], 7, v[190:191]
	v_or_b32_e32 v188, 16, v190
	v_lshl_add_u64 v[64:65], v[168:169], 0, v[64:65]
	v_ashrrev_i32_e32 v189, 31, v188
	global_load_dwordx4 v[192:195], v[64:65], off
	global_load_dwordx4 v[206:209], v[64:65], off offset:16
	v_lshlrev_b64 v[64:65], 7, v[188:189]
	v_lshl_add_u64 v[64:65], v[168:169], 0, v[64:65]
	global_load_dwordx4 v[212:215], v[64:65], off
	global_load_dwordx4 v[216:219], v[64:65], off offset:16
	v_or_b32_e32 v186, 32, v190
	v_ashrrev_i32_e32 v187, 31, v186
	v_lshlrev_b64 v[64:65], 7, v[186:187]
	v_or_b32_e32 v184, 48, v190
	v_lshl_add_u64 v[64:65], v[168:169], 0, v[64:65]
	v_ashrrev_i32_e32 v185, 31, v184
	global_load_dwordx4 v[220:223], v[64:65], off
	global_load_dwordx4 v[224:227], v[64:65], off offset:16
	v_lshlrev_b64 v[64:65], 7, v[184:185]
	v_lshl_add_u64 v[64:65], v[168:169], 0, v[64:65]
	global_load_dwordx4 v[228:231], v[64:65], off
	global_load_dwordx4 v[232:235], v[64:65], off offset:16
	v_lshl_or_b32 v180, s13, 7, v200
	v_and_b32_e32 v65, 64, v204
	v_xor_b32_e32 v64, 16, v204
	v_ashrrev_i32_e32 v181, 31, v180
	v_add_u32_e32 v65, 64, v65
	v_readlane_b32 s44, v243, 3
	v_xor_b32_e32 v66, 32, v204
	v_lshlrev_b64 v[182:183], 2, v[180:181]
	v_cmp_lt_i32_e32 vcc, v64, v65
	v_readlane_b32 s52, v243, 11
	v_readlane_b32 s53, v243, 12
	v_cndmask_b32_e32 v64, v204, v64, vcc
	v_cmp_lt_i32_e32 vcc, v66, v65
	v_lshl_add_u64 v[92:93], s[52:53], 0, v[182:183]
	v_readlane_b32 s54, v243, 13
	v_cndmask_b32_e32 v65, v204, v66, vcc
	v_add_co_u32_e32 v94, vcc, 0x5000, v92
	v_readlane_b32 s55, v243, 14
	s_nop 0
	v_addc_co_u32_e32 v95, vcc, 0, v93, vcc
	v_add_co_u32_e32 v96, vcc, 0xb000, v92
	v_lshl_add_u64 v[72:73], s[54:55], 0, v[182:183]
	v_lshl_add_u64 v[74:75], v[92:93], 0, s[26:27]
	v_lshl_add_u64 v[76:77], v[92:93], 0, s[28:29]
	v_addc_co_u32_e32 v97, vcc, 0, v93, vcc
	v_lshlrev_b32_e32 v187, 2, v64
	v_lshlrev_b32_e32 v185, 2, v65
	global_load_dwordx4 v[64:67], v[92:93], off offset:16
	global_load_dwordx4 v[80:83], v[92:93], off
	global_load_dwordx4 v[68:71], v[72:73], off offset:16
	global_load_dwordx4 v[84:87], v[72:73], off
	s_nop 0
	global_load_dwordx4 v[72:75], v[74:75], off offset:16
	s_nop 0
	global_load_dwordx4 v[76:79], v[76:77], off offset:16
	s_nop 0
	global_load_dwordx4 v[92:95], v[94:95], off offset:2048
	s_nop 0
	global_load_dwordx4 v[96:99], v[96:97], off
	v_mov_b32_e32 v211, 0
	v_mov_b32_e32 v205, 0
	v_readlane_b32 s45, v243, 4
	v_readlane_b32 s46, v243, 5
	v_readlane_b32 s47, v243, 6
	v_readlane_b32 s48, v243, 7
	v_readlane_b32 s49, v243, 8
	v_readlane_b32 s50, v243, 9
	v_readlane_b32 s51, v243, 10
	v_readlane_b32 s56, v243, 15
	v_readlane_b32 s57, v243, 16
	v_readlane_b32 s58, v243, 17
	v_readlane_b32 s59, v243, 18
	s_waitcnt vmcnt(0)
	v_mov_b32_e32 v196, v192
	v_mov_b32_e32 v197, v206
	v_mov_b32_e32 v206, v193
	v_mov_b32_e32 v192, v194
	v_mov_b32_e32 v193, v208
	v_mov_b32_e32 v208, v195
	v_pk_add_f32 v[194:195], v[196:197], v[206:207]
	v_pk_add_f32 v[192:193], v[192:193], v[208:209]
	v_mov_b32_e32 v196, v212
	v_mov_b32_e32 v197, v216
	v_mov_b32_e32 v216, v213
	v_mov_b32_e32 v206, v214
	v_mov_b32_e32 v207, v218
	v_mov_b32_e32 v218, v215
	v_pk_add_f32 v[192:193], v[194:195], v[192:193]
	v_pk_add_f32 v[194:195], v[196:197], v[216:217]
	v_pk_add_f32 v[196:197], v[206:207], v[218:219]
	v_mov_b32_e32 v208, v220
	v_pk_add_f32 v[194:195], v[194:195], v[196:197]
	v_mov_b32_e32 v197, v192
	v_mov_b32_e32 v196, v194
	v_mov_b32_e32 v192, v195
	v_pk_add_f32 v[192:193], v[196:197], v[192:193]
	ds_bpermute_b32 v195, v187, v193
	ds_bpermute_b32 v194, v187, v192
	v_mov_b32_e32 v209, v224
	v_mov_b32_e32 v224, v221
	v_mov_b32_e32 v212, v222
	v_mov_b32_e32 v213, v226
	s_waitcnt lgkmcnt(0)
	v_pk_add_f32 v[192:193], v[192:193], v[194:195]
	ds_bpermute_b32 v195, v185, v193
	ds_bpermute_b32 v194, v185, v192
	v_mov_b32_e32 v226, v223
	v_mov_b32_e32 v196, v228
	v_mov_b32_e32 v197, v232
	v_mov_b32_e32 v232, v229
	s_waitcnt lgkmcnt(0)
; DI unsigned pack2(float lo, float hi) { f32x2 v = {lo, hi}; bf16v2 r = __builtin_convertvector(v, bf16v2); return __builtin_bit_cast(unsigned, r); }
; DI float silu_f(float x) { return x * sigmoid_f(x); }
; DI float dpp_ror1(float v) { return __int_as_float(__builtin_amdgcn_update_dpp(0, __float_as_int(v), 0x121, 0xf, 0xf, false)); }
; DI float dpp_ror2(float v) { return __int_as_float(__builtin_amdgcn_update_dpp(0, __float_as_int(v), 0x122, 0xf, 0xf, false)); }
;   DI void operator()(const f32x4 (&acc)[2][2][4][2], const Unit& u, int wr, int wc, int fr, int fq) const {
;     ...
;       for (int m = 0; m < 4; ++m) {
;         float g[8], uu[8], a[8];
;         const float rs = rsv[m];
; #pragma unroll
;         for (int e = 0; e < 4; ++e) { g[e] = acc[ai][0][m][0][e] * rs; g[4 + e] = acc[ai][0][m][1][e] * rs; uu[e] = acc[ai][1][m][0][e] * rs; uu[4 + e] = acc[ai][1][m][1][e] * rs; }
; #pragma unroll
;         for (int e = 0; e < 8; ++e) {
;           const float x1 = dpp_ror1(g[e]), x2 = dpp_ror2(g[e]);
;           const float pr1 = (fr == 0) ? p1[e] : x1, pr2 = (fr < 2) ? p2[e] : x2;
;           a[e] = w2[e] * g[e] + w1[e] * pr1 + w0[e] * pr2 + bb[e];
;           p1[e] = x1; p2[e] = x2;
;         }
;         if (m == 0 && fr < 2) {
;           float* ha = headA + (size_t)(span * 2 + fr) * 5632 + col; float* hu = headU + (size_t)(span * 2 + fr) * 5632 + col;
;           *(f32x4*)ha = (f32x4){a[0], a[1], a[2], a[3]}; *(f32x4*)(ha + 4) = (f32x4){a[4], a[5], a[6], a[7]};
;           *(f32x4*)hu = (f32x4){uu[0], uu[1], uu[2], uu[3]}; *(f32x4*)(hu + 4) = (f32x4){uu[4], uu[5], uu[6], uu[7]};
;         } else {
;           u32x4 w;
;           w.x = pack2(silu_f(a[0]) * uu[0], silu_f(a[1]) * uu[1]);
;           w.y = pack2(silu_f(a[2]) * uu[2], silu_f(a[3]) * uu[3]);
;           w.z = pack2(silu_f(a[4]) * uu[4], silu_f(a[5]) * uu[5]);
;           w.w = pack2(silu_f(a[6]) * uu[6], silu_f(a[7]) * uu[7]);
;           *(u32x4*)(H + (size_t)(row0 + 16 * m + fr) * 5632 + col) = w;
;         }
	v_pk_add_f32 v[192:193], v[192:193], v[194:195]
	v_mov_b32_e32 v206, v230
	v_pk_fma_f32 v[192:193], v[192:193], s[30:31], v[178:179] op_sel_hi:[1,0,0]
	v_mov_b32_e32 v207, v234
	v_mul_f32_e32 v189, 0x4b800000, v193
	v_cmp_gt_f32_e64 s[12:13], s74, v193
	v_mov_b32_e32 v234, v231
	v_pk_add_f32 v[208:209], v[208:209], v[224:225]
	v_cndmask_b32_e64 v189, v193, v189, s[12:13]
	v_rsq_f32_e32 v189, v189
	v_pk_add_f32 v[212:213], v[212:213], v[226:227]
	v_pk_add_f32 v[196:197], v[196:197], v[232:233]
	v_pk_add_f32 v[194:195], v[206:207], v[234:235]
	v_mul_f32_e32 v191, 0x45800000, v189
	v_cndmask_b32_e64 v220, v189, v191, s[12:13]
	v_pk_add_f32 v[208:209], v[208:209], v[212:213]
	v_pk_add_f32 v[194:195], v[196:197], v[194:195]
	v_pk_mul_f32 v[156:157], v[156:157], v[220:221] op_sel_hi:[1,0]
	v_mov_b32_e32 v216, 0
	v_mov_b32_e32 v218, 0
	v_mov_b32_e32 v196, v194
	v_mov_b32_e32 v197, v208
	v_mov_b32_e32 v208, v195
	v_mov_b32_dpp v216, v156 row_ror:1 row_mask:0xf bank_mask:0xf
	v_mov_b32_dpp v218, v157 row_ror:1 row_mask:0xf bank_mask:0xf
	v_pk_add_f32 v[194:195], v[196:197], v[208:209]
	v_cndmask_b32_e64 v207, v218, 0, s[0:1]
	v_cndmask_b32_e64 v206, v216, 0, s[0:1]
	v_pk_mul_f32 v[158:159], v[158:159], v[220:221] op_sel_hi:[1,0]
	v_mov_b32_e32 v212, 0
	v_mov_b32_e32 v214, 0
	ds_bpermute_b32 v197, v187, v195
	ds_bpermute_b32 v196, v187, v194
	v_mov_b32_e32 v215, 0
	v_mov_b32_e32 v217, 0
	v_pk_mul_f32 v[206:207], v[92:93], v[206:207]
	v_mov_b32_dpp v212, v158 row_ror:1 row_mask:0xf bank_mask:0xf
	v_mov_b32_dpp v214, v159 row_ror:1 row_mask:0xf bank_mask:0xf
	v_mov_b32_dpp v215, v156 row_ror:2 row_mask:0xf bank_mask:0xf
	v_mov_b32_dpp v217, v157 row_ror:2 row_mask:0xf bank_mask:0xf
	v_pk_fma_f32 v[156:157], v[96:97], v[156:157], v[206:207]
	v_mov_b32_e32 v213, 0
	v_cndmask_b32_e64 v207, v214, 0, s[0:1]
	v_cndmask_b32_e64 v206, v212, 0, s[0:1]
	v_cndmask_b32_e64 v209, v217, 0, s[4:5]
	v_cndmask_b32_e64 v208, v215, 0, s[4:5]
	v_mov_b32_dpp v211, v158 row_ror:2 row_mask:0xf bank_mask:0xf
	v_mov_b32_dpp v213, v159 row_ror:2 row_mask:0xf bank_mask:0xf
	v_pk_mul_f32 v[206:207], v[94:95], v[206:207]
	v_pk_fma_f32 v[156:157], v[80:81], v[208:209], v[156:157]
	v_cndmask_b32_e64 v209, v213, 0, s[4:5]
	v_cndmask_b32_e64 v208, v211, 0, s[4:5]
	v_pk_fma_f32 v[158:159], v[98:99], v[158:159], v[206:207]
	v_pk_mul_f32 v[144:145], v[144:145], v[220:221] op_sel_hi:[1,0]
	v_pk_fma_f32 v[158:159], v[82:83], v[208:209], v[158:159]
	v_mov_b32_e32 v207, 0
	v_mov_b32_e32 v209, 0
	v_pk_mul_f32 v[146:147], v[146:147], v[220:221] op_sel_hi:[1,0]
	v_mov_b32_e32 v191, 0
	s_waitcnt lgkmcnt(0)
	v_pk_add_f32 v[194:195], v[194:195], v[196:197]
	v_mov_b32_dpp v207, v144 row_ror:1 row_mask:0xf bank_mask:0xf
	v_mov_b32_dpp v209, v145 row_ror:1 row_mask:0xf bank_mask:0xf
	v_mov_b32_dpp v191, v146 row_ror:1 row_mask:0xf bank_mask:0xf
	v_mov_b32_dpp v205, v147 row_ror:1 row_mask:0xf bank_mask:0xf
	ds_bpermute_b32 v197, v185, v195
	ds_bpermute_b32 v196, v185, v194
	v_pk_mul_f32 v[152:153], v[152:153], v[220:221] op_sel_hi:[1,0]
	v_pk_mul_f32 v[148:149], v[148:149], v[220:221] op_sel_hi:[1,0]
	v_pk_mul_f32 v[154:155], v[154:155], v[220:221] op_sel_hi:[1,0]
	v_pk_mul_f32 v[150:151], v[150:151], v[220:221] op_sel_hi:[1,0]
	v_mov_b32_e32 v206, 0
	v_mov_b32_e32 v208, 0
	v_cndmask_b32_e64 v223, v209, 0, s[0:1]
	v_cndmask_b32_e64 v222, v207, 0, s[0:1]
	v_mov_b32_e32 v189, 0
	v_mov_b32_e32 v193, 0
	v_cndmask_b32_e64 v221, v205, 0, s[0:1]
	v_cndmask_b32_e64 v220, v191, 0, s[0:1]
	v_mov_b32_dpp v206, v144 row_ror:2 row_mask:0xf bank_mask:0xf
	v_mov_b32_dpp v208, v145 row_ror:2 row_mask:0xf bank_mask:0xf
	v_pk_mul_f32 v[222:223], v[72:73], v[222:223]
	v_mov_b32_dpp v189, v146 row_ror:2 row_mask:0xf bank_mask:0xf
	v_mov_b32_dpp v193, v147 row_ror:2 row_mask:0xf bank_mask:0xf
	v_pk_mul_f32 v[220:221], v[74:75], v[220:221]
	v_cndmask_b32_e64 v225, v208, 0, s[4:5]
	v_cndmask_b32_e64 v224, v206, 0, s[4:5]
	v_pk_fma_f32 v[144:145], v[76:77], v[144:145], v[222:223]
	v_cndmask_b32_e64 v223, v193, 0, s[4:5]
	v_cndmask_b32_e64 v222, v189, 0, s[4:5]
	v_pk_fma_f32 v[146:147], v[78:79], v[146:147], v[220:221]
	v_pk_fma_f32 v[144:145], v[64:65], v[224:225], v[144:145]
	v_pk_fma_f32 v[146:147], v[66:67], v[222:223], v[146:147]
	v_cmp_gt_f32_e32 vcc, s74, v192
	v_pk_add_f32 v[156:157], v[84:85], v[156:157]
	v_pk_add_f32 v[158:159], v[86:87], v[158:159]
	v_pk_add_f32 v[144:145], v[68:69], v[144:145]
	v_pk_add_f32 v[146:147], v[70:71], v[146:147]
	s_and_saveexec_b64 s[12:13], s[10:11]
	s_xor_b64 s[12:13], exec, s[12:13]
	s_cbranch_execz .LBB0_814
	v_mul_f32_e32 v219, 0xbfb8aa3b, v156
	v_exp_f32_e32 v219, v219
	v_mul_f32_e32 v220, 0xbfb8aa3b, v157
	v_exp_f32_e32 v220, v220
	v_mul_f32_e32 v222, 0xbfb8aa3b, v159
	v_add_f32_e32 v219, 1.0, v219
	v_exp_f32_e32 v223, v222
	v_add_f32_e32 v221, 1.0, v220
	v_rcp_f32_e32 v220, v219
	v_mul_f32_e32 v219, 0xbfb8aa3b, v158
	v_exp_f32_e32 v219, v219
	v_rcp_f32_e32 v221, v221
	v_add_f32_e32 v219, 1.0, v219
	v_rcp_f32_e32 v222, v219
	v_add_f32_e32 v219, 1.0, v223
	v_rcp_f32_e32 v223, v219
	v_pk_mul_f32 v[156:157], v[156:157], v[220:221]
	s_nop 0
	v_pk_mul_f32 v[152:153], v[152:153], v[156:157]
	v_pk_mul_f32 v[156:157], v[158:159], v[222:223]
	v_cvt_pk_bf16_f32 v152, v152, v153
	v_mul_f32_e32 v153, 0xbfb8aa3b, v144
	v_pk_mul_f32 v[154:155], v[154:155], v[156:157]
	v_exp_f32_e32 v156, v153
	v_mul_f32_e32 v153, 0xbfb8aa3b, v145
	v_exp_f32_e32 v157, v153
	v_cvt_pk_bf16_f32 v153, v154, v155
	v_add_f32_e32 v154, 1.0, v156
	v_mul_f32_e32 v156, 0xbfb8aa3b, v146
	v_add_f32_e32 v155, 1.0, v157
	v_mul_f32_e32 v157, 0xbfb8aa3b, v147
	v_exp_f32_e32 v156, v156
	v_exp_f32_e32 v157, v157
	v_rcp_f32_e32 v154, v154
	v_rcp_f32_e32 v155, v155
	v_add_f32_e32 v156, 1.0, v156
	v_add_f32_e32 v157, 1.0, v157
	v_rcp_f32_e32 v156, v156
	v_rcp_f32_e32 v157, v157
	v_pk_mul_f32 v[144:145], v[144:145], v[154:155]
	s_nop 0
	v_pk_mul_f32 v[144:145], v[148:149], v[144:145]
	s_nop 0
	v_cvt_pk_bf16_f32 v154, v144, v145
	v_pk_mul_f32 v[144:145], v[146:147], v[156:157]
	s_nop 0
	v_pk_mul_f32 v[144:145], v[150:151], v[144:145]
	s_nop 0
	v_cvt_pk_bf16_f32 v155, v144, v145
	v_mov_b64_e32 v[144:145], s[16:17]
	v_mad_i64_i32 v[144:145], s[14:15], v190, s75, v[144:145]
	v_lshl_add_u64 v[144:145], v[180:181], 1, v[144:145]
	global_store_dwordx4 v[144:145], v[152:155], off

; #define PG8_STAGE(bufoff, gbase, voff) do { _Pragma("unroll") for (int _i = 0; _i < 2; ++_i) \
;     __builtin_amdgcn_global_load_lds((const unsigned*)((const char*)(gbase) + (voff)[_i]), (LAS unsigned*)(lds + (bufoff) + ldsw + _i * 8192), 16, 0, 0); } while (0)
; #define PG8_LDA(dst, b, h) do { _Pragma("unroll") for (int m = 0; m < 4; ++m) _Pragma("unroll") for (int k = 0; k < 2; ++k) dst[m][k] = *(const LAS bf16x8*)(lds + PG8_SA(b, h) + aoff + m * 2048 + k * 1024); } while (0)
; #define PG8_LDB(dst, b, h) do { _Pragma("unroll") for (int n = 0; n < 2; ++n) _Pragma("unroll") for (int k = 0; k < 2; ++k) dst[n][k] = *(const LAS bf16x8*)(lds + PG8_SB(b, h) + boff + n * 2048 + k * 1024); } while (0)
; #define PG8_MMA(ai, bj, At, Bt) do { __builtin_amdgcn_s_setprio(1); _Pragma("unroll") for (int m = 0; m < 4; ++m) _Pragma("unroll") for (int n = 0; n < 2; ++n) _Pragma("unroll") for (int k = 0; k < 2; ++k) \
;     acc[ai][bj][m][n] = __builtin_amdgcn_mfma_f32_16x16x32_bf16(Bt[n][k], At[m][k], acc[ai][bj][m][n], 0, 0, 0); __builtin_amdgcn_s_setprio(0); } while (0)
; #define PG8_WAIT_V(n) asm volatile("s_waitcnt vmcnt(" #n ")" ::: "memory")
; #define PG8_WAIT_L(n) asm volatile("s_waitcnt lgkmcnt(" #n ")" ::: "memory")
; #define PG8_BAR __builtin_amdgcn_s_barrier()
; #define PG8_SCHED __builtin_amdgcn_sched_barrier(0)
; template <class Epi, class Sched = StaticOrder>
; DI void gemm_phase(LAS unsigned char* lds, const Gemm g, const Sched& S, const Epi& E) {
;     ...
;       PG8_LDB(B0, 0, 0); PG8_SCHED; PG8_LDA(At, 0, 0); PG8_STAGE(PG8_SA(1, 1), a1 + hstep, voffA);
;       PG8_WAIT_L(8); PG8_BAR; PG8_WAIT_L(0); PG8_MMA(0, 0, At, B0); PG8_BAR; PG8_SCHED;
;       PG8_LDB(B1, 0, 1); PG8_STAGE(PG8_SB(0, 0), b2, voffB);
;       PG8_BAR; PG8_WAIT_L(0); PG8_MMA(0, 1, At, B1); PG8_BAR;
;       PG8_LDA(At, 0, 1); PG8_STAGE(PG8_SA(0, 0), a2, voffA);
;       PG8_BAR; PG8_WAIT_L(0); PG8_MMA(1, 0, At, B0); PG8_BAR; PG8_SCHED;
;       PG8_STAGE(PG8_SB(0, 1), b2 + hstep, voffB);
;       PG8_WAIT_V(6); PG8_BAR; PG8_MMA(1, 1, At, B1); PG8_BAR;
.LBB0_961:
	ds_read_b128 v[128:131], v214
	ds_read_b128 v[132:135], v214 offset:1024
	ds_read_b128 v[136:139], v214 offset:2048
	ds_read_b128 v[140:143], v214 offset:3072
	s_add_u32 s20, s18, 0xffea0080
	s_addc_u32 s21, s19, -1
	s_cmpk_eq_i32 s44, 0x54
	s_cselect_b32 s23, s5, s21
	s_cselect_b32 s22, s4, s20
	s_cselect_b32 s21, s7, s43
	s_cselect_b32 s20, s6, s42
	s_add_i32 m0, s31, 0xc000
	ds_read_b128 v[144:147], v215
	ds_read_b128 v[148:151], v215 offset:1024
	ds_read_b128 v[152:155], v215 offset:2048
	ds_read_b128 v[156:159], v215 offset:3072
	ds_read_b128 v[160:163], v215 offset:4096
	ds_read_b128 v[164:167], v215 offset:5120
	ds_read_b128 v[168:171], v215 offset:6144
	ds_read_b128 v[172:175], v215 offset:7168
	global_load_lds_dwordx4 v184, s[18:19]
	s_add_i32 m0, s31, 0xe000
	s_nop 0
	global_load_lds_dwordx4 v186, s[18:19]
	ds_read_b128 v[192:195], v216
	ds_read_b128 v[196:199], v216 offset:1024
	ds_read_b128 v[200:203], v216 offset:2048
	ds_read_b128 v[204:207], v216 offset:3072
	s_waitcnt vmcnt(8)
	s_waitcnt lgkmcnt(4)
	s_setprio 1
	s_barrier
	v_mfma_f32_16x16x32_bf16 v[124:127], v[128:131], v[144:147], v[124:127]
	v_mfma_f32_16x16x32_bf16 v[120:123], v[136:139], v[144:147], v[120:123]
	v_mfma_f32_16x16x32_bf16 v[108:111], v[128:131], v[152:155], v[108:111]
	v_mfma_f32_16x16x32_bf16 v[104:107], v[136:139], v[152:155], v[104:107]
	v_mfma_f32_16x16x32_bf16 v[92:95], v[128:131], v[160:163], v[92:95]
	v_mfma_f32_16x16x32_bf16 v[88:91], v[136:139], v[160:163], v[88:91]
	v_mfma_f32_16x16x32_bf16 v[76:79], v[128:131], v[168:171], v[76:79]
	v_mfma_f32_16x16x32_bf16 v[72:75], v[136:139], v[168:171], v[72:75]
	v_mfma_f32_16x16x32_bf16 v[124:127], v[132:135], v[148:151], v[124:127]
	v_mfma_f32_16x16x32_bf16 v[120:123], v[140:143], v[148:151], v[120:123]
	v_mfma_f32_16x16x32_bf16 v[108:111], v[132:135], v[156:159], v[108:111]
	v_mfma_f32_16x16x32_bf16 v[104:107], v[140:143], v[156:159], v[104:107]
	v_mfma_f32_16x16x32_bf16 v[92:95], v[132:135], v[164:167], v[92:95]
	v_mfma_f32_16x16x32_bf16 v[88:91], v[140:143], v[164:167], v[88:91]
	v_mfma_f32_16x16x32_bf16 v[76:79], v[132:135], v[172:175], v[76:79]
	v_mfma_f32_16x16x32_bf16 v[72:75], v[140:143], v[172:175], v[72:75]
	s_waitcnt lgkmcnt(0)
	v_mfma_f32_16x16x32_bf16 v[116:119], v[192:195], v[144:147], v[116:119]
	v_mfma_f32_16x16x32_bf16 v[112:115], v[200:203], v[144:147], v[112:115]
	v_mfma_f32_16x16x32_bf16 v[100:103], v[192:195], v[152:155], v[100:103]
	v_mfma_f32_16x16x32_bf16 v[96:99], v[200:203], v[152:155], v[96:99]
	v_mfma_f32_16x16x32_bf16 v[84:87], v[192:195], v[160:163], v[84:87]
	v_mfma_f32_16x16x32_bf16 v[80:83], v[200:203], v[160:163], v[80:83]
	v_mfma_f32_16x16x32_bf16 v[68:71], v[192:195], v[168:171], v[68:71]
	v_mfma_f32_16x16x32_bf16 v[64:67], v[200:203], v[168:171], v[64:67]
	v_mfma_f32_16x16x32_bf16 v[116:119], v[196:199], v[148:151], v[116:119]
	v_mfma_f32_16x16x32_bf16 v[112:115], v[204:207], v[148:151], v[112:115]
	v_mfma_f32_16x16x32_bf16 v[100:103], v[196:199], v[156:159], v[100:103]
	v_mfma_f32_16x16x32_bf16 v[96:99], v[204:207], v[156:159], v[96:99]
	v_mfma_f32_16x16x32_bf16 v[84:87], v[196:199], v[164:167], v[84:87]
	v_mfma_f32_16x16x32_bf16 v[80:83], v[204:207], v[164:167], v[80:83]
	v_mfma_f32_16x16x32_bf16 v[68:71], v[196:199], v[172:175], v[68:71]
	v_mfma_f32_16x16x32_bf16 v[64:67], v[204:207], v[172:175], v[64:67]
	s_barrier
	s_setprio 0
	s_add_i32 s45, s46, s30
	s_add_u32 s98, s20, 0x80
	s_addc_u32 s99, s21, 0
	s_add_u32 s100, s22, 0x80
	s_addc_u32 s101, s23, 0
	s_mov_b32 m0, s45
	s_nop 0
	global_load_lds_dwordx4 v178, s[20:21]
	s_add_i32 m0, s45, 0x2000
	s_nop 0
	global_load_lds_dwordx4 v182, s[20:21]
	s_mov_b32 m0, s31
	s_nop 0
	global_load_lds_dwordx4 v176, s[22:23]
	s_mov_b32 m0, s33
	s_nop 0
	global_load_lds_dwordx4 v180, s[22:23]
	ds_read_b128 v[144:147], v215 offset:16384
	ds_read_b128 v[148:151], v215 offset:17408
	ds_read_b128 v[152:155], v215 offset:18432
	ds_read_b128 v[156:159], v215 offset:19456
	ds_read_b128 v[160:163], v215 offset:20480
	ds_read_b128 v[164:167], v215 offset:21504
	ds_read_b128 v[168:171], v215 offset:22528
	ds_read_b128 v[172:175], v215 offset:23552
	s_add_u32 s52, s20, 0x160000
	s_addc_u32 s53, s21, 0
	s_add_i32 s45, s47, s30
	s_waitcnt vmcnt(6)
	s_waitcnt lgkmcnt(0)
	s_setprio 1
	s_barrier
	v_mfma_f32_16x16x32_bf16 v[60:63], v[128:131], v[144:147], v[60:63]
	s_mov_b32 m0, s45
	v_mfma_f32_16x16x32_bf16 v[56:59], v[136:139], v[144:147], v[56:59]
	global_load_lds_dwordx4 v178, s[52:53]
	v_mfma_f32_16x16x32_bf16 v[44:47], v[128:131], v[152:155], v[44:47]
	s_bitset1_b32 m0, 13
	v_mfma_f32_16x16x32_bf16 v[40:43], v[136:139], v[152:155], v[40:43]
	global_load_lds_dwordx4 v182, s[52:53]
	v_mfma_f32_16x16x32_bf16 v[28:31], v[128:131], v[160:163], v[28:31]
	v_mfma_f32_16x16x32_bf16 v[24:27], v[136:139], v[160:163], v[24:27]
	v_mfma_f32_16x16x32_bf16 v[12:15], v[128:131], v[168:171], v[12:15]
	v_mfma_f32_16x16x32_bf16 v[8:11], v[136:139], v[168:171], v[8:11]
	v_mfma_f32_16x16x32_bf16 v[60:63], v[132:135], v[148:151], v[60:63]
	v_mfma_f32_16x16x32_bf16 v[56:59], v[140:143], v[148:151], v[56:59]
	v_mfma_f32_16x16x32_bf16 v[44:47], v[132:135], v[156:159], v[44:47]
	v_mfma_f32_16x16x32_bf16 v[40:43], v[140:143], v[156:159], v[40:43]
	v_mfma_f32_16x16x32_bf16 v[28:31], v[132:135], v[164:167], v[28:31]
	v_mfma_f32_16x16x32_bf16 v[24:27], v[140:143], v[164:167], v[24:27]
	v_mfma_f32_16x16x32_bf16 v[12:15], v[132:135], v[172:175], v[12:15]
	v_mfma_f32_16x16x32_bf16 v[8:11], v[140:143], v[172:175], v[8:11]
	v_mfma_f32_16x16x32_bf16 v[52:55], v[192:195], v[144:147], v[52:55]
	v_mfma_f32_16x16x32_bf16 v[48:51], v[200:203], v[144:147], v[48:51]
	v_mfma_f32_16x16x32_bf16 v[36:39], v[192:195], v[152:155], v[36:39]
	v_mfma_f32_16x16x32_bf16 v[32:35], v[200:203], v[152:155], v[32:35]
	v_mfma_f32_16x16x32_bf16 v[20:23], v[192:195], v[160:163], v[20:23]
	v_mfma_f32_16x16x32_bf16 v[16:19], v[200:203], v[160:163], v[16:19]
	v_mfma_f32_16x16x32_bf16 v[4:7], v[192:195], v[168:171], v[4:7]
	v_mfma_f32_16x16x32_bf16 v[0:3], v[200:203], v[168:171], v[0:3]
	v_mfma_f32_16x16x32_bf16 v[52:55], v[196:199], v[148:151], v[52:55]
	v_mfma_f32_16x16x32_bf16 v[48:51], v[204:207], v[148:151], v[48:51]
	v_mfma_f32_16x16x32_bf16 v[36:39], v[196:199], v[156:159], v[36:39]
	v_mfma_f32_16x16x32_bf16 v[32:35], v[204:207], v[156:159], v[32:35]
	v_mfma_f32_16x16x32_bf16 v[20:23], v[196:199], v[164:167], v[20:23]
	v_mfma_f32_16x16x32_bf16 v[16:19], v[204:207], v[164:167], v[16:19]
	v_mfma_f32_16x16x32_bf16 v[4:7], v[196:199], v[172:175], v[4:7]
	v_mfma_f32_16x16x32_bf16 v[0:3], v[204:207], v[172:175], v[0:3]
	s_barrier
; #define PG8_STAGE(bufoff, gbase, voff) do { _Pragma("unroll") for (int _i = 0; _i < 2; ++_i) \
;     __builtin_amdgcn_global_load_lds((const unsigned*)((const char*)(gbase) + (voff)[_i]), (LAS unsigned*)(lds + (bufoff) + ldsw + _i * 8192), 16, 0, 0); } while (0)
; #define PG8_LDA(dst, b, h) do { _Pragma("unroll") for (int m = 0; m < 4; ++m) _Pragma("unroll") for (int k = 0; k < 2; ++k) dst[m][k] = *(const LAS bf16x8*)(lds + PG8_SA(b, h) + aoff + m * 2048 + k * 1024); } while (0)
; #define PG8_LDB(dst, b, h) do { _Pragma("unroll") for (int n = 0; n < 2; ++n) _Pragma("unroll") for (int k = 0; k < 2; ++k) dst[n][k] = *(const LAS bf16x8*)(lds + PG8_SB(b, h) + boff + n * 2048 + k * 1024); } while (0)
; #define PG8_MMA(ai, bj, At, Bt) do { __builtin_amdgcn_s_setprio(1); _Pragma("unroll") for (int m = 0; m < 4; ++m) _Pragma("unroll") for (int n = 0; n < 2; ++n) _Pragma("unroll") for (int k = 0; k < 2; ++k) \
;     acc[ai][bj][m][n] = __builtin_amdgcn_mfma_f32_16x16x32_bf16(Bt[n][k], At[m][k], acc[ai][bj][m][n], 0, 0, 0); __builtin_amdgcn_s_setprio(0); } while (0)
; #define PG8_WAIT_V(n) asm volatile("s_waitcnt vmcnt(" #n ")" ::: "memory")
; #define PG8_WAIT_L(n) asm volatile("s_waitcnt lgkmcnt(" #n ")" ::: "memory")
; #define PG8_BAR __builtin_amdgcn_s_barrier()
; #define PG8_SCHED __builtin_amdgcn_sched_barrier(0)
; template <class Epi, class Sched = StaticOrder>
; DI void gemm_phase(LAS unsigned char* lds, const Gemm g, const Sched& S, const Epi& E) {
;     ...
;       PG8_LDB(B0, 1, 0); PG8_SCHED; PG8_LDA(At, 1, 0); PG8_STAGE(PG8_SA(0, 1), a2 + hstep, voffA);
;       PG8_WAIT_L(8); PG8_BAR; PG8_WAIT_L(0); PG8_MMA(0, 0, At, B0); PG8_BAR; PG8_SCHED;
;       PG8_LDB(B1, 1, 1); PG8_STAGE(PG8_SB(1, 0), b3, voffB);
;       PG8_BAR; PG8_WAIT_L(0); PG8_MMA(0, 1, At, B1); PG8_BAR;
;       PG8_LDA(At, 1, 1); PG8_STAGE(PG8_SA(1, 0), a3, voffA);
;       PG8_BAR; PG8_WAIT_L(0); PG8_MMA(1, 0, At, B0); PG8_BAR; PG8_SCHED;
;       PG8_STAGE(PG8_SB(1, 1), b3 + hstep, voffB);
;       PG8_WAIT_V(6); PG8_BAR; PG8_MMA(1, 1, At, B1); PG8_BAR;
	s_setprio 0
	s_add_i32 s45, 0, 0x18000
	v_add_u32_e32 v140, s45, v212
	ds_read_b128 v[128:131], v140
	ds_read_b128 v[132:135], v140 offset:1024
	ds_read_b128 v[136:139], v140 offset:2048
	ds_read_b128 v[140:143], v140 offset:3072
	s_add_u32 s22, s22, 0x160000
	s_addc_u32 s23, s23, 0
	s_mov_b32 m0, s34
	ds_read_b128 v[144:147], v215 offset:32768
	ds_read_b128 v[148:151], v215 offset:33792
	ds_read_b128 v[152:155], v215 offset:34816
	ds_read_b128 v[156:159], v215 offset:35840
	ds_read_b128 v[160:163], v215 offset:36864
	ds_read_b128 v[164:167], v215 offset:37888
	ds_read_b128 v[168:171], v215 offset:38912
	ds_read_b128 v[172:175], v215 offset:39936
	global_load_lds_dwordx4 v176, s[22:23]
	s_mov_b32 m0, s35
	s_nop 0
	global_load_lds_dwordx4 v180, s[22:23]
	s_add_i32 s22, 0, 0x1c000
	v_add_u32_e32 v204, s22, v212
	ds_read_b128 v[192:195], v204
	ds_read_b128 v[196:199], v204 offset:1024
	ds_read_b128 v[200:203], v204 offset:2048
	ds_read_b128 v[204:207], v204 offset:3072
	s_waitcnt vmcnt(8)
	s_waitcnt lgkmcnt(4)
	s_setprio 1
	s_barrier
	v_mfma_f32_16x16x32_bf16 v[124:127], v[128:131], v[144:147], v[124:127]
	v_mfma_f32_16x16x32_bf16 v[120:123], v[136:139], v[144:147], v[120:123]
	v_mfma_f32_16x16x32_bf16 v[108:111], v[128:131], v[152:155], v[108:111]
	v_mfma_f32_16x16x32_bf16 v[104:107], v[136:139], v[152:155], v[104:107]
	v_mfma_f32_16x16x32_bf16 v[92:95], v[128:131], v[160:163], v[92:95]
	v_mfma_f32_16x16x32_bf16 v[88:91], v[136:139], v[160:163], v[88:91]
	v_mfma_f32_16x16x32_bf16 v[76:79], v[128:131], v[168:171], v[76:79]
	v_mfma_f32_16x16x32_bf16 v[72:75], v[136:139], v[168:171], v[72:75]
	v_mfma_f32_16x16x32_bf16 v[124:127], v[132:135], v[148:151], v[124:127]
	v_mfma_f32_16x16x32_bf16 v[120:123], v[140:143], v[148:151], v[120:123]
	v_mfma_f32_16x16x32_bf16 v[108:111], v[132:135], v[156:159], v[108:111]
	v_mfma_f32_16x16x32_bf16 v[104:107], v[140:143], v[156:159], v[104:107]
	v_mfma_f32_16x16x32_bf16 v[92:95], v[132:135], v[164:167], v[92:95]
	v_mfma_f32_16x16x32_bf16 v[88:91], v[140:143], v[164:167], v[88:91]
	v_mfma_f32_16x16x32_bf16 v[76:79], v[132:135], v[172:175], v[76:79]
	v_mfma_f32_16x16x32_bf16 v[72:75], v[140:143], v[172:175], v[72:75]
	s_waitcnt lgkmcnt(0)
	v_mfma_f32_16x16x32_bf16 v[116:119], v[192:195], v[144:147], v[116:119]
	v_mfma_f32_16x16x32_bf16 v[112:115], v[200:203], v[144:147], v[112:115]
	v_mfma_f32_16x16x32_bf16 v[100:103], v[192:195], v[152:155], v[100:103]
	v_mfma_f32_16x16x32_bf16 v[96:99], v[200:203], v[152:155], v[96:99]
	v_mfma_f32_16x16x32_bf16 v[84:87], v[192:195], v[160:163], v[84:87]
	v_mfma_f32_16x16x32_bf16 v[80:83], v[200:203], v[160:163], v[80:83]
	v_mfma_f32_16x16x32_bf16 v[68:71], v[192:195], v[168:171], v[68:71]
	v_mfma_f32_16x16x32_bf16 v[64:67], v[200:203], v[168:171], v[64:67]
	v_mfma_f32_16x16x32_bf16 v[116:119], v[196:199], v[148:151], v[116:119]
	v_mfma_f32_16x16x32_bf16 v[112:115], v[204:207], v[148:151], v[112:115]
	v_mfma_f32_16x16x32_bf16 v[100:103], v[196:199], v[156:159], v[100:103]
	v_mfma_f32_16x16x32_bf16 v[96:99], v[204:207], v[156:159], v[96:99]
	v_mfma_f32_16x16x32_bf16 v[84:87], v[196:199], v[164:167], v[84:87]
	v_mfma_f32_16x16x32_bf16 v[80:83], v[204:207], v[164:167], v[80:83]
	v_mfma_f32_16x16x32_bf16 v[68:71], v[196:199], v[172:175], v[68:71]
	v_mfma_f32_16x16x32_bf16 v[64:67], v[204:207], v[172:175], v[64:67]
	s_barrier
	s_setprio 0
	s_add_i32 s23, s45, s30
	s_mov_b32 m0, s23
	s_nop 0
	global_load_lds_dwordx4 v178, s[98:99]
	s_add_i32 m0, s23, 0x2000
	s_nop 0
	global_load_lds_dwordx4 v182, s[98:99]
	s_mov_b32 m0, s37
	s_nop 0
	global_load_lds_dwordx4 v176, s[100:101]
	s_mov_b32 m0, s38
	s_nop 0
	global_load_lds_dwordx4 v180, s[100:101]
	ds_read_b128 v[144:147], v215 offset:49152
	ds_read_b128 v[148:151], v215 offset:50176
	ds_read_b128 v[152:155], v215 offset:51200
	ds_read_b128 v[156:159], v215 offset:52224
	ds_read_b128 v[160:163], v215 offset:53248
	ds_read_b128 v[164:167], v215 offset:54272
	ds_read_b128 v[168:171], v215 offset:55296
	ds_read_b128 v[172:175], v215 offset:56320
	s_add_u32 s20, s20, 0x160080
	s_addc_u32 s21, s21, 0
	s_add_i32 s22, s22, s30
	s_add_i32 s44, s44, 2
	s_add_u32 s18, s18, 0x100
	s_addc_u32 s19, s19, 0
	s_add_u32 s42, s42, 0x100
	s_addc_u32 s43, s43, 0
	s_cmpk_gt_u32 s44, 0x55
	s_waitcnt vmcnt(6)
	s_waitcnt lgkmcnt(0)
	s_setprio 1
	s_barrier
	v_mfma_f32_16x16x32_bf16 v[60:63], v[128:131], v[144:147], v[60:63]
	s_mov_b32 m0, s22
	v_mfma_f32_16x16x32_bf16 v[56:59], v[136:139], v[144:147], v[56:59]
	global_load_lds_dwordx4 v178, s[20:21]
	v_mfma_f32_16x16x32_bf16 v[44:47], v[128:131], v[152:155], v[44:47]
	s_bitset1_b32 m0, 13
	v_mfma_f32_16x16x32_bf16 v[40:43], v[136:139], v[152:155], v[40:43]
	global_load_lds_dwordx4 v182, s[20:21]
	v_mfma_f32_16x16x32_bf16 v[28:31], v[128:131], v[160:163], v[28:31]
	v_mfma_f32_16x16x32_bf16 v[24:27], v[136:139], v[160:163], v[24:27]
	v_mfma_f32_16x16x32_bf16 v[12:15], v[128:131], v[168:171], v[12:15]
	v_mfma_f32_16x16x32_bf16 v[8:11], v[136:139], v[168:171], v[8:11]
	v_mfma_f32_16x16x32_bf16 v[60:63], v[132:135], v[148:151], v[60:63]
	v_mfma_f32_16x16x32_bf16 v[56:59], v[140:143], v[148:151], v[56:59]
	v_mfma_f32_16x16x32_bf16 v[44:47], v[132:135], v[156:159], v[44:47]
	v_mfma_f32_16x16x32_bf16 v[40:43], v[140:143], v[156:159], v[40:43]
	v_mfma_f32_16x16x32_bf16 v[28:31], v[132:135], v[164:167], v[28:31]
	v_mfma_f32_16x16x32_bf16 v[24:27], v[140:143], v[164:167], v[24:27]
	v_mfma_f32_16x16x32_bf16 v[12:15], v[132:135], v[172:175], v[12:15]
	v_mfma_f32_16x16x32_bf16 v[8:11], v[140:143], v[172:175], v[8:11]
	v_mfma_f32_16x16x32_bf16 v[52:55], v[192:195], v[144:147], v[52:55]
	v_mfma_f32_16x16x32_bf16 v[48:51], v[200:203], v[144:147], v[48:51]
	v_mfma_f32_16x16x32_bf16 v[36:39], v[192:195], v[152:155], v[36:39]
	v_mfma_f32_16x16x32_bf16 v[32:35], v[200:203], v[152:155], v[32:35]
	v_mfma_f32_16x16x32_bf16 v[20:23], v[192:195], v[160:163], v[20:23]
	v_mfma_f32_16x16x32_bf16 v[16:19], v[200:203], v[160:163], v[16:19]
	v_mfma_f32_16x16x32_bf16 v[4:7], v[192:195], v[168:171], v[4:7]
	v_mfma_f32_16x16x32_bf16 v[0:3], v[200:203], v[168:171], v[0:3]
	v_mfma_f32_16x16x32_bf16 v[52:55], v[196:199], v[148:151], v[52:55]
	v_mfma_f32_16x16x32_bf16 v[48:51], v[204:207], v[148:151], v[48:51]
	v_mfma_f32_16x16x32_bf16 v[36:39], v[196:199], v[156:159], v[36:39]
	v_mfma_f32_16x16x32_bf16 v[32:35], v[204:207], v[156:159], v[32:35]
	v_mfma_f32_16x16x32_bf16 v[20:23], v[196:199], v[164:167], v[20:23]
	v_mfma_f32_16x16x32_bf16 v[16:19], v[204:207], v[164:167], v[16:19]
	v_mfma_f32_16x16x32_bf16 v[4:7], v[196:199], v[172:175], v[4:7]
	v_mfma_f32_16x16x32_bf16 v[0:3], v[204:207], v[172:175], v[0:3]
	s_barrier
; DI unsigned pack2(float lo, float hi) { f32x2 v = {lo, hi}; bf16v2 r = __builtin_convertvector(v, bf16v2); return __builtin_bit_cast(unsigned, r); }
;   DI void operator()(const f32x4 (&acc)[2][2][4][2], const Unit& u, int wr, int wc, int fr, int fq) const {
;     const int row0 = u.pm * BM + wr * 64 + fr, col0 = u.pn * BM + wc * 32 + 8 * fq;
; #pragma unroll
;     for (int ai = 0; ai < 2; ++ai) {
;       f32x4 bv[4][2][2];
; #pragma unroll
;       for (int m = 0; m < 4; ++m)
; #pragma unroll
;         for (int bj = 0; bj < 2; ++bj) {
;           const float* bp = base + (size_t)(row0 + ai * HALF + m * 16) * 2048 + col0 + bj * HALF;
;           bv[m][bj][0] = *(const f32x4*)bp; bv[m][bj][1] = *(const f32x4*)(bp + 4);
;         }
; #pragma unroll
;       for (int m = 0; m < 4; ++m) {
;         const int row = row0 + ai * HALF + m * 16;
;         const size_t off = (size_t)row * 2048 + col0;
;         float ss = 0.f;
; #pragma unroll
;         for (int bj = 0; bj < 2; ++bj) {
;           const f32x4 v0 = acc[ai][bj][m][0] + bv[m][bj][0], v1 = acc[ai][bj][m][1] + bv[m][bj][1];
;           *(f32x4*)(C + off + bj * HALF) = v0; *(f32x4*)(C + off + bj * HALF + 4) = v1;
;           if (xb) {
;             u32x4 w; w.x = pack2(v0[0], v0[1]); w.y = pack2(v0[2], v0[3]); w.z = pack2(v1[0], v1[1]); w.w = pack2(v1[2], v1[3]);
;             *(u32x4*)(xb + off + bj * HALF) = w;
;             ss += v0[0] * v0[0] + v0[1] * v0[1] + v0[2] * v0[2] + v0[3] * v0[3] + v1[0] * v1[0] + v1[1] * v1[1] + v1[2] * v1[2] + v1[3] * v1[3];
;           }
;         }
;         if (xb) {
;           ss += __shfl_xor(ss, 16); ss += __shfl_xor(ss, 32);
;           if (fq == 0) ssq[(size_t)row * 32 + u.pn * 4 + wc] = ss;
;         }
	s_setprio 0
	s_cbranch_scc0 .LBB0_961
	v_lshl_add_u32 v194, s51, 8, v211
	v_lshl_or_b32 v192, s2, 8, v213
	v_readlane_b32 s52, v243, 3
	v_ashrrev_i32_e32 v193, 31, v192
	v_readlane_b32 s66, v243, 17
	v_readlane_b32 s67, v243, 18
	v_ashrrev_i32_e32 v195, 31, v194
	v_lshlrev_b64 v[128:129], 13, v[194:195]
	v_lshl_add_u64 v[196:197], v[192:193], 2, s[66:67]
	v_lshl_add_u64 v[236:237], v[196:197], 0, v[128:129]
	global_load_dwordx4 v[220:223], v[236:237], off
	global_load_dwordx4 v[224:227], v[236:237], off offset:16
	global_load_dwordx4 v[228:231], v[236:237], off offset:512
	global_load_dwordx4 v[232:235], v[236:237], off offset:528
	v_or_b32_e32 v206, 16, v194
	v_or_b32_e32 v202, 32, v194
	v_or_b32_e32 v198, 48, v194
	v_ashrrev_i32_e32 v207, 31, v206
	v_ashrrev_i32_e32 v203, 31, v202
	v_ashrrev_i32_e32 v199, 31, v198
	v_lshlrev_b64 v[128:129], 13, v[206:207]
	v_lshlrev_b64 v[130:131], 13, v[202:203]
	v_lshlrev_b64 v[132:133], 13, v[198:199]
	v_lshl_add_u64 v[208:209], v[196:197], 0, v[128:129]
	v_lshl_add_u64 v[204:205], v[196:197], 0, v[130:131]
	v_lshl_add_u64 v[200:201], v[196:197], 0, v[132:133]
	global_load_dwordx4 v[168:171], v[208:209], off offset:16
	global_load_dwordx4 v[172:175], v[208:209], off
	global_load_dwordx4 v[160:163], v[208:209], off offset:528
	global_load_dwordx4 v[164:167], v[208:209], off offset:512
	global_load_dwordx4 v[152:155], v[204:205], off offset:16
	global_load_dwordx4 v[156:159], v[204:205], off
	global_load_dwordx4 v[144:147], v[204:205], off offset:528
	global_load_dwordx4 v[148:151], v[204:205], off offset:512
	global_load_dwordx4 v[136:139], v[200:201], off offset:16
	global_load_dwordx4 v[140:143], v[200:201], off
	global_load_dwordx4 v[128:131], v[200:201], off offset:528
	global_load_dwordx4 v[132:135], v[200:201], off offset:512
	v_and_b32_e32 v218, 64, v217
	v_xor_b32_e32 v238, 16, v217
	v_add_u32_e32 v240, 64, v218
	v_xor_b32_e32 v239, 32, v217
	v_cmp_lt_i32_e32 vcc, v238, v240
	v_lshlrev_b64 v[218:219], 11, v[194:195]
	s_lshl_b32 s18, s2, 2
	v_cndmask_b32_e32 v241, v217, v238, vcc
	v_cmp_lt_i32_e32 vcc, v239, v240
	s_ashr_i32 s19, s18, 31
	v_readlane_b32 s53, v243, 4
	v_cndmask_b32_e32 v240, v217, v239, vcc
	v_lshl_add_u64 v[238:239], v[218:219], 0, v[192:193]
	v_lshlrev_b32_e32 v218, 2, v241
	v_lshl_add_u64 v[238:239], v[238:239], 1, s[12:13]
	v_readlane_b32 s54, v243, 5
	v_readlane_b32 s55, v243, 6
	v_readlane_b32 s56, v243, 7
	v_readlane_b32 s57, v243, 8
	v_readlane_b32 s58, v243, 9
	v_readlane_b32 s59, v243, 10
	v_readlane_b32 s60, v243, 11
	v_readlane_b32 s61, v243, 12
	v_readlane_b32 s62, v243, 13
	v_readlane_b32 s63, v243, 14
	v_readlane_b32 s64, v243, 15
	v_readlane_b32 s65, v243, 16
	s_waitcnt vmcnt(0)
	v_pk_add_f32 v[126:127], v[126:127], v[222:223]
	v_pk_add_f32 v[124:125], v[124:125], v[220:221]
	v_pk_add_f32 v[116:117], v[116:117], v[228:229]
	v_pk_add_f32 v[122:123], v[122:123], v[226:227]
	v_pk_add_f32 v[120:121], v[120:121], v[224:225]
	v_pk_add_f32 v[220:221], v[112:113], v[232:233]
	global_store_dwordx4 v[236:237], v[124:127], off
	global_store_dwordx4 v[236:237], v[120:123], off offset:16
	v_cvt_pk_bf16_f32 v112, v124, v125
	v_mul_f32_e32 v125, v125, v125
	v_mul_f32_e32 v219, v117, v117
	v_pk_add_f32 v[118:119], v[118:119], v[230:231]
	v_fmac_f32_e32 v125, v124, v124
	v_fmac_f32_e32 v219, v116, v116
	v_fmac_f32_e32 v125, v126, v126
	v_fmac_f32_e32 v219, v118, v118
	v_fmac_f32_e32 v125, v127, v127
	v_fmac_f32_e32 v219, v119, v119
	v_fmac_f32_e32 v125, v120, v120
	v_fmac_f32_e32 v219, v220, v220
	v_pk_add_f32 v[222:223], v[114:115], v[234:235]
	v_fmac_f32_e32 v125, v121, v121
	v_fmac_f32_e32 v219, v221, v221
	v_fmac_f32_e32 v125, v122, v122
	v_fmac_f32_e32 v219, v222, v222
	v_fmac_f32_e32 v125, v123, v123
	v_fmac_f32_e32 v219, v223, v223
	v_cvt_pk_bf16_f32 v114, v120, v121
	v_add_f32_e32 v121, v125, v219
	v_cvt_pk_bf16_f32 v115, v122, v123
	ds_bpermute_b32 v122, v218, v121
	v_cvt_pk_bf16_f32 v113, v126, v127
	global_store_dwordx4 v[238:239], v[112:115], off
	global_store_dwordx4 v[236:237], v[116:119], off offset:512
	global_store_dwordx4 v[236:237], v[220:223], off offset:528
	v_lshlrev_b32_e32 v126, 2, v240
	v_cvt_pk_bf16_f32 v120, v116, v117
	s_waitcnt lgkmcnt(0)
	v_add_f32_e32 v112, v121, v122
	ds_bpermute_b32 v113, v126, v112
	v_cvt_pk_bf16_f32 v121, v118, v119
	v_cvt_pk_bf16_f32 v122, v220, v221
	v_cvt_pk_bf16_f32 v123, v222, v223
	global_store_dwordx4 v[238:239], v[120:123], off offset:256
	s_and_saveexec_b64 s[20:21], s[0:1]
	s_cbranch_execz .LBB0_964
	s_waitcnt lgkmcnt(0)
	v_add_f32_e32 v114, v112, v113
	v_lshlrev_b64 v[112:113], 7, v[194:195]
	v_lshl_add_u64 v[112:113], s[14:15], 0, v[112:113]
	v_lshl_add_u64 v[112:113], s[18:19], 2, v[112:113]
	s_lshl_b32 s2, s36, 2
	v_lshl_add_u64 v[112:113], v[112:113], 0, s[2:3]
	global_store_dword v[112:113], v114, off

; #define PG8_STAGE(bufoff, gbase, voff) do { _Pragma("unroll") for (int _i = 0; _i < 2; ++_i) \
;     __builtin_amdgcn_global_load_lds((const unsigned*)((const char*)(gbase) + (voff)[_i]), (LAS unsigned*)(lds + (bufoff) + ldsw + _i * 8192), 16, 0, 0); } while (0)
; #define PG8_LDA(dst, b, h) do { _Pragma("unroll") for (int m = 0; m < 4; ++m) _Pragma("unroll") for (int k = 0; k < 2; ++k) dst[m][k] = *(const LAS bf16x8*)(lds + PG8_SA(b, h) + aoff + m * 2048 + k * 1024); } while (0)
; #define PG8_LDB(dst, b, h) do { _Pragma("unroll") for (int n = 0; n < 2; ++n) _Pragma("unroll") for (int k = 0; k < 2; ++k) dst[n][k] = *(const LAS bf16x8*)(lds + PG8_SB(b, h) + boff + n * 2048 + k * 1024); } while (0)
; #define PG8_MMA(ai, bj, At, Bt) do { __builtin_amdgcn_s_setprio(1); _Pragma("unroll") for (int m = 0; m < 4; ++m) _Pragma("unroll") for (int n = 0; n < 2; ++n) _Pragma("unroll") for (int k = 0; k < 2; ++k) \
;     acc[ai][bj][m][n] = __builtin_amdgcn_mfma_f32_16x16x32_bf16(Bt[n][k], At[m][k], acc[ai][bj][m][n], 0, 0, 0); __builtin_amdgcn_s_setprio(0); } while (0)
; #define PG8_WAIT_V(n) asm volatile("s_waitcnt vmcnt(" #n ")" ::: "memory")
; #define PG8_WAIT_L(n) asm volatile("s_waitcnt lgkmcnt(" #n ")" ::: "memory")
; #define PG8_BAR __builtin_amdgcn_s_barrier()
; #define PG8_SCHED __builtin_amdgcn_sched_barrier(0)
; template <class Epi, class Sched = StaticOrder>
; DI void gemm_phase(LAS unsigned char* lds, const Gemm g, const Sched& S, const Epi& E) {
;     ...
;       PG8_LDB(B0, 0, 0); PG8_SCHED; PG8_LDA(At, 0, 0); PG8_STAGE(PG8_SA(1, 1), a1 + hstep, voffA);
;       PG8_WAIT_L(8); PG8_BAR; PG8_WAIT_L(0); PG8_MMA(0, 0, At, B0); PG8_BAR; PG8_SCHED;
;       PG8_LDB(B1, 0, 1); PG8_STAGE(PG8_SB(0, 0), b2, voffB);
;       PG8_BAR; PG8_WAIT_L(0); PG8_MMA(0, 1, At, B1); PG8_BAR;
;       PG8_LDA(At, 0, 1); PG8_STAGE(PG8_SA(0, 0), a2, voffA);
;       PG8_BAR; PG8_WAIT_L(0); PG8_MMA(1, 0, At, B0); PG8_BAR; PG8_SCHED;
;       PG8_STAGE(PG8_SB(0, 1), b2 + hstep, voffB);
;       PG8_WAIT_V(6); PG8_BAR; PG8_MMA(1, 1, At, B1); PG8_BAR;
.LBB0_1052:
	ds_read_b128 v[128:131], v203
	ds_read_b128 v[132:135], v203 offset:1024
	ds_read_b128 v[136:139], v203 offset:2048
	ds_read_b128 v[140:143], v203 offset:3072
	s_add_u32 s12, s10, 0xfff80080
	s_addc_u32 s13, s11, -1
	s_cmp_eq_u32 s52, 28
	s_cselect_b32 s65, s41, s13
	s_cselect_b32 s64, s42, s12
	s_cselect_b32 s13, s43, s49
	s_cselect_b32 s12, s44, s45
	s_add_i32 m0, s61, 0xc000
	ds_read_b128 v[144:147], v204
	ds_read_b128 v[148:151], v204 offset:1024
	ds_read_b128 v[152:155], v204 offset:2048
	ds_read_b128 v[156:159], v204 offset:3072
	ds_read_b128 v[178:181], v204 offset:4096
	ds_read_b128 v[182:185], v204 offset:5120
	ds_read_b128 v[186:189], v204 offset:6144
	ds_read_b128 v[190:193], v204 offset:7168
	global_load_lds_dwordx4 v172, s[10:11]
	s_add_i32 m0, s61, 0xe000
	s_nop 0
	global_load_lds_dwordx4 v174, s[10:11]
	ds_read_b128 v[194:197], v205
	ds_read_b128 v[212:215], v205 offset:1024
	ds_read_b128 v[216:219], v205 offset:2048
	ds_read_b128 v[220:223], v205 offset:3072
	s_waitcnt vmcnt(8)
	s_waitcnt lgkmcnt(4)
	s_setprio 1
	s_barrier
	v_mfma_f32_16x16x32_bf16 v[124:127], v[128:131], v[144:147], v[124:127]
	v_mfma_f32_16x16x32_bf16 v[120:123], v[136:139], v[144:147], v[120:123]
	v_mfma_f32_16x16x32_bf16 v[116:119], v[128:131], v[152:155], v[116:119]
	v_mfma_f32_16x16x32_bf16 v[104:107], v[136:139], v[152:155], v[104:107]
	v_mfma_f32_16x16x32_bf16 v[92:95], v[128:131], v[178:181], v[92:95]
	v_mfma_f32_16x16x32_bf16 v[88:91], v[136:139], v[178:181], v[88:91]
	v_mfma_f32_16x16x32_bf16 v[84:87], v[128:131], v[186:189], v[84:87]
	v_mfma_f32_16x16x32_bf16 v[72:75], v[136:139], v[186:189], v[72:75]
	v_mfma_f32_16x16x32_bf16 v[124:127], v[132:135], v[148:151], v[124:127]
	v_mfma_f32_16x16x32_bf16 v[120:123], v[140:143], v[148:151], v[120:123]
	v_mfma_f32_16x16x32_bf16 v[116:119], v[132:135], v[156:159], v[116:119]
	v_mfma_f32_16x16x32_bf16 v[104:107], v[140:143], v[156:159], v[104:107]
	v_mfma_f32_16x16x32_bf16 v[92:95], v[132:135], v[182:185], v[92:95]
	v_mfma_f32_16x16x32_bf16 v[88:91], v[140:143], v[182:185], v[88:91]
	v_mfma_f32_16x16x32_bf16 v[84:87], v[132:135], v[190:193], v[84:87]
	v_mfma_f32_16x16x32_bf16 v[72:75], v[140:143], v[190:193], v[72:75]
	s_waitcnt lgkmcnt(0)
	v_mfma_f32_16x16x32_bf16 v[112:115], v[194:197], v[144:147], v[112:115]
	v_mfma_f32_16x16x32_bf16 v[108:111], v[216:219], v[144:147], v[108:111]
	v_mfma_f32_16x16x32_bf16 v[100:103], v[194:197], v[152:155], v[100:103]
	v_mfma_f32_16x16x32_bf16 v[96:99], v[216:219], v[152:155], v[96:99]
	v_mfma_f32_16x16x32_bf16 v[80:83], v[194:197], v[178:181], v[80:83]
	v_mfma_f32_16x16x32_bf16 v[76:79], v[216:219], v[178:181], v[76:79]
	v_mfma_f32_16x16x32_bf16 v[68:71], v[194:197], v[186:189], v[68:71]
	v_mfma_f32_16x16x32_bf16 v[64:67], v[216:219], v[186:189], v[64:67]
	v_mfma_f32_16x16x32_bf16 v[112:115], v[212:215], v[148:151], v[112:115]
	v_mfma_f32_16x16x32_bf16 v[108:111], v[220:223], v[148:151], v[108:111]
	v_mfma_f32_16x16x32_bf16 v[100:103], v[212:215], v[156:159], v[100:103]
	v_mfma_f32_16x16x32_bf16 v[96:99], v[220:223], v[156:159], v[96:99]
	v_mfma_f32_16x16x32_bf16 v[80:83], v[212:215], v[182:185], v[80:83]
	v_mfma_f32_16x16x32_bf16 v[76:79], v[220:223], v[182:185], v[76:79]
	v_mfma_f32_16x16x32_bf16 v[68:71], v[212:215], v[190:193], v[68:71]
	v_mfma_f32_16x16x32_bf16 v[64:67], v[220:223], v[190:193], v[64:67]
	s_barrier
	s_setprio 0
	s_add_i32 s53, s80, s70
	s_add_u32 s98, s12, 0x80
	s_addc_u32 s99, s13, 0
	s_add_u32 s100, s64, 0x80
	s_addc_u32 s101, s65, 0
	s_mov_b32 m0, s53
	s_nop 0
	global_load_lds_dwordx4 v162, s[12:13]
	s_add_i32 m0, s53, 0x2000
	s_nop 0
	global_load_lds_dwordx4 v166, s[12:13]
	s_mov_b32 m0, s61
	s_nop 0
	global_load_lds_dwordx4 v160, s[64:65]
	s_mov_b32 m0, s63
	s_nop 0
	global_load_lds_dwordx4 v164, s[64:65]
	ds_read_b128 v[144:147], v204 offset:16384
	ds_read_b128 v[148:151], v204 offset:17408
	ds_read_b128 v[152:155], v204 offset:18432
	ds_read_b128 v[156:159], v204 offset:19456
	ds_read_b128 v[178:181], v204 offset:20480
	ds_read_b128 v[182:185], v204 offset:21504
	ds_read_b128 v[186:189], v204 offset:22528
	ds_read_b128 v[190:193], v204 offset:23552
	s_add_u32 s54, s12, 0x80000
	s_addc_u32 s55, s13, 0
	s_add_i32 s53, s81, s70
	s_waitcnt vmcnt(6)
	s_waitcnt lgkmcnt(0)
	s_setprio 1
	s_barrier
	v_mfma_f32_16x16x32_bf16 v[60:63], v[128:131], v[144:147], v[60:63]
	s_mov_b32 m0, s53
	v_mfma_f32_16x16x32_bf16 v[56:59], v[136:139], v[144:147], v[56:59]
	global_load_lds_dwordx4 v162, s[54:55]
	v_mfma_f32_16x16x32_bf16 v[48:51], v[128:131], v[152:155], v[48:51]
	s_bitset1_b32 m0, 13
	v_mfma_f32_16x16x32_bf16 v[40:43], v[136:139], v[152:155], v[40:43]
	global_load_lds_dwordx4 v166, s[54:55]
	v_mfma_f32_16x16x32_bf16 v[28:31], v[128:131], v[178:181], v[28:31]
	v_mfma_f32_16x16x32_bf16 v[24:27], v[136:139], v[178:181], v[24:27]
	v_mfma_f32_16x16x32_bf16 v[12:15], v[128:131], v[186:189], v[12:15]
	v_mfma_f32_16x16x32_bf16 v[8:11], v[136:139], v[186:189], v[8:11]
	v_mfma_f32_16x16x32_bf16 v[60:63], v[132:135], v[148:151], v[60:63]
	v_mfma_f32_16x16x32_bf16 v[56:59], v[140:143], v[148:151], v[56:59]
	v_mfma_f32_16x16x32_bf16 v[48:51], v[132:135], v[156:159], v[48:51]
	v_mfma_f32_16x16x32_bf16 v[40:43], v[140:143], v[156:159], v[40:43]
	v_mfma_f32_16x16x32_bf16 v[28:31], v[132:135], v[182:185], v[28:31]
	v_mfma_f32_16x16x32_bf16 v[24:27], v[140:143], v[182:185], v[24:27]
	v_mfma_f32_16x16x32_bf16 v[12:15], v[132:135], v[190:193], v[12:15]
	v_mfma_f32_16x16x32_bf16 v[8:11], v[140:143], v[190:193], v[8:11]
	v_mfma_f32_16x16x32_bf16 v[52:55], v[194:197], v[144:147], v[52:55]
	v_mfma_f32_16x16x32_bf16 v[44:47], v[216:219], v[144:147], v[44:47]
	v_mfma_f32_16x16x32_bf16 v[36:39], v[194:197], v[152:155], v[36:39]
	v_mfma_f32_16x16x32_bf16 v[32:35], v[216:219], v[152:155], v[32:35]
	v_mfma_f32_16x16x32_bf16 v[20:23], v[194:197], v[178:181], v[20:23]
	v_mfma_f32_16x16x32_bf16 v[16:19], v[216:219], v[178:181], v[16:19]
	v_mfma_f32_16x16x32_bf16 v[4:7], v[194:197], v[186:189], v[4:7]
	v_mfma_f32_16x16x32_bf16 v[0:3], v[216:219], v[186:189], v[0:3]
	v_mfma_f32_16x16x32_bf16 v[52:55], v[212:215], v[148:151], v[52:55]
	v_mfma_f32_16x16x32_bf16 v[44:47], v[220:223], v[148:151], v[44:47]
	v_mfma_f32_16x16x32_bf16 v[36:39], v[212:215], v[156:159], v[36:39]
	v_mfma_f32_16x16x32_bf16 v[32:35], v[220:223], v[156:159], v[32:35]
	v_mfma_f32_16x16x32_bf16 v[20:23], v[212:215], v[182:185], v[20:23]
	v_mfma_f32_16x16x32_bf16 v[16:19], v[220:223], v[182:185], v[16:19]
	v_mfma_f32_16x16x32_bf16 v[4:7], v[212:215], v[190:193], v[4:7]
	v_mfma_f32_16x16x32_bf16 v[0:3], v[220:223], v[190:193], v[0:3]
	s_barrier
; #define PG8_STAGE(bufoff, gbase, voff) do { _Pragma("unroll") for (int _i = 0; _i < 2; ++_i) \
;     __builtin_amdgcn_global_load_lds((const unsigned*)((const char*)(gbase) + (voff)[_i]), (LAS unsigned*)(lds + (bufoff) + ldsw + _i * 8192), 16, 0, 0); } while (0)
; #define PG8_LDA(dst, b, h) do { _Pragma("unroll") for (int m = 0; m < 4; ++m) _Pragma("unroll") for (int k = 0; k < 2; ++k) dst[m][k] = *(const LAS bf16x8*)(lds + PG8_SA(b, h) + aoff + m * 2048 + k * 1024); } while (0)
; #define PG8_LDB(dst, b, h) do { _Pragma("unroll") for (int n = 0; n < 2; ++n) _Pragma("unroll") for (int k = 0; k < 2; ++k) dst[n][k] = *(const LAS bf16x8*)(lds + PG8_SB(b, h) + boff + n * 2048 + k * 1024); } while (0)
; #define PG8_MMA(ai, bj, At, Bt) do { __builtin_amdgcn_s_setprio(1); _Pragma("unroll") for (int m = 0; m < 4; ++m) _Pragma("unroll") for (int n = 0; n < 2; ++n) _Pragma("unroll") for (int k = 0; k < 2; ++k) \
;     acc[ai][bj][m][n] = __builtin_amdgcn_mfma_f32_16x16x32_bf16(Bt[n][k], At[m][k], acc[ai][bj][m][n], 0, 0, 0); __builtin_amdgcn_s_setprio(0); } while (0)
; #define PG8_WAIT_V(n) asm volatile("s_waitcnt vmcnt(" #n ")" ::: "memory")
; #define PG8_WAIT_L(n) asm volatile("s_waitcnt lgkmcnt(" #n ")" ::: "memory")
; #define PG8_BAR __builtin_amdgcn_s_barrier()
; #define PG8_SCHED __builtin_amdgcn_sched_barrier(0)
; template <class Epi, class Sched = StaticOrder>
; DI void gemm_phase(LAS unsigned char* lds, const Gemm g, const Sched& S, const Epi& E) {
;     ...
;       PG8_LDB(B0, 1, 0); PG8_SCHED; PG8_LDA(At, 1, 0); PG8_STAGE(PG8_SA(0, 1), a2 + hstep, voffA);
;       PG8_WAIT_L(8); PG8_BAR; PG8_WAIT_L(0); PG8_MMA(0, 0, At, B0); PG8_BAR; PG8_SCHED;
;       PG8_LDB(B1, 1, 1); PG8_STAGE(PG8_SB(1, 0), b3, voffB);
;       PG8_BAR; PG8_WAIT_L(0); PG8_MMA(0, 1, At, B1); PG8_BAR;
;       PG8_LDA(At, 1, 1); PG8_STAGE(PG8_SA(1, 0), a3, voffA);
;       PG8_BAR; PG8_WAIT_L(0); PG8_MMA(1, 0, At, B0); PG8_BAR; PG8_SCHED;
;       PG8_STAGE(PG8_SB(1, 1), b3 + hstep, voffB);
;       PG8_WAIT_V(6); PG8_BAR; PG8_MMA(1, 1, At, B1); PG8_BAR;
	s_setprio 0
	s_add_i32 s53, 0, 0x18000
	v_add_u32_e32 v140, s53, v199
	ds_read_b128 v[128:131], v140
	ds_read_b128 v[132:135], v140 offset:1024
	ds_read_b128 v[136:139], v140 offset:2048
	ds_read_b128 v[140:143], v140 offset:3072
	s_add_u32 s54, s64, 0x80000
	s_addc_u32 s55, s65, 0
	s_mov_b32 m0, s71
	ds_read_b128 v[144:147], v204 offset:32768
	ds_read_b128 v[148:151], v204 offset:33792
	ds_read_b128 v[152:155], v204 offset:34816
	ds_read_b128 v[156:159], v204 offset:35840
	ds_read_b128 v[178:181], v204 offset:36864
	ds_read_b128 v[182:185], v204 offset:37888
	ds_read_b128 v[186:189], v204 offset:38912
	ds_read_b128 v[190:193], v204 offset:39936
	global_load_lds_dwordx4 v160, s[54:55]
	s_mov_b32 m0, s72
	s_nop 0
	global_load_lds_dwordx4 v164, s[54:55]
	s_add_i32 s54, 0, 0x1c000
	v_add_u32_e32 v168, s54, v199
	ds_read_b128 v[194:197], v168
	ds_read_b128 v[212:215], v168 offset:1024
	ds_read_b128 v[216:219], v168 offset:2048
	ds_read_b128 v[220:223], v168 offset:3072
	s_waitcnt vmcnt(8)
	s_waitcnt lgkmcnt(4)
	s_setprio 1
	s_barrier
	v_mfma_f32_16x16x32_bf16 v[124:127], v[128:131], v[144:147], v[124:127]
	v_mfma_f32_16x16x32_bf16 v[120:123], v[136:139], v[144:147], v[120:123]
	v_mfma_f32_16x16x32_bf16 v[116:119], v[128:131], v[152:155], v[116:119]
	v_mfma_f32_16x16x32_bf16 v[104:107], v[136:139], v[152:155], v[104:107]
	v_mfma_f32_16x16x32_bf16 v[92:95], v[128:131], v[178:181], v[92:95]
	v_mfma_f32_16x16x32_bf16 v[88:91], v[136:139], v[178:181], v[88:91]
	v_mfma_f32_16x16x32_bf16 v[84:87], v[128:131], v[186:189], v[84:87]
	v_mfma_f32_16x16x32_bf16 v[72:75], v[136:139], v[186:189], v[72:75]
	v_mfma_f32_16x16x32_bf16 v[124:127], v[132:135], v[148:151], v[124:127]
	v_mfma_f32_16x16x32_bf16 v[120:123], v[140:143], v[148:151], v[120:123]
	v_mfma_f32_16x16x32_bf16 v[116:119], v[132:135], v[156:159], v[116:119]
	v_mfma_f32_16x16x32_bf16 v[104:107], v[140:143], v[156:159], v[104:107]
	v_mfma_f32_16x16x32_bf16 v[92:95], v[132:135], v[182:185], v[92:95]
	v_mfma_f32_16x16x32_bf16 v[88:91], v[140:143], v[182:185], v[88:91]
	v_mfma_f32_16x16x32_bf16 v[84:87], v[132:135], v[190:193], v[84:87]
	v_mfma_f32_16x16x32_bf16 v[72:75], v[140:143], v[190:193], v[72:75]
	s_waitcnt lgkmcnt(0)
	v_mfma_f32_16x16x32_bf16 v[112:115], v[194:197], v[144:147], v[112:115]
	v_mfma_f32_16x16x32_bf16 v[108:111], v[216:219], v[144:147], v[108:111]
	v_mfma_f32_16x16x32_bf16 v[100:103], v[194:197], v[152:155], v[100:103]
	v_mfma_f32_16x16x32_bf16 v[96:99], v[216:219], v[152:155], v[96:99]
	v_mfma_f32_16x16x32_bf16 v[80:83], v[194:197], v[178:181], v[80:83]
	v_mfma_f32_16x16x32_bf16 v[76:79], v[216:219], v[178:181], v[76:79]
	v_mfma_f32_16x16x32_bf16 v[68:71], v[194:197], v[186:189], v[68:71]
	v_mfma_f32_16x16x32_bf16 v[64:67], v[216:219], v[186:189], v[64:67]
	v_mfma_f32_16x16x32_bf16 v[112:115], v[212:215], v[148:151], v[112:115]
	v_mfma_f32_16x16x32_bf16 v[108:111], v[220:223], v[148:151], v[108:111]
	v_mfma_f32_16x16x32_bf16 v[100:103], v[212:215], v[156:159], v[100:103]
	v_mfma_f32_16x16x32_bf16 v[96:99], v[220:223], v[156:159], v[96:99]
	v_mfma_f32_16x16x32_bf16 v[80:83], v[212:215], v[182:185], v[80:83]
	v_mfma_f32_16x16x32_bf16 v[76:79], v[220:223], v[182:185], v[76:79]
	v_mfma_f32_16x16x32_bf16 v[68:71], v[212:215], v[190:193], v[68:71]
	v_mfma_f32_16x16x32_bf16 v[64:67], v[220:223], v[190:193], v[64:67]
	s_barrier
	s_setprio 0
	s_add_i32 s53, s53, s70
	s_mov_b32 m0, s53
	s_nop 0
	global_load_lds_dwordx4 v162, s[98:99]
	s_add_i32 m0, s53, 0x2000
	s_nop 0
	global_load_lds_dwordx4 v166, s[98:99]
	s_mov_b32 m0, s76
	s_nop 0
	global_load_lds_dwordx4 v160, s[100:101]
	s_mov_b32 m0, s77
	s_nop 0
	global_load_lds_dwordx4 v164, s[100:101]
	ds_read_b128 v[144:147], v204 offset:49152
	ds_read_b128 v[148:151], v204 offset:50176
	ds_read_b128 v[152:155], v204 offset:51200
	ds_read_b128 v[156:159], v204 offset:52224
	ds_read_b128 v[178:181], v204 offset:53248
	ds_read_b128 v[182:185], v204 offset:54272
	ds_read_b128 v[186:189], v204 offset:55296
	ds_read_b128 v[190:193], v204 offset:56320
	s_add_u32 s12, s12, 0x80080
	s_addc_u32 s13, s13, 0
	s_add_i32 s53, s54, s70
	s_add_i32 s52, s52, 2
	s_add_u32 s10, s10, 0x100
	s_addc_u32 s11, s11, 0
	s_add_u32 s45, s45, 0x100
	s_addc_u32 s49, s49, 0
	s_cmp_gt_u32 s52, 29
	s_waitcnt vmcnt(6)
	s_waitcnt lgkmcnt(0)
	s_setprio 1
	s_barrier
	v_mfma_f32_16x16x32_bf16 v[60:63], v[128:131], v[144:147], v[60:63]
	s_mov_b32 m0, s53
	v_mfma_f32_16x16x32_bf16 v[56:59], v[136:139], v[144:147], v[56:59]
	global_load_lds_dwordx4 v162, s[12:13]
	v_mfma_f32_16x16x32_bf16 v[48:51], v[128:131], v[152:155], v[48:51]
	s_bitset1_b32 m0, 13
	v_mfma_f32_16x16x32_bf16 v[40:43], v[136:139], v[152:155], v[40:43]
	global_load_lds_dwordx4 v166, s[12:13]
	v_mfma_f32_16x16x32_bf16 v[28:31], v[128:131], v[178:181], v[28:31]
	v_mfma_f32_16x16x32_bf16 v[24:27], v[136:139], v[178:181], v[24:27]
	v_mfma_f32_16x16x32_bf16 v[12:15], v[128:131], v[186:189], v[12:15]
	v_mfma_f32_16x16x32_bf16 v[8:11], v[136:139], v[186:189], v[8:11]
	v_mfma_f32_16x16x32_bf16 v[60:63], v[132:135], v[148:151], v[60:63]
	v_mfma_f32_16x16x32_bf16 v[56:59], v[140:143], v[148:151], v[56:59]
	v_mfma_f32_16x16x32_bf16 v[48:51], v[132:135], v[156:159], v[48:51]
	v_mfma_f32_16x16x32_bf16 v[40:43], v[140:143], v[156:159], v[40:43]
	v_mfma_f32_16x16x32_bf16 v[28:31], v[132:135], v[182:185], v[28:31]
	v_mfma_f32_16x16x32_bf16 v[24:27], v[140:143], v[182:185], v[24:27]
	v_mfma_f32_16x16x32_bf16 v[12:15], v[132:135], v[190:193], v[12:15]
	v_mfma_f32_16x16x32_bf16 v[8:11], v[140:143], v[190:193], v[8:11]
	v_mfma_f32_16x16x32_bf16 v[52:55], v[194:197], v[144:147], v[52:55]
	v_mfma_f32_16x16x32_bf16 v[44:47], v[216:219], v[144:147], v[44:47]
	v_mfma_f32_16x16x32_bf16 v[36:39], v[194:197], v[152:155], v[36:39]
	v_mfma_f32_16x16x32_bf16 v[32:35], v[216:219], v[152:155], v[32:35]
	v_mfma_f32_16x16x32_bf16 v[20:23], v[194:197], v[178:181], v[20:23]
	v_mfma_f32_16x16x32_bf16 v[16:19], v[216:219], v[178:181], v[16:19]
	v_mfma_f32_16x16x32_bf16 v[4:7], v[194:197], v[186:189], v[4:7]
	v_mfma_f32_16x16x32_bf16 v[0:3], v[216:219], v[186:189], v[0:3]
	v_mfma_f32_16x16x32_bf16 v[52:55], v[212:215], v[148:151], v[52:55]
	v_mfma_f32_16x16x32_bf16 v[44:47], v[220:223], v[148:151], v[44:47]
	v_mfma_f32_16x16x32_bf16 v[36:39], v[212:215], v[156:159], v[36:39]
	v_mfma_f32_16x16x32_bf16 v[32:35], v[220:223], v[156:159], v[32:35]
	v_mfma_f32_16x16x32_bf16 v[20:23], v[212:215], v[182:185], v[20:23]
	v_mfma_f32_16x16x32_bf16 v[16:19], v[220:223], v[182:185], v[16:19]
	v_mfma_f32_16x16x32_bf16 v[4:7], v[212:215], v[190:193], v[4:7]
	v_mfma_f32_16x16x32_bf16 v[0:3], v[220:223], v[190:193], v[0:3]
	s_barrier
; DI float row_rstd(const float* ssq, int row, int fq) {
;   const f32x4 a = *(const f32x4*)(ssq + (size_t)row * 32 + fq * 8), b = *(const f32x4*)(ssq + (size_t)row * 32 + fq * 8 + 4);
;   float sm = ((a[0] + a[1]) + (a[2] + a[3])) + ((b[0] + b[1]) + (b[2] + b[3]));
;   sm += __shfl_xor(sm, 16); sm += __shfl_xor(sm, 32);
;   return rsqrtf(sm * (1.0f / 2048.f) + 1e-6f);
;   DI void operator()(const f32x4 (&acc)[2][2][4][2], const Unit& u, int wr, int wc, int fr, int fq) const {
;     ...
;     const int col = u.pn * 128 + wc * 32 + 8 * fq;
;     float w0[8], w1[8], w2[8];
; #pragma unroll
;     for (int e = 0; e < 8; ++e) { w0[e] = cw[col + e]; w1[e] = cw[2048 + col + e]; w2[e] = cw[4096 + col + e]; }
; #pragma unroll
;     for (int ai = 0; ai < 2; ++ai) {
;       const int row0 = u.pm * BM + ai * HALF + wr * 64, span = row0 >> 6;
;       float rsv[4];
; #pragma unroll
;       for (int m = 0; m < 4; ++m) rsv[m] = row_rstd(ssq, row0 + 16 * m + fr, fq);
	s_setprio 0
	s_cbranch_scc0 .LBB0_1052
	s_cmp_lt_i32 s62, 16
	s_mov_b64 s[10:11], -1
	s_cbranch_scc0 .LBB0_1067
	s_lshl_b32 s41, s60, 8
	s_add_i32 s41, s41, s75
	v_or_b32_e32 v186, s41, v177
	v_ashrrev_i32_e32 v187, 31, v186
	v_lshlrev_b64 v[128:129], 7, v[186:187]
	v_or_b32_e32 v180, 16, v186
	v_lshl_add_u64 v[128:129], v[170:171], 0, v[128:129]
	v_ashrrev_i32_e32 v181, 31, v180
	global_load_dwordx4 v[152:155], v[128:129], off
	global_load_dwordx4 v[156:159], v[128:129], off offset:16
	v_lshlrev_b64 v[128:129], 7, v[180:181]
	v_lshl_add_u64 v[128:129], v[170:171], 0, v[128:129]
	global_load_dwordx4 v[188:191], v[128:129], off
	global_load_dwordx4 v[192:195], v[128:129], off offset:16
	v_or_b32_e32 v184, 32, v186
	v_ashrrev_i32_e32 v185, 31, v184
	v_lshlrev_b64 v[128:129], 7, v[184:185]
	v_or_b32_e32 v182, 48, v186
	v_lshl_add_u64 v[128:129], v[170:171], 0, v[128:129]
	v_ashrrev_i32_e32 v183, 31, v182
	global_load_dwordx4 v[212:215], v[128:129], off
	global_load_dwordx4 v[216:219], v[128:129], off offset:16
	v_lshlrev_b64 v[128:129], 7, v[182:183]
	v_lshl_add_u64 v[128:129], v[170:171], 0, v[128:129]
	global_load_dwordx4 v[220:223], v[128:129], off
	global_load_dwordx4 v[224:227], v[128:129], off offset:16
	v_and_b32_e32 v129, 64, v206
	v_lshl_or_b32 v178, s62, 7, v200
	v_xor_b32_e32 v128, 16, v206
	v_add_u32_e32 v129, 64, v129
	v_readlane_b32 s44, v243, 3
	v_xor_b32_e32 v130, 32, v206
	v_ashrrev_i32_e32 v179, 31, v178
	v_readlane_b32 s45, v243, 4
	v_cmp_lt_i32_e32 vcc, v128, v129
	s_movk_i32 s10, 0x2000
	v_lshl_add_u64 v[144:145], v[178:179], 2, s[44:45]
	v_cndmask_b32_e32 v134, v206, v128, vcc
	v_cmp_lt_i32_e32 vcc, v130, v129
	v_lshl_add_u64 v[132:133], v[144:145], 0, s[26:27]
	v_lshl_add_u64 v[136:137], v[144:145], 0, s[28:29]
	v_cndmask_b32_e32 v135, v206, v130, vcc
	v_add_co_u32_e32 v146, vcc, s10, v144
	global_load_dwordx4 v[128:131], v[144:145], off offset:16
	global_load_dwordx4 v[140:143], v[144:145], off
	v_addc_co_u32_e32 v147, vcc, 0, v145, vcc
	v_add_co_u32_e32 v148, vcc, s74, v144
	v_lshlrev_b32_e32 v196, 2, v134
	s_nop 0
	v_addc_co_u32_e32 v149, vcc, 0, v145, vcc
	v_lshlrev_b32_e32 v207, 2, v135
	global_load_dwordx4 v[132:135], v[132:133], off offset:16
	s_nop 0
	global_load_dwordx4 v[136:139], v[136:137], off offset:16
	s_nop 0
	global_load_dwordx4 v[144:147], v[146:147], off
	s_nop 0
	global_load_dwordx4 v[148:151], v[148:149], off
	v_mov_b32_e32 v197, 0
	v_mov_b32_e32 v211, 0
	v_readlane_b32 s46, v243, 5
	v_readlane_b32 s47, v243, 6
	v_readlane_b32 s48, v243, 7
	v_readlane_b32 s49, v243, 8
	v_readlane_b32 s50, v243, 9
	v_readlane_b32 s51, v243, 10
	v_readlane_b32 s52, v243, 11
	v_readlane_b32 s53, v243, 12
	v_readlane_b32 s54, v243, 13
	v_readlane_b32 s55, v243, 14
	v_readlane_b32 s56, v243, 15
	v_readlane_b32 s57, v243, 16
	v_readlane_b32 s58, v243, 17
	v_readlane_b32 s59, v243, 18
	s_waitcnt vmcnt(0)
	v_mov_b32_e32 v208, v152
	v_mov_b32_e32 v209, v156
	v_mov_b32_e32 v156, v153
	v_mov_b32_e32 v152, v154
	v_mov_b32_e32 v153, v158
	v_mov_b32_e32 v158, v155
	v_pk_add_f32 v[154:155], v[208:209], v[156:157]
	v_pk_add_f32 v[152:153], v[152:153], v[158:159]
	v_mov_b32_e32 v156, v188
	v_mov_b32_e32 v157, v192
	v_mov_b32_e32 v192, v189
	v_mov_b32_e32 v158, v190
	v_mov_b32_e32 v159, v194
	v_mov_b32_e32 v194, v191
	v_pk_add_f32 v[152:153], v[154:155], v[152:153]
	v_pk_add_f32 v[154:155], v[156:157], v[192:193]
	v_pk_add_f32 v[156:157], v[158:159], v[194:195]
	v_mov_b32_e32 v188, v212
	v_pk_add_f32 v[154:155], v[154:155], v[156:157]
	v_mov_b32_e32 v157, v152
	v_mov_b32_e32 v156, v154
	v_mov_b32_e32 v152, v155
	v_pk_add_f32 v[152:153], v[156:157], v[152:153]
	ds_bpermute_b32 v155, v196, v153
	ds_bpermute_b32 v154, v196, v152
	v_mov_b32_e32 v189, v216
	v_mov_b32_e32 v216, v213
	v_mov_b32_e32 v190, v214
	v_mov_b32_e32 v191, v218
	s_waitcnt lgkmcnt(0)
	v_pk_add_f32 v[152:153], v[152:153], v[154:155]
	ds_bpermute_b32 v155, v207, v153
	ds_bpermute_b32 v154, v207, v152
	v_mov_b32_e32 v218, v215
	v_mov_b32_e32 v208, v220
	v_mov_b32_e32 v209, v224
	v_mov_b32_e32 v224, v221
	v_mov_b32_e32 v212, v222
	v_mov_b32_e32 v213, v226
	v_mov_b32_e32 v226, v223
	v_pk_add_f32 v[156:157], v[188:189], v[216:217]
	v_pk_add_f32 v[158:159], v[190:191], v[218:219]
	v_pk_add_f32 v[188:189], v[208:209], v[224:225]
	v_pk_add_f32 v[190:191], v[212:213], v[226:227]
	s_waitcnt lgkmcnt(0)
; DI unsigned pack2(float lo, float hi) { f32x2 v = {lo, hi}; bf16v2 r = __builtin_convertvector(v, bf16v2); return __builtin_bit_cast(unsigned, r); }
; DI float dpp_ror1(float v) { return __int_as_float(__builtin_amdgcn_update_dpp(0, __float_as_int(v), 0x121, 0xf, 0xf, false)); }
; DI float dpp_ror2(float v) { return __int_as_float(__builtin_amdgcn_update_dpp(0, __float_as_int(v), 0x122, 0xf, 0xf, false)); }
;   DI void operator()(const f32x4 (&acc)[2][2][4][2], const Unit& u, int wr, int wc, int fr, int fq) const {
;     ...
; #pragma unroll
;       for (int m = 0; m < 4; ++m) {
;         float g[8], a[8];
;         const float rs1 = rsv[m], rs2 = rs1 * rs1;
; #pragma unroll
;         for (int e = 0; e < 4; ++e) { g[e] = acc[ai][0][m][0][e] * acc[ai][1][m][0][e] * rs2; g[4 + e] = acc[ai][0][m][1][e] * acc[ai][1][m][1][e] * rs2; }
; #pragma unroll
;         for (int e = 0; e < 8; ++e) {
;           const float x1 = dpp_ror1(g[e]), x2 = dpp_ror2(g[e]);
;           const float pr1 = (fr == 0) ? p1[e] : x1, pr2 = (fr < 2) ? p2[e] : x2;
;           a[e] = w2[e] * g[e] + w1[e] * pr1 + w0[e] * pr2;
;           p1[e] = x1; p2[e] = x2;
;         }
;         if (m == 0 && fr < 2) {
;           float* hc = headC + (size_t)(span * 2 + fr) * 2048 + col;
;           *(f32x4*)hc = (f32x4){a[0], a[1], a[2], a[3]}; *(f32x4*)(hc + 4) = (f32x4){a[4], a[5], a[6], a[7]};
;         } else {
;           u32x4 w; w.x = pack2(a[0] * rs1, a[1] * rs1); w.y = pack2(a[2] * rs1, a[3] * rs1); w.z = pack2(a[4] * rs1, a[5] * rs1); w.w = pack2(a[6] * rs1, a[7] * rs1);
;           *(u32x4*)(C + (size_t)(row0 + 16 * m + fr) * 2048 + col) = w;
;         }
	v_pk_add_f32 v[152:153], v[152:153], v[154:155]
	v_pk_add_f32 v[156:157], v[156:157], v[158:159]
	v_pk_add_f32 v[158:159], v[188:189], v[190:191]
	v_pk_fma_f32 v[188:189], v[152:153], s[30:31], v[176:177] op_sel_hi:[1,0,0]
	v_mov_b32_e32 v153, v156
	v_mul_f32_e32 v152, 0x4b800000, v189
	v_cmp_gt_f32_e64 s[10:11], s84, v189
	v_mov_b32_e32 v156, v159
	v_mov_b32_e32 v194, v123
	v_cndmask_b32_e64 v152, v189, v152, s[10:11]
	v_rsq_f32_e32 v168, v152
	v_mov_b32_e32 v152, v158
	v_pk_add_f32 v[152:153], v[152:153], v[156:157]
	ds_bpermute_b32 v155, v196, v153
	ds_bpermute_b32 v154, v196, v152
	v_mul_f32_e32 v156, 0x45800000, v168
	v_cndmask_b32_e64 v195, v168, v156, s[10:11]
	v_mov_b32_e32 v217, 0
	v_mul_f32_e32 v156, v125, v113
	s_waitcnt lgkmcnt(0)
	v_pk_add_f32 v[190:191], v[152:153], v[154:155]
	v_mov_b32_e32 v152, v111
	v_mov_b32_e32 v153, v195
	v_mul_f32_e32 v154, v124, v112
	v_pk_mul_f32 v[152:153], v[194:195], v[152:153]
	v_mul_f32_e32 v155, v120, v108
	v_mul_f32_e32 v154, v154, v153
	v_pk_mul_f32 v[222:223], v[152:153], v[152:153] op_sel:[0,1] op_sel_hi:[1,0]
	v_mov_b32_e32 v213, 0
	v_mov_b32_dpp v217, v154 row_ror:1 row_mask:0xf bank_mask:0xf
	v_cndmask_b32_e64 v152, v217, 0, s[0:1]
	v_mul_f32_e32 v157, v121, v109
	v_mul_f32_e32 v158, v126, v114
	v_mul_f32_e32 v159, v122, v110
	v_mul_f32_e32 v168, v127, v115
	v_mul_f32_e32 v194, v155, v153
	v_mul_f32_e32 v155, v156, v153
	v_mov_b32_dpp v213, v154 row_ror:2 row_mask:0xf bank_mask:0xf
	v_mov_b32_e32 v221, 0
	v_mul_f32_e32 v152, v144, v152
	v_mul_f32_e32 v208, v157, v153
	v_mul_f32_e32 v156, v158, v153
	v_mul_f32_e32 v159, v159, v153
	v_mul_f32_e32 v157, v168, v153
	v_mov_b32_dpp v221, v155 row_ror:1 row_mask:0xf bank_mask:0xf
	v_cndmask_b32_e64 v153, v213, 0, s[8:9]
	v_fmac_f32_e32 v152, v148, v154
	v_mov_b32_e32 v219, 0
	v_fmac_f32_e32 v152, v140, v153
	v_cndmask_b32_e64 v153, v221, 0, s[0:1]
	v_mov_b32_dpp v219, v155 row_ror:2 row_mask:0xf bank_mask:0xf
	v_mul_f32_e32 v153, v145, v153
	v_mov_b32_e32 v216, 0
	v_cndmask_b32_e64 v154, v219, 0, s[8:9]
	v_fmac_f32_e32 v153, v149, v155
	v_mov_b32_dpp v216, v156 row_ror:1 row_mask:0xf bank_mask:0xf
	v_fmac_f32_e32 v153, v141, v154
	v_mov_b32_e32 v212, 0
	v_cndmask_b32_e64 v154, v216, 0, s[0:1]
	v_mov_b32_e32 v220, 0
	v_mov_b32_dpp v212, v156 row_ror:2 row_mask:0xf bank_mask:0xf
	v_mul_f32_e32 v154, v146, v154
	v_mov_b32_dpp v220, v157 row_ror:1 row_mask:0xf bank_mask:0xf
	v_cndmask_b32_e64 v155, v212, 0, s[8:9]
	v_fmac_f32_e32 v154, v150, v156
	v_mov_b32_e32 v218, 0
	v_fmac_f32_e32 v154, v142, v155
	v_cndmask_b32_e64 v155, v220, 0, s[0:1]
	v_mov_b32_dpp v218, v157 row_ror:2 row_mask:0xf bank_mask:0xf
	v_mul_f32_e32 v155, v147, v155
	v_cndmask_b32_e64 v156, v218, 0, s[8:9]
	v_fmac_f32_e32 v155, v151, v157
	v_mov_b32_dpp v197, v194 row_ror:1 row_mask:0xf bank_mask:0xf
	v_fmac_f32_e32 v155, v143, v156
	v_mov_b32_e32 v189, 0
	v_cndmask_b32_e64 v156, v197, 0, s[0:1]
	v_mov_b32_e32 v214, 0
	v_mov_b32_dpp v189, v194 row_ror:2 row_mask:0xf bank_mask:0xf
	v_mul_f32_e32 v156, v132, v156
	v_mov_b32_dpp v214, v208 row_ror:1 row_mask:0xf bank_mask:0xf
	v_cndmask_b32_e64 v157, v189, 0, s[8:9]
	v_fmac_f32_e32 v156, v136, v194
	v_fmac_f32_e32 v156, v128, v157
	v_cndmask_b32_e64 v157, v214, 0, s[0:1]
	v_mov_b32_e32 v209, 0
	v_mul_f32_e32 v157, v133, v157
	v_fmac_f32_e32 v157, v137, v208
	v_mov_b32_dpp v209, v208 row_ror:2 row_mask:0xf bank_mask:0xf
	v_mov_b32_e32 v208, 0
	v_cndmask_b32_e64 v158, v209, 0, s[8:9]
	v_fmac_f32_e32 v157, v129, v158
	v_mov_b32_dpp v208, v159 row_ror:1 row_mask:0xf bank_mask:0xf
	v_mov_b32_e32 v194, 0
	v_cndmask_b32_e64 v158, v208, 0, s[0:1]
	ds_bpermute_b32 v193, v207, v191
	ds_bpermute_b32 v192, v207, v190
	v_mov_b32_dpp v194, v159 row_ror:2 row_mask:0xf bank_mask:0xf
	v_mov_b32_e32 v215, 0
	v_mul_f32_e32 v158, v134, v158
	v_cndmask_b32_e64 v168, v194, 0, s[8:9]
	v_mov_b32_dpp v215, v222 row_ror:1 row_mask:0xf bank_mask:0xf
	v_fmac_f32_e32 v158, v138, v159
	v_mov_b32_dpp v211, v222 row_ror:2 row_mask:0xf bank_mask:0xf
	v_fmac_f32_e32 v158, v130, v168
	v_cndmask_b32_e64 v168, v215, 0, s[0:1]
	v_mul_f32_e32 v159, v139, v222
	v_cndmask_b32_e64 v223, v211, 0, s[8:9]
	v_fmac_f32_e32 v159, v135, v168
	v_cmp_gt_f32_e32 vcc, s84, v188
	v_fmac_f32_e32 v159, v131, v223
	s_and_saveexec_b64 s[10:11], s[4:5]
	s_xor_b64 s[10:11], exec, s[10:11]
	s_cbranch_execz .LBB0_1056
	v_mul_f32_e32 v152, v195, v152
	v_mul_f32_e32 v153, v195, v153
	v_cvt_pk_bf16_f32 v152, v152, v153
	v_mul_f32_e32 v153, v195, v154
	v_mul_f32_e32 v154, v195, v155
	v_cvt_pk_bf16_f32 v153, v153, v154
	v_mul_f32_e32 v154, v195, v156
	v_mul_f32_e32 v155, v195, v157
	v_cvt_pk_bf16_f32 v154, v154, v155
	v_mul_f32_e32 v155, v195, v158
	v_mul_f32_e32 v156, v195, v159
	v_cvt_pk_bf16_f32 v155, v155, v156
	v_lshlrev_b64 v[156:157], 12, v[186:187]
	v_lshl_add_u64 v[156:157], s[18:19], 0, v[156:157]
	v_lshl_add_u64 v[156:157], v[178:179], 1, v[156:157]
	global_store_dwordx4 v[156:157], v[152:155], off

; #define PG8_STAGE(bufoff, gbase, voff) do { _Pragma("unroll") for (int _i = 0; _i < 2; ++_i) \
;     __builtin_amdgcn_global_load_lds((const unsigned*)((const char*)(gbase) + (voff)[_i]), (LAS unsigned*)(lds + (bufoff) + ldsw + _i * 8192), 16, 0, 0); } while (0)
; #define PG8_LDA(dst, b, h) do { _Pragma("unroll") for (int m = 0; m < 4; ++m) _Pragma("unroll") for (int k = 0; k < 2; ++k) dst[m][k] = *(const LAS bf16x8*)(lds + PG8_SA(b, h) + aoff + m * 2048 + k * 1024); } while (0)
; #define PG8_LDB(dst, b, h) do { _Pragma("unroll") for (int n = 0; n < 2; ++n) _Pragma("unroll") for (int k = 0; k < 2; ++k) dst[n][k] = *(const LAS bf16x8*)(lds + PG8_SB(b, h) + boff + n * 2048 + k * 1024); } while (0)
; #define PG8_MMA(ai, bj, At, Bt) do { __builtin_amdgcn_s_setprio(1); _Pragma("unroll") for (int m = 0; m < 4; ++m) _Pragma("unroll") for (int n = 0; n < 2; ++n) _Pragma("unroll") for (int k = 0; k < 2; ++k) \
;     acc[ai][bj][m][n] = __builtin_amdgcn_mfma_f32_16x16x32_bf16(Bt[n][k], At[m][k], acc[ai][bj][m][n], 0, 0, 0); __builtin_amdgcn_s_setprio(0); } while (0)
; #define PG8_WAIT_V(n) asm volatile("s_waitcnt vmcnt(" #n ")" ::: "memory")
; #define PG8_WAIT_L(n) asm volatile("s_waitcnt lgkmcnt(" #n ")" ::: "memory")
; #define PG8_BAR __builtin_amdgcn_s_barrier()
; #define PG8_SCHED __builtin_amdgcn_sched_barrier(0)
; template <class Epi, class Sched = StaticOrder>
; DI void gemm_phase(LAS unsigned char* lds, const Gemm g, const Sched& S, const Epi& E) {
;     ...
;       PG8_LDB(B0, 0, 0); PG8_SCHED; PG8_LDA(At, 0, 0); PG8_STAGE(PG8_SA(1, 1), a1 + hstep, voffA);
;       PG8_WAIT_L(8); PG8_BAR; PG8_WAIT_L(0); PG8_MMA(0, 0, At, B0); PG8_BAR; PG8_SCHED;
;       PG8_LDB(B1, 0, 1); PG8_STAGE(PG8_SB(0, 0), b2, voffB);
;       PG8_BAR; PG8_WAIT_L(0); PG8_MMA(0, 1, At, B1); PG8_BAR;
;       PG8_LDA(At, 0, 1); PG8_STAGE(PG8_SA(0, 0), a2, voffA);
;       PG8_BAR; PG8_WAIT_L(0); PG8_MMA(1, 0, At, B0); PG8_BAR; PG8_SCHED;
;       PG8_STAGE(PG8_SB(0, 1), b2 + hstep, voffB);
;       PG8_WAIT_V(6); PG8_BAR; PG8_MMA(1, 1, At, B1); PG8_BAR;
.LBB0_1194:
	ds_read_b128 v[128:131], v214
	ds_read_b128 v[132:135], v214 offset:1024
	ds_read_b128 v[136:139], v214 offset:2048
	ds_read_b128 v[140:143], v214 offset:3072
	s_add_u32 s24, s22, 0xfff80080
	s_addc_u32 s25, s23, -1
	s_cmp_eq_u32 s54, 28
	s_cselect_b32 s27, s17, s25
	s_cselect_b32 s26, s43, s24
	s_cselect_b32 s25, s15, s53
	s_cselect_b32 s24, s51, s52
	s_add_i32 m0, s37, 0xc000
	ds_read_b128 v[144:147], v215
	ds_read_b128 v[148:151], v215 offset:1024
	ds_read_b128 v[152:155], v215 offset:2048
	ds_read_b128 v[156:159], v215 offset:3072
	ds_read_b128 v[160:163], v215 offset:4096
	ds_read_b128 v[164:167], v215 offset:5120
	ds_read_b128 v[168:171], v215 offset:6144
	ds_read_b128 v[172:175], v215 offset:7168
	global_load_lds_dwordx4 v184, s[22:23]
	s_add_i32 m0, s37, 0xe000
	s_nop 0
	global_load_lds_dwordx4 v186, s[22:23]
	ds_read_b128 v[192:195], v216
	ds_read_b128 v[196:199], v216 offset:1024
	ds_read_b128 v[200:203], v216 offset:2048
	ds_read_b128 v[204:207], v216 offset:3072
	s_waitcnt vmcnt(8)
	s_waitcnt lgkmcnt(4)
	s_setprio 1
	s_barrier
	v_mfma_f32_16x16x32_bf16 v[124:127], v[128:131], v[144:147], v[124:127]
	v_mfma_f32_16x16x32_bf16 v[120:123], v[136:139], v[144:147], v[120:123]
	v_mfma_f32_16x16x32_bf16 v[108:111], v[128:131], v[152:155], v[108:111]
	v_mfma_f32_16x16x32_bf16 v[104:107], v[136:139], v[152:155], v[104:107]
	v_mfma_f32_16x16x32_bf16 v[92:95], v[128:131], v[160:163], v[92:95]
	v_mfma_f32_16x16x32_bf16 v[88:91], v[136:139], v[160:163], v[88:91]
	v_mfma_f32_16x16x32_bf16 v[76:79], v[128:131], v[168:171], v[76:79]
	v_mfma_f32_16x16x32_bf16 v[72:75], v[136:139], v[168:171], v[72:75]
	v_mfma_f32_16x16x32_bf16 v[124:127], v[132:135], v[148:151], v[124:127]
	v_mfma_f32_16x16x32_bf16 v[120:123], v[140:143], v[148:151], v[120:123]
	v_mfma_f32_16x16x32_bf16 v[108:111], v[132:135], v[156:159], v[108:111]
	v_mfma_f32_16x16x32_bf16 v[104:107], v[140:143], v[156:159], v[104:107]
	v_mfma_f32_16x16x32_bf16 v[92:95], v[132:135], v[164:167], v[92:95]
	v_mfma_f32_16x16x32_bf16 v[88:91], v[140:143], v[164:167], v[88:91]
	v_mfma_f32_16x16x32_bf16 v[76:79], v[132:135], v[172:175], v[76:79]
	v_mfma_f32_16x16x32_bf16 v[72:75], v[140:143], v[172:175], v[72:75]
	s_waitcnt lgkmcnt(0)
	v_mfma_f32_16x16x32_bf16 v[116:119], v[192:195], v[144:147], v[116:119]
	v_mfma_f32_16x16x32_bf16 v[112:115], v[200:203], v[144:147], v[112:115]
	v_mfma_f32_16x16x32_bf16 v[100:103], v[192:195], v[152:155], v[100:103]
	v_mfma_f32_16x16x32_bf16 v[96:99], v[200:203], v[152:155], v[96:99]
	v_mfma_f32_16x16x32_bf16 v[84:87], v[192:195], v[160:163], v[84:87]
	v_mfma_f32_16x16x32_bf16 v[80:83], v[200:203], v[160:163], v[80:83]
	v_mfma_f32_16x16x32_bf16 v[68:71], v[192:195], v[168:171], v[68:71]
	v_mfma_f32_16x16x32_bf16 v[64:67], v[200:203], v[168:171], v[64:67]
	v_mfma_f32_16x16x32_bf16 v[116:119], v[196:199], v[148:151], v[116:119]
	v_mfma_f32_16x16x32_bf16 v[112:115], v[204:207], v[148:151], v[112:115]
	v_mfma_f32_16x16x32_bf16 v[100:103], v[196:199], v[156:159], v[100:103]
	v_mfma_f32_16x16x32_bf16 v[96:99], v[204:207], v[156:159], v[96:99]
	v_mfma_f32_16x16x32_bf16 v[84:87], v[196:199], v[164:167], v[84:87]
	v_mfma_f32_16x16x32_bf16 v[80:83], v[204:207], v[164:167], v[80:83]
	v_mfma_f32_16x16x32_bf16 v[68:71], v[196:199], v[172:175], v[68:71]
	v_mfma_f32_16x16x32_bf16 v[64:67], v[204:207], v[172:175], v[64:67]
	s_barrier
	s_setprio 0
	s_add_i32 s55, s48, s35
	s_add_u32 s98, s24, 0x80
	s_addc_u32 s99, s25, 0
	s_add_u32 s100, s26, 0x80
	s_addc_u32 s101, s27, 0
	s_mov_b32 m0, s55
	s_nop 0
	global_load_lds_dwordx4 v180, s[24:25]
	s_add_i32 m0, s55, 0x2000
	s_nop 0
	global_load_lds_dwordx4 v176, s[24:25]
	s_mov_b32 m0, s37
	s_nop 0
	global_load_lds_dwordx4 v182, s[26:27]
	s_mov_b32 m0, s38
	s_nop 0
	global_load_lds_dwordx4 v178, s[26:27]
	ds_read_b128 v[144:147], v215 offset:16384
	ds_read_b128 v[148:151], v215 offset:17408
	ds_read_b128 v[152:155], v215 offset:18432
	ds_read_b128 v[156:159], v215 offset:19456
	ds_read_b128 v[160:163], v215 offset:20480
	ds_read_b128 v[164:167], v215 offset:21504
	ds_read_b128 v[168:171], v215 offset:22528
	ds_read_b128 v[172:175], v215 offset:23552
	s_add_u32 s56, s24, 0x80000
	s_addc_u32 s57, s25, 0
	s_add_i32 s55, s49, s35
	s_waitcnt vmcnt(6)
	s_waitcnt lgkmcnt(0)
	s_setprio 1
	s_barrier
	v_mfma_f32_16x16x32_bf16 v[60:63], v[128:131], v[144:147], v[60:63]
	s_mov_b32 m0, s55
	v_mfma_f32_16x16x32_bf16 v[56:59], v[136:139], v[144:147], v[56:59]
	global_load_lds_dwordx4 v180, s[56:57]
	v_mfma_f32_16x16x32_bf16 v[44:47], v[128:131], v[152:155], v[44:47]
	s_bitset1_b32 m0, 13
	v_mfma_f32_16x16x32_bf16 v[40:43], v[136:139], v[152:155], v[40:43]
	global_load_lds_dwordx4 v176, s[56:57]
	v_mfma_f32_16x16x32_bf16 v[28:31], v[128:131], v[160:163], v[28:31]
	v_mfma_f32_16x16x32_bf16 v[24:27], v[136:139], v[160:163], v[24:27]
	v_mfma_f32_16x16x32_bf16 v[12:15], v[128:131], v[168:171], v[12:15]
	v_mfma_f32_16x16x32_bf16 v[8:11], v[136:139], v[168:171], v[8:11]
	v_mfma_f32_16x16x32_bf16 v[60:63], v[132:135], v[148:151], v[60:63]
	v_mfma_f32_16x16x32_bf16 v[56:59], v[140:143], v[148:151], v[56:59]
	v_mfma_f32_16x16x32_bf16 v[44:47], v[132:135], v[156:159], v[44:47]
	v_mfma_f32_16x16x32_bf16 v[40:43], v[140:143], v[156:159], v[40:43]
	v_mfma_f32_16x16x32_bf16 v[28:31], v[132:135], v[164:167], v[28:31]
	v_mfma_f32_16x16x32_bf16 v[24:27], v[140:143], v[164:167], v[24:27]
	v_mfma_f32_16x16x32_bf16 v[12:15], v[132:135], v[172:175], v[12:15]
	v_mfma_f32_16x16x32_bf16 v[8:11], v[140:143], v[172:175], v[8:11]
	v_mfma_f32_16x16x32_bf16 v[52:55], v[192:195], v[144:147], v[52:55]
	v_mfma_f32_16x16x32_bf16 v[48:51], v[200:203], v[144:147], v[48:51]
	v_mfma_f32_16x16x32_bf16 v[36:39], v[192:195], v[152:155], v[36:39]
	v_mfma_f32_16x16x32_bf16 v[32:35], v[200:203], v[152:155], v[32:35]
	v_mfma_f32_16x16x32_bf16 v[20:23], v[192:195], v[160:163], v[20:23]
	v_mfma_f32_16x16x32_bf16 v[16:19], v[200:203], v[160:163], v[16:19]
	v_mfma_f32_16x16x32_bf16 v[4:7], v[192:195], v[168:171], v[4:7]
	v_mfma_f32_16x16x32_bf16 v[0:3], v[200:203], v[168:171], v[0:3]
	v_mfma_f32_16x16x32_bf16 v[52:55], v[196:199], v[148:151], v[52:55]
	v_mfma_f32_16x16x32_bf16 v[48:51], v[204:207], v[148:151], v[48:51]
	v_mfma_f32_16x16x32_bf16 v[36:39], v[196:199], v[156:159], v[36:39]
	v_mfma_f32_16x16x32_bf16 v[32:35], v[204:207], v[156:159], v[32:35]
	v_mfma_f32_16x16x32_bf16 v[20:23], v[196:199], v[164:167], v[20:23]
	v_mfma_f32_16x16x32_bf16 v[16:19], v[204:207], v[164:167], v[16:19]
	v_mfma_f32_16x16x32_bf16 v[4:7], v[196:199], v[172:175], v[4:7]
	v_mfma_f32_16x16x32_bf16 v[0:3], v[204:207], v[172:175], v[0:3]
	s_barrier
; #define PG8_STAGE(bufoff, gbase, voff) do { _Pragma("unroll") for (int _i = 0; _i < 2; ++_i) \
;     __builtin_amdgcn_global_load_lds((const unsigned*)((const char*)(gbase) + (voff)[_i]), (LAS unsigned*)(lds + (bufoff) + ldsw + _i * 8192), 16, 0, 0); } while (0)
; #define PG8_LDA(dst, b, h) do { _Pragma("unroll") for (int m = 0; m < 4; ++m) _Pragma("unroll") for (int k = 0; k < 2; ++k) dst[m][k] = *(const LAS bf16x8*)(lds + PG8_SA(b, h) + aoff + m * 2048 + k * 1024); } while (0)
; #define PG8_LDB(dst, b, h) do { _Pragma("unroll") for (int n = 0; n < 2; ++n) _Pragma("unroll") for (int k = 0; k < 2; ++k) dst[n][k] = *(const LAS bf16x8*)(lds + PG8_SB(b, h) + boff + n * 2048 + k * 1024); } while (0)
; #define PG8_MMA(ai, bj, At, Bt) do { __builtin_amdgcn_s_setprio(1); _Pragma("unroll") for (int m = 0; m < 4; ++m) _Pragma("unroll") for (int n = 0; n < 2; ++n) _Pragma("unroll") for (int k = 0; k < 2; ++k) \
;     acc[ai][bj][m][n] = __builtin_amdgcn_mfma_f32_16x16x32_bf16(Bt[n][k], At[m][k], acc[ai][bj][m][n], 0, 0, 0); __builtin_amdgcn_s_setprio(0); } while (0)
; #define PG8_WAIT_V(n) asm volatile("s_waitcnt vmcnt(" #n ")" ::: "memory")
; #define PG8_WAIT_L(n) asm volatile("s_waitcnt lgkmcnt(" #n ")" ::: "memory")
; #define PG8_BAR __builtin_amdgcn_s_barrier()
; #define PG8_SCHED __builtin_amdgcn_sched_barrier(0)
; template <class Epi, class Sched = StaticOrder>
; DI void gemm_phase(LAS unsigned char* lds, const Gemm g, const Sched& S, const Epi& E) {
;     ...
;       PG8_LDB(B0, 1, 0); PG8_SCHED; PG8_LDA(At, 1, 0); PG8_STAGE(PG8_SA(0, 1), a2 + hstep, voffA);
;       PG8_WAIT_L(8); PG8_BAR; PG8_WAIT_L(0); PG8_MMA(0, 0, At, B0); PG8_BAR; PG8_SCHED;
;       PG8_LDB(B1, 1, 1); PG8_STAGE(PG8_SB(1, 0), b3, voffB);
;       PG8_BAR; PG8_WAIT_L(0); PG8_MMA(0, 1, At, B1); PG8_BAR;
;       PG8_LDA(At, 1, 1); PG8_STAGE(PG8_SA(1, 0), a3, voffA);
;       PG8_BAR; PG8_WAIT_L(0); PG8_MMA(1, 0, At, B0); PG8_BAR; PG8_SCHED;
;       PG8_STAGE(PG8_SB(1, 1), b3 + hstep, voffB);
;       PG8_WAIT_V(6); PG8_BAR; PG8_MMA(1, 1, At, B1); PG8_BAR;
	s_setprio 0
	s_add_i32 s55, 0, 0x18000
	v_add_u32_e32 v140, s55, v212
	ds_read_b128 v[128:131], v140
	ds_read_b128 v[132:135], v140 offset:1024
	ds_read_b128 v[136:139], v140 offset:2048
	ds_read_b128 v[140:143], v140 offset:3072
	s_add_u32 s26, s26, 0x80000
	s_addc_u32 s27, s27, 0
	s_mov_b32 m0, s39
	ds_read_b128 v[144:147], v215 offset:32768
	ds_read_b128 v[148:151], v215 offset:33792
	ds_read_b128 v[152:155], v215 offset:34816
	ds_read_b128 v[156:159], v215 offset:35840
	ds_read_b128 v[160:163], v215 offset:36864
	ds_read_b128 v[164:167], v215 offset:37888
	ds_read_b128 v[168:171], v215 offset:38912
	ds_read_b128 v[172:175], v215 offset:39936
	global_load_lds_dwordx4 v182, s[26:27]
	s_mov_b32 m0, s40
	s_nop 0
	global_load_lds_dwordx4 v178, s[26:27]
	s_add_i32 s26, 0, 0x1c000
	v_add_u32_e32 v204, s26, v212
	ds_read_b128 v[192:195], v204
	ds_read_b128 v[196:199], v204 offset:1024
	ds_read_b128 v[200:203], v204 offset:2048
	ds_read_b128 v[204:207], v204 offset:3072
	s_waitcnt vmcnt(8)
	s_waitcnt lgkmcnt(4)
	s_setprio 1
	s_barrier
	v_mfma_f32_16x16x32_bf16 v[124:127], v[128:131], v[144:147], v[124:127]
	v_mfma_f32_16x16x32_bf16 v[120:123], v[136:139], v[144:147], v[120:123]
	v_mfma_f32_16x16x32_bf16 v[108:111], v[128:131], v[152:155], v[108:111]
	v_mfma_f32_16x16x32_bf16 v[104:107], v[136:139], v[152:155], v[104:107]
	v_mfma_f32_16x16x32_bf16 v[92:95], v[128:131], v[160:163], v[92:95]
	v_mfma_f32_16x16x32_bf16 v[88:91], v[136:139], v[160:163], v[88:91]
	v_mfma_f32_16x16x32_bf16 v[76:79], v[128:131], v[168:171], v[76:79]
	v_mfma_f32_16x16x32_bf16 v[72:75], v[136:139], v[168:171], v[72:75]
	v_mfma_f32_16x16x32_bf16 v[124:127], v[132:135], v[148:151], v[124:127]
	v_mfma_f32_16x16x32_bf16 v[120:123], v[140:143], v[148:151], v[120:123]
	v_mfma_f32_16x16x32_bf16 v[108:111], v[132:135], v[156:159], v[108:111]
	v_mfma_f32_16x16x32_bf16 v[104:107], v[140:143], v[156:159], v[104:107]
	v_mfma_f32_16x16x32_bf16 v[92:95], v[132:135], v[164:167], v[92:95]
	v_mfma_f32_16x16x32_bf16 v[88:91], v[140:143], v[164:167], v[88:91]
	v_mfma_f32_16x16x32_bf16 v[76:79], v[132:135], v[172:175], v[76:79]
	v_mfma_f32_16x16x32_bf16 v[72:75], v[140:143], v[172:175], v[72:75]
	s_waitcnt lgkmcnt(0)
	v_mfma_f32_16x16x32_bf16 v[116:119], v[192:195], v[144:147], v[116:119]
	v_mfma_f32_16x16x32_bf16 v[112:115], v[200:203], v[144:147], v[112:115]
	v_mfma_f32_16x16x32_bf16 v[100:103], v[192:195], v[152:155], v[100:103]
	v_mfma_f32_16x16x32_bf16 v[96:99], v[200:203], v[152:155], v[96:99]
	v_mfma_f32_16x16x32_bf16 v[84:87], v[192:195], v[160:163], v[84:87]
	v_mfma_f32_16x16x32_bf16 v[80:83], v[200:203], v[160:163], v[80:83]
	v_mfma_f32_16x16x32_bf16 v[68:71], v[192:195], v[168:171], v[68:71]
	v_mfma_f32_16x16x32_bf16 v[64:67], v[200:203], v[168:171], v[64:67]
	v_mfma_f32_16x16x32_bf16 v[116:119], v[196:199], v[148:151], v[116:119]
	v_mfma_f32_16x16x32_bf16 v[112:115], v[204:207], v[148:151], v[112:115]
	v_mfma_f32_16x16x32_bf16 v[100:103], v[196:199], v[156:159], v[100:103]
	v_mfma_f32_16x16x32_bf16 v[96:99], v[204:207], v[156:159], v[96:99]
	v_mfma_f32_16x16x32_bf16 v[84:87], v[196:199], v[164:167], v[84:87]
	v_mfma_f32_16x16x32_bf16 v[80:83], v[204:207], v[164:167], v[80:83]
	v_mfma_f32_16x16x32_bf16 v[68:71], v[196:199], v[172:175], v[68:71]
	v_mfma_f32_16x16x32_bf16 v[64:67], v[204:207], v[172:175], v[64:67]
	s_barrier
	s_setprio 0
	s_add_i32 s27, s55, s35
	s_mov_b32 m0, s27
	s_nop 0
	global_load_lds_dwordx4 v180, s[98:99]
	s_add_i32 m0, s27, 0x2000
	s_nop 0
	global_load_lds_dwordx4 v176, s[98:99]
	s_mov_b32 m0, s44
	s_nop 0
	global_load_lds_dwordx4 v182, s[100:101]
	s_mov_b32 m0, s45
	s_nop 0
	global_load_lds_dwordx4 v178, s[100:101]
	ds_read_b128 v[144:147], v215 offset:49152
	ds_read_b128 v[148:151], v215 offset:50176
	ds_read_b128 v[152:155], v215 offset:51200
	ds_read_b128 v[156:159], v215 offset:52224
	ds_read_b128 v[160:163], v215 offset:53248
	ds_read_b128 v[164:167], v215 offset:54272
	ds_read_b128 v[168:171], v215 offset:55296
	ds_read_b128 v[172:175], v215 offset:56320
	s_add_u32 s24, s24, 0x80080
	s_addc_u32 s25, s25, 0
	s_add_i32 s26, s26, s35
	s_add_i32 s54, s54, 2
	s_add_u32 s22, s22, 0x100
	s_addc_u32 s23, s23, 0
	s_add_u32 s52, s52, 0x100
	s_addc_u32 s53, s53, 0
	s_cmp_gt_u32 s54, 29
	s_waitcnt vmcnt(6)
	s_waitcnt lgkmcnt(0)
	s_setprio 1
	s_barrier
	v_mfma_f32_16x16x32_bf16 v[60:63], v[128:131], v[144:147], v[60:63]
	s_mov_b32 m0, s26
	v_mfma_f32_16x16x32_bf16 v[56:59], v[136:139], v[144:147], v[56:59]
	global_load_lds_dwordx4 v180, s[24:25]
	v_mfma_f32_16x16x32_bf16 v[44:47], v[128:131], v[152:155], v[44:47]
	s_bitset1_b32 m0, 13
	v_mfma_f32_16x16x32_bf16 v[40:43], v[136:139], v[152:155], v[40:43]
	global_load_lds_dwordx4 v176, s[24:25]
	v_mfma_f32_16x16x32_bf16 v[28:31], v[128:131], v[160:163], v[28:31]
	v_mfma_f32_16x16x32_bf16 v[24:27], v[136:139], v[160:163], v[24:27]
	v_mfma_f32_16x16x32_bf16 v[12:15], v[128:131], v[168:171], v[12:15]
	v_mfma_f32_16x16x32_bf16 v[8:11], v[136:139], v[168:171], v[8:11]
	v_mfma_f32_16x16x32_bf16 v[60:63], v[132:135], v[148:151], v[60:63]
	v_mfma_f32_16x16x32_bf16 v[56:59], v[140:143], v[148:151], v[56:59]
	v_mfma_f32_16x16x32_bf16 v[44:47], v[132:135], v[156:159], v[44:47]
	v_mfma_f32_16x16x32_bf16 v[40:43], v[140:143], v[156:159], v[40:43]
	v_mfma_f32_16x16x32_bf16 v[28:31], v[132:135], v[164:167], v[28:31]
	v_mfma_f32_16x16x32_bf16 v[24:27], v[140:143], v[164:167], v[24:27]
	v_mfma_f32_16x16x32_bf16 v[12:15], v[132:135], v[172:175], v[12:15]
	v_mfma_f32_16x16x32_bf16 v[8:11], v[140:143], v[172:175], v[8:11]
	v_mfma_f32_16x16x32_bf16 v[52:55], v[192:195], v[144:147], v[52:55]
	v_mfma_f32_16x16x32_bf16 v[48:51], v[200:203], v[144:147], v[48:51]
	v_mfma_f32_16x16x32_bf16 v[36:39], v[192:195], v[152:155], v[36:39]
	v_mfma_f32_16x16x32_bf16 v[32:35], v[200:203], v[152:155], v[32:35]
	v_mfma_f32_16x16x32_bf16 v[20:23], v[192:195], v[160:163], v[20:23]
	v_mfma_f32_16x16x32_bf16 v[16:19], v[200:203], v[160:163], v[16:19]
	v_mfma_f32_16x16x32_bf16 v[4:7], v[192:195], v[168:171], v[4:7]
	v_mfma_f32_16x16x32_bf16 v[0:3], v[200:203], v[168:171], v[0:3]
	v_mfma_f32_16x16x32_bf16 v[52:55], v[196:199], v[148:151], v[52:55]
	v_mfma_f32_16x16x32_bf16 v[48:51], v[204:207], v[148:151], v[48:51]
	v_mfma_f32_16x16x32_bf16 v[36:39], v[196:199], v[156:159], v[36:39]
	v_mfma_f32_16x16x32_bf16 v[32:35], v[204:207], v[156:159], v[32:35]
	v_mfma_f32_16x16x32_bf16 v[20:23], v[196:199], v[164:167], v[20:23]
	v_mfma_f32_16x16x32_bf16 v[16:19], v[204:207], v[164:167], v[16:19]
	v_mfma_f32_16x16x32_bf16 v[4:7], v[196:199], v[172:175], v[4:7]
	v_mfma_f32_16x16x32_bf16 v[0:3], v[204:207], v[172:175], v[0:3]
	s_barrier
; DI unsigned pack2(float lo, float hi) { f32x2 v = {lo, hi}; bf16v2 r = __builtin_convertvector(v, bf16v2); return __builtin_bit_cast(unsigned, r); }
;   DI void operator()(const f32x4 (&acc)[2][2][4][2], const Unit& u, int wr, int wc, int fr, int fq) const {
;     const int row0 = u.pm * BM + wr * 64 + fr, col0 = u.pn * BM + wc * 32 + 8 * fq;
; #pragma unroll
;     for (int ai = 0; ai < 2; ++ai) {
;       f32x4 bv[4][2][2];
; #pragma unroll
;       for (int m = 0; m < 4; ++m)
; #pragma unroll
;         for (int bj = 0; bj < 2; ++bj) {
;           const float* bp = base + (size_t)(row0 + ai * HALF + m * 16) * 2048 + col0 + bj * HALF;
;           bv[m][bj][0] = *(const f32x4*)bp; bv[m][bj][1] = *(const f32x4*)(bp + 4);
;         }
; #pragma unroll
;       for (int m = 0; m < 4; ++m) {
;         const int row = row0 + ai * HALF + m * 16;
;         const size_t off = (size_t)row * 2048 + col0;
;         float ss = 0.f;
; #pragma unroll
;         for (int bj = 0; bj < 2; ++bj) {
;           const f32x4 v0 = acc[ai][bj][m][0] + bv[m][bj][0], v1 = acc[ai][bj][m][1] + bv[m][bj][1];
;           *(f32x4*)(C + off + bj * HALF) = v0; *(f32x4*)(C + off + bj * HALF + 4) = v1;
;           if (xb) {
;             u32x4 w; w.x = pack2(v0[0], v0[1]); w.y = pack2(v0[2], v0[3]); w.z = pack2(v1[0], v1[1]); w.w = pack2(v1[2], v1[3]);
;             *(u32x4*)(xb + off + bj * HALF) = w;
;             ss += v0[0] * v0[0] + v0[1] * v0[1] + v0[2] * v0[2] + v0[3] * v0[3] + v1[0] * v1[0] + v1[1] * v1[1] + v1[2] * v1[2] + v1[3] * v1[3];
;           }
;         }
;         if (xb) {
;           ss += __shfl_xor(ss, 16); ss += __shfl_xor(ss, 32);
;           if (fq == 0) ssq[(size_t)row * 32 + u.pn * 4 + wc] = ss;
;         }
	s_setprio 0
	s_cbranch_scc0 .LBB0_1194
	v_lshl_add_u32 v194, s12, 8, v211
	v_lshl_or_b32 v192, s42, 8, v213
	v_readlane_b32 s52, v243, 3
	v_ashrrev_i32_e32 v193, 31, v192
	v_readlane_b32 s66, v243, 17
	v_readlane_b32 s67, v243, 18
	v_ashrrev_i32_e32 v195, 31, v194
	v_lshlrev_b64 v[128:129], 13, v[194:195]
	v_lshl_add_u64 v[196:197], v[192:193], 2, s[66:67]
	v_lshl_add_u64 v[236:237], v[196:197], 0, v[128:129]
	global_load_dwordx4 v[220:223], v[236:237], off
	global_load_dwordx4 v[224:227], v[236:237], off offset:16
	global_load_dwordx4 v[228:231], v[236:237], off offset:512
	global_load_dwordx4 v[232:235], v[236:237], off offset:528
	v_or_b32_e32 v206, 16, v194
	v_or_b32_e32 v202, 32, v194
	v_or_b32_e32 v198, 48, v194
	v_ashrrev_i32_e32 v207, 31, v206
	v_ashrrev_i32_e32 v203, 31, v202
	v_ashrrev_i32_e32 v199, 31, v198
	v_lshlrev_b64 v[128:129], 13, v[206:207]
	v_lshlrev_b64 v[130:131], 13, v[202:203]
	v_lshlrev_b64 v[132:133], 13, v[198:199]
	v_lshl_add_u64 v[208:209], v[196:197], 0, v[128:129]
	v_lshl_add_u64 v[204:205], v[196:197], 0, v[130:131]
	v_lshl_add_u64 v[200:201], v[196:197], 0, v[132:133]
	global_load_dwordx4 v[168:171], v[208:209], off offset:16
	global_load_dwordx4 v[172:175], v[208:209], off
	global_load_dwordx4 v[160:163], v[208:209], off offset:528
	global_load_dwordx4 v[164:167], v[208:209], off offset:512
	global_load_dwordx4 v[152:155], v[204:205], off offset:16
	global_load_dwordx4 v[156:159], v[204:205], off
	global_load_dwordx4 v[144:147], v[204:205], off offset:528
	global_load_dwordx4 v[148:151], v[204:205], off offset:512
	global_load_dwordx4 v[136:139], v[200:201], off offset:16
	global_load_dwordx4 v[140:143], v[200:201], off
	global_load_dwordx4 v[128:131], v[200:201], off offset:528
	global_load_dwordx4 v[132:135], v[200:201], off offset:512
	v_and_b32_e32 v218, 64, v217
	v_xor_b32_e32 v238, 16, v217
	v_add_u32_e32 v240, 64, v218
	v_xor_b32_e32 v239, 32, v217
	v_cmp_lt_i32_e32 vcc, v238, v240
	v_lshlrev_b64 v[218:219], 11, v[194:195]
	s_lshl_b32 s22, s42, 2
	v_cndmask_b32_e32 v241, v217, v238, vcc
	v_cmp_lt_i32_e32 vcc, v239, v240
	s_ashr_i32 s23, s22, 31
	v_readlane_b32 s53, v243, 4
	v_cndmask_b32_e32 v240, v217, v239, vcc
	v_lshl_add_u64 v[238:239], v[218:219], 0, v[192:193]
	v_lshlrev_b32_e32 v218, 2, v241
	v_lshl_add_u64 v[238:239], v[238:239], 1, s[2:3]
	v_readlane_b32 s54, v243, 5
	v_readlane_b32 s55, v243, 6
	v_readlane_b32 s56, v243, 7
	v_readlane_b32 s57, v243, 8
	v_readlane_b32 s58, v243, 9
	v_readlane_b32 s59, v243, 10
	v_readlane_b32 s60, v243, 11
	v_readlane_b32 s61, v243, 12
	v_readlane_b32 s62, v243, 13
	v_readlane_b32 s63, v243, 14
	v_readlane_b32 s64, v243, 15
	v_readlane_b32 s65, v243, 16
	s_waitcnt vmcnt(0)
	v_pk_add_f32 v[126:127], v[126:127], v[222:223]
	v_pk_add_f32 v[124:125], v[124:125], v[220:221]
	v_pk_add_f32 v[116:117], v[116:117], v[228:229]
	v_pk_add_f32 v[122:123], v[122:123], v[226:227]
	v_pk_add_f32 v[120:121], v[120:121], v[224:225]
	v_pk_add_f32 v[220:221], v[112:113], v[232:233]
	global_store_dwordx4 v[236:237], v[124:127], off
	global_store_dwordx4 v[236:237], v[120:123], off offset:16
	v_cvt_pk_bf16_f32 v112, v124, v125
	v_mul_f32_e32 v125, v125, v125
	v_mul_f32_e32 v219, v117, v117
	v_pk_add_f32 v[118:119], v[118:119], v[230:231]
	v_fmac_f32_e32 v125, v124, v124
	v_fmac_f32_e32 v219, v116, v116
	v_fmac_f32_e32 v125, v126, v126
	v_fmac_f32_e32 v219, v118, v118
	v_fmac_f32_e32 v125, v127, v127
	v_fmac_f32_e32 v219, v119, v119
	v_fmac_f32_e32 v125, v120, v120
	v_fmac_f32_e32 v219, v220, v220
	v_pk_add_f32 v[222:223], v[114:115], v[234:235]
	v_fmac_f32_e32 v125, v121, v121
	v_fmac_f32_e32 v219, v221, v221
	v_fmac_f32_e32 v125, v122, v122
	v_fmac_f32_e32 v219, v222, v222
	v_fmac_f32_e32 v125, v123, v123
	v_fmac_f32_e32 v219, v223, v223
	v_cvt_pk_bf16_f32 v114, v120, v121
	v_add_f32_e32 v121, v125, v219
	v_cvt_pk_bf16_f32 v115, v122, v123
	ds_bpermute_b32 v122, v218, v121
	v_cvt_pk_bf16_f32 v113, v126, v127
	global_store_dwordx4 v[238:239], v[112:115], off
	global_store_dwordx4 v[236:237], v[116:119], off offset:512
	global_store_dwordx4 v[236:237], v[220:223], off offset:528
	v_lshlrev_b32_e32 v126, 2, v240
	v_cvt_pk_bf16_f32 v120, v116, v117
	s_waitcnt lgkmcnt(0)
	v_add_f32_e32 v112, v121, v122
	ds_bpermute_b32 v113, v126, v112
	v_cvt_pk_bf16_f32 v121, v118, v119
	v_cvt_pk_bf16_f32 v122, v220, v221
	v_cvt_pk_bf16_f32 v123, v222, v223
	global_store_dwordx4 v[238:239], v[120:123], off offset:256
	s_and_saveexec_b64 s[24:25], s[0:1]
	s_cbranch_execz .LBB0_1197
	s_waitcnt lgkmcnt(0)
	v_add_f32_e32 v114, v112, v113
	v_lshlrev_b64 v[112:113], 7, v[194:195]
	v_lshl_add_u64 v[112:113], s[8:9], 0, v[112:113]
	v_lshl_add_u64 v[112:113], s[22:23], 2, v[112:113]
	s_lshl_b32 s12, s41, 2
	v_lshl_add_u64 v[112:113], v[112:113], 0, s[12:13]
	global_store_dword v[112:113], v114, off

; #define PG8_STAGE(bufoff, gbase, voff) do { _Pragma("unroll") for (int _i = 0; _i < 2; ++_i) \
;     __builtin_amdgcn_global_load_lds((const unsigned*)((const char*)(gbase) + (voff)[_i]), (LAS unsigned*)(lds + (bufoff) + ldsw + _i * 8192), 16, 0, 0); } while (0)
; #define PG8_LDA(dst, b, h) do { _Pragma("unroll") for (int m = 0; m < 4; ++m) _Pragma("unroll") for (int k = 0; k < 2; ++k) dst[m][k] = *(const LAS bf16x8*)(lds + PG8_SA(b, h) + aoff + m * 2048 + k * 1024); } while (0)
; #define PG8_LDB(dst, b, h) do { _Pragma("unroll") for (int n = 0; n < 2; ++n) _Pragma("unroll") for (int k = 0; k < 2; ++k) dst[n][k] = *(const LAS bf16x8*)(lds + PG8_SB(b, h) + boff + n * 2048 + k * 1024); } while (0)
; #define PG8_MMA(ai, bj, At, Bt) do { __builtin_amdgcn_s_setprio(1); _Pragma("unroll") for (int m = 0; m < 4; ++m) _Pragma("unroll") for (int n = 0; n < 2; ++n) _Pragma("unroll") for (int k = 0; k < 2; ++k) \
;     acc[ai][bj][m][n] = __builtin_amdgcn_mfma_f32_16x16x32_bf16(Bt[n][k], At[m][k], acc[ai][bj][m][n], 0, 0, 0); __builtin_amdgcn_s_setprio(0); } while (0)
; #define PG8_WAIT_V(n) asm volatile("s_waitcnt vmcnt(" #n ")" ::: "memory")
; #define PG8_WAIT_L(n) asm volatile("s_waitcnt lgkmcnt(" #n ")" ::: "memory")
; #define PG8_BAR __builtin_amdgcn_s_barrier()
; #define PG8_SCHED __builtin_amdgcn_sched_barrier(0)
; template <class Epi, class Sched = StaticOrder>
; DI void gemm_phase(LAS unsigned char* lds, const Gemm g, const Sched& S, const Epi& E) {
;     ...
;       PG8_LDB(B0, 0, 0); PG8_SCHED; PG8_LDA(At, 0, 0); PG8_STAGE(PG8_SA(1, 1), a1 + hstep, voffA);
;       PG8_WAIT_L(8); PG8_BAR; PG8_WAIT_L(0); PG8_MMA(0, 0, At, B0); PG8_BAR; PG8_SCHED;
;       PG8_LDB(B1, 0, 1); PG8_STAGE(PG8_SB(0, 0), b2, voffB);
;       PG8_BAR; PG8_WAIT_L(0); PG8_MMA(0, 1, At, B1); PG8_BAR;
;       PG8_LDA(At, 0, 1); PG8_STAGE(PG8_SA(0, 0), a2, voffA);
;       PG8_BAR; PG8_WAIT_L(0); PG8_MMA(1, 0, At, B0); PG8_BAR; PG8_SCHED;
;       PG8_STAGE(PG8_SB(0, 1), b2 + hstep, voffB);
;       PG8_WAIT_V(6); PG8_BAR; PG8_MMA(1, 1, At, B1); PG8_BAR;
.LBB0_1277:
	ds_read_b128 v[64:67], v201
	ds_read_b128 v[68:71], v201 offset:1024
	ds_read_b128 v[72:75], v201 offset:2048
	ds_read_b128 v[76:79], v201 offset:3072
	s_add_u32 s48, s14, 0xfff80080
	s_addc_u32 s49, s15, -1
	s_cmp_eq_u32 s58, 28
	s_cselect_b32 s51, s41, s49
	s_cselect_b32 s50, s42, s48
	s_cselect_b32 s49, s39, s53
	s_cselect_b32 s48, s43, s52
	s_add_i32 m0, s64, 0xc000
	ds_read_b128 v[80:83], v202
	ds_read_b128 v[84:87], v202 offset:1024
	ds_read_b128 v[88:91], v202 offset:2048
	ds_read_b128 v[92:95], v202 offset:3072
	ds_read_b128 v[180:183], v202 offset:4096
	ds_read_b128 v[184:187], v202 offset:5120
	ds_read_b128 v[188:191], v202 offset:6144
	ds_read_b128 v[192:195], v202 offset:7168
	global_load_lds_dwordx4 v170, s[14:15]
	s_add_i32 m0, s64, 0xe000
	s_nop 0
	global_load_lds_dwordx4 v172, s[14:15]
	ds_read_b128 v[206:209], v203
	ds_read_b128 v[212:215], v203 offset:1024
	ds_read_b128 v[216:219], v203 offset:2048
	ds_read_b128 v[220:223], v203 offset:3072
	s_waitcnt vmcnt(8)
	s_waitcnt lgkmcnt(4)
	s_setprio 1
	s_barrier
	v_mfma_f32_16x16x32_bf16 v[156:159], v[64:67], v[80:83], v[156:159]
	v_mfma_f32_16x16x32_bf16 v[144:147], v[72:75], v[80:83], v[144:147]
	v_mfma_f32_16x16x32_bf16 v[140:143], v[64:67], v[88:91], v[140:143]
	v_mfma_f32_16x16x32_bf16 v[132:135], v[72:75], v[88:91], v[132:135]
	v_mfma_f32_16x16x32_bf16 v[124:127], v[64:67], v[180:183], v[124:127]
	v_mfma_f32_16x16x32_bf16 v[116:119], v[72:75], v[180:183], v[116:119]
	v_mfma_f32_16x16x32_bf16 v[112:115], v[64:67], v[188:191], v[112:115]
	v_mfma_f32_16x16x32_bf16 v[108:111], v[72:75], v[188:191], v[108:111]
	v_mfma_f32_16x16x32_bf16 v[156:159], v[68:71], v[84:87], v[156:159]
	v_mfma_f32_16x16x32_bf16 v[144:147], v[76:79], v[84:87], v[144:147]
	v_mfma_f32_16x16x32_bf16 v[140:143], v[68:71], v[92:95], v[140:143]
	v_mfma_f32_16x16x32_bf16 v[132:135], v[76:79], v[92:95], v[132:135]
	v_mfma_f32_16x16x32_bf16 v[124:127], v[68:71], v[184:187], v[124:127]
	v_mfma_f32_16x16x32_bf16 v[116:119], v[76:79], v[184:187], v[116:119]
	v_mfma_f32_16x16x32_bf16 v[112:115], v[68:71], v[192:195], v[112:115]
	v_mfma_f32_16x16x32_bf16 v[108:111], v[76:79], v[192:195], v[108:111]
	s_waitcnt lgkmcnt(0)
	v_mfma_f32_16x16x32_bf16 v[152:155], v[206:209], v[80:83], v[152:155]
	v_mfma_f32_16x16x32_bf16 v[80:83], v[216:219], v[80:83], v[148:151]
	v_mfma_f32_16x16x32_bf16 v[152:155], v[212:215], v[84:87], v[152:155]
	v_mfma_f32_16x16x32_bf16 v[80:83], v[220:223], v[84:87], v[80:83]
	v_mfma_f32_16x16x32_bf16 v[84:87], v[206:209], v[88:91], v[136:139]
	v_mfma_f32_16x16x32_bf16 v[88:91], v[216:219], v[88:91], v[128:131]
	v_mfma_f32_16x16x32_bf16 v[104:107], v[216:219], v[180:183], v[104:107]
	v_mfma_f32_16x16x32_bf16 v[100:103], v[206:209], v[188:191], v[100:103]
	v_mfma_f32_16x16x32_bf16 v[96:99], v[216:219], v[188:191], v[96:99]
	v_mfma_f32_16x16x32_bf16 v[84:87], v[212:215], v[92:95], v[84:87]
	v_mfma_f32_16x16x32_bf16 v[88:91], v[220:223], v[92:95], v[88:91]
	v_mfma_f32_16x16x32_bf16 v[92:95], v[206:209], v[180:183], v[120:123]
	v_mfma_f32_16x16x32_bf16 v[104:107], v[220:223], v[184:187], v[104:107]
	v_mfma_f32_16x16x32_bf16 v[100:103], v[212:215], v[192:195], v[100:103]
	v_mfma_f32_16x16x32_bf16 v[96:99], v[220:223], v[192:195], v[96:99]
	v_mfma_f32_16x16x32_bf16 v[92:95], v[212:215], v[184:187], v[92:95]
	s_barrier
	s_setprio 0
	s_add_i32 s59, s72, s62
	s_add_u32 s98, s48, 0x80
	s_addc_u32 s99, s49, 0
	s_add_u32 s100, s50, 0x80
	s_addc_u32 s101, s51, 0
	s_mov_b32 m0, s59
	s_nop 0
	global_load_lds_dwordx4 v164, s[48:49]
	s_add_i32 m0, s59, 0x2000
	s_nop 0
	global_load_lds_dwordx4 v160, s[48:49]
	s_mov_b32 m0, s64
	s_nop 0
	global_load_lds_dwordx4 v166, s[50:51]
	s_mov_b32 m0, s65
	s_nop 0
	global_load_lds_dwordx4 v162, s[50:51]
	ds_read_b128 v[120:123], v202 offset:16384
	ds_read_b128 v[128:131], v202 offset:17408
	ds_read_b128 v[136:139], v202 offset:18432
	ds_read_b128 v[148:151], v202 offset:19456
	ds_read_b128 v[180:183], v202 offset:20480
	ds_read_b128 v[184:187], v202 offset:21504
	ds_read_b128 v[188:191], v202 offset:22528
	ds_read_b128 v[192:195], v202 offset:23552
	s_add_u32 s78, s48, 0x80000
	s_addc_u32 s79, s49, 0
	s_add_i32 s59, s73, s62
	s_waitcnt vmcnt(6)
	s_waitcnt lgkmcnt(0)
	s_setprio 1
	s_barrier
	v_mfma_f32_16x16x32_bf16 v[60:63], v[64:67], v[120:123], v[60:63]
	s_mov_b32 m0, s59
	v_mfma_f32_16x16x32_bf16 v[48:51], v[72:75], v[120:123], v[48:51]
	global_load_lds_dwordx4 v164, s[78:79]
	v_mfma_f32_16x16x32_bf16 v[44:47], v[64:67], v[136:139], v[44:47]
	s_bitset1_b32 m0, 13
	v_mfma_f32_16x16x32_bf16 v[36:39], v[72:75], v[136:139], v[36:39]
	global_load_lds_dwordx4 v160, s[78:79]
	v_mfma_f32_16x16x32_bf16 v[28:31], v[64:67], v[180:183], v[28:31]
	v_mfma_f32_16x16x32_bf16 v[20:23], v[72:75], v[180:183], v[20:23]
	v_mfma_f32_16x16x32_bf16 v[16:19], v[64:67], v[188:191], v[16:19]
	v_mfma_f32_16x16x32_bf16 v[12:15], v[72:75], v[188:191], v[12:15]
	v_mfma_f32_16x16x32_bf16 v[60:63], v[68:71], v[128:131], v[60:63]
	v_mfma_f32_16x16x32_bf16 v[48:51], v[76:79], v[128:131], v[48:51]
	v_mfma_f32_16x16x32_bf16 v[44:47], v[68:71], v[148:151], v[44:47]
	v_mfma_f32_16x16x32_bf16 v[36:39], v[76:79], v[148:151], v[36:39]
	v_mfma_f32_16x16x32_bf16 v[28:31], v[68:71], v[184:187], v[28:31]
	v_mfma_f32_16x16x32_bf16 v[20:23], v[76:79], v[184:187], v[20:23]
	v_mfma_f32_16x16x32_bf16 v[16:19], v[68:71], v[192:195], v[16:19]
	v_mfma_f32_16x16x32_bf16 v[12:15], v[76:79], v[192:195], v[12:15]
	v_mfma_f32_16x16x32_bf16 v[56:59], v[206:209], v[120:123], v[56:59]
	v_mfma_f32_16x16x32_bf16 v[52:55], v[216:219], v[120:123], v[52:55]
	v_mfma_f32_16x16x32_bf16 v[40:43], v[206:209], v[136:139], v[40:43]
	v_mfma_f32_16x16x32_bf16 v[32:35], v[216:219], v[136:139], v[32:35]
	v_mfma_f32_16x16x32_bf16 v[24:27], v[206:209], v[180:183], v[24:27]
	v_mfma_f32_16x16x32_bf16 v[8:11], v[216:219], v[180:183], v[8:11]
	v_mfma_f32_16x16x32_bf16 v[4:7], v[206:209], v[188:191], v[4:7]
	v_mfma_f32_16x16x32_bf16 v[0:3], v[216:219], v[188:191], v[0:3]
	v_mfma_f32_16x16x32_bf16 v[56:59], v[212:215], v[128:131], v[56:59]
	v_mfma_f32_16x16x32_bf16 v[52:55], v[220:223], v[128:131], v[52:55]
	v_mfma_f32_16x16x32_bf16 v[40:43], v[212:215], v[148:151], v[40:43]
	v_mfma_f32_16x16x32_bf16 v[32:35], v[220:223], v[148:151], v[32:35]
	v_mfma_f32_16x16x32_bf16 v[24:27], v[212:215], v[184:187], v[24:27]
	v_mfma_f32_16x16x32_bf16 v[8:11], v[220:223], v[184:187], v[8:11]
	v_mfma_f32_16x16x32_bf16 v[4:7], v[212:215], v[192:195], v[4:7]
	v_mfma_f32_16x16x32_bf16 v[0:3], v[220:223], v[192:195], v[0:3]
	s_barrier
; #define PG8_STAGE(bufoff, gbase, voff) do { _Pragma("unroll") for (int _i = 0; _i < 2; ++_i) \
;     __builtin_amdgcn_global_load_lds((const unsigned*)((const char*)(gbase) + (voff)[_i]), (LAS unsigned*)(lds + (bufoff) + ldsw + _i * 8192), 16, 0, 0); } while (0)
; #define PG8_LDA(dst, b, h) do { _Pragma("unroll") for (int m = 0; m < 4; ++m) _Pragma("unroll") for (int k = 0; k < 2; ++k) dst[m][k] = *(const LAS bf16x8*)(lds + PG8_SA(b, h) + aoff + m * 2048 + k * 1024); } while (0)
; #define PG8_LDB(dst, b, h) do { _Pragma("unroll") for (int n = 0; n < 2; ++n) _Pragma("unroll") for (int k = 0; k < 2; ++k) dst[n][k] = *(const LAS bf16x8*)(lds + PG8_SB(b, h) + boff + n * 2048 + k * 1024); } while (0)
; #define PG8_MMA(ai, bj, At, Bt) do { __builtin_amdgcn_s_setprio(1); _Pragma("unroll") for (int m = 0; m < 4; ++m) _Pragma("unroll") for (int n = 0; n < 2; ++n) _Pragma("unroll") for (int k = 0; k < 2; ++k) \
;     acc[ai][bj][m][n] = __builtin_amdgcn_mfma_f32_16x16x32_bf16(Bt[n][k], At[m][k], acc[ai][bj][m][n], 0, 0, 0); __builtin_amdgcn_s_setprio(0); } while (0)
; #define PG8_WAIT_V(n) asm volatile("s_waitcnt vmcnt(" #n ")" ::: "memory")
; #define PG8_WAIT_L(n) asm volatile("s_waitcnt lgkmcnt(" #n ")" ::: "memory")
; #define PG8_BAR __builtin_amdgcn_s_barrier()
; #define PG8_SCHED __builtin_amdgcn_sched_barrier(0)
; template <class Epi, class Sched = StaticOrder>
; DI void gemm_phase(LAS unsigned char* lds, const Gemm g, const Sched& S, const Epi& E) {
;     ...
;       PG8_LDB(B0, 1, 0); PG8_SCHED; PG8_LDA(At, 1, 0); PG8_STAGE(PG8_SA(0, 1), a2 + hstep, voffA);
;       PG8_WAIT_L(8); PG8_BAR; PG8_WAIT_L(0); PG8_MMA(0, 0, At, B0); PG8_BAR; PG8_SCHED;
;       PG8_LDB(B1, 1, 1); PG8_STAGE(PG8_SB(1, 0), b3, voffB);
;       PG8_BAR; PG8_WAIT_L(0); PG8_MMA(0, 1, At, B1); PG8_BAR;
;       PG8_LDA(At, 1, 1); PG8_STAGE(PG8_SA(1, 0), a3, voffA);
;       PG8_BAR; PG8_WAIT_L(0); PG8_MMA(1, 0, At, B0); PG8_BAR; PG8_SCHED;
;       PG8_STAGE(PG8_SB(1, 1), b3 + hstep, voffB);
;       PG8_WAIT_V(6); PG8_BAR; PG8_MMA(1, 1, At, B1); PG8_BAR;
	s_setprio 0
	s_add_i32 s59, 0, 0x18000
	v_add_u32_e32 v76, s59, v198
	ds_read_b128 v[64:67], v76
	ds_read_b128 v[68:71], v76 offset:1024
	ds_read_b128 v[72:75], v76 offset:2048
	ds_read_b128 v[76:79], v76 offset:3072
	s_add_u32 s50, s50, 0x80000
	s_addc_u32 s51, s51, 0
	s_mov_b32 m0, s66
	ds_read_b128 v[120:123], v202 offset:32768
	ds_read_b128 v[128:131], v202 offset:33792
	ds_read_b128 v[180:183], v202 offset:34816
	ds_read_b128 v[184:187], v202 offset:35840
	ds_read_b128 v[188:191], v202 offset:36864
	ds_read_b128 v[192:195], v202 offset:37888
	ds_read_b128 v[206:209], v202 offset:38912
	ds_read_b128 v[212:215], v202 offset:39936
	global_load_lds_dwordx4 v166, s[50:51]
	s_mov_b32 m0, s67
	s_nop 0
	global_load_lds_dwordx4 v162, s[50:51]
	s_add_i32 s50, 0, 0x1c000
	v_add_u32_e32 v244, s50, v198
	ds_read_b128 v[216:219], v244
	ds_read_b128 v[220:223], v244 offset:1024
	ds_read_b128 v[224:227], v244 offset:2048
	ds_read_b128 v[228:231], v244 offset:3072
	s_waitcnt vmcnt(8)
	s_waitcnt lgkmcnt(4)
	s_setprio 1
	s_barrier
	v_mfma_f32_16x16x32_bf16 v[136:139], v[64:67], v[120:123], v[156:159]
	v_mfma_f32_16x16x32_bf16 v[156:159], v[68:71], v[128:131], v[136:139]
	v_mfma_f32_16x16x32_bf16 v[136:139], v[72:75], v[120:123], v[144:147]
	v_mfma_f32_16x16x32_bf16 v[144:147], v[76:79], v[128:131], v[136:139]
	v_mfma_f32_16x16x32_bf16 v[136:139], v[64:67], v[180:183], v[140:143]
	v_mfma_f32_16x16x32_bf16 v[132:135], v[72:75], v[180:183], v[132:135]
	v_mfma_f32_16x16x32_bf16 v[124:127], v[64:67], v[188:191], v[124:127]
	v_mfma_f32_16x16x32_bf16 v[116:119], v[72:75], v[188:191], v[116:119]
	v_mfma_f32_16x16x32_bf16 v[112:115], v[64:67], v[206:209], v[112:115]
	v_mfma_f32_16x16x32_bf16 v[108:111], v[72:75], v[206:209], v[108:111]
	v_mfma_f32_16x16x32_bf16 v[140:143], v[68:71], v[184:187], v[136:139]
	v_mfma_f32_16x16x32_bf16 v[132:135], v[76:79], v[184:187], v[132:135]
	v_mfma_f32_16x16x32_bf16 v[124:127], v[68:71], v[192:195], v[124:127]
	v_mfma_f32_16x16x32_bf16 v[116:119], v[76:79], v[192:195], v[116:119]
	v_mfma_f32_16x16x32_bf16 v[112:115], v[68:71], v[212:215], v[112:115]
	v_mfma_f32_16x16x32_bf16 v[108:111], v[76:79], v[212:215], v[108:111]
	s_waitcnt lgkmcnt(0)
	v_mfma_f32_16x16x32_bf16 v[80:83], v[224:227], v[120:123], v[80:83]
	v_mfma_f32_16x16x32_bf16 v[136:139], v[216:219], v[120:123], v[152:155]
	v_mfma_f32_16x16x32_bf16 v[148:151], v[228:231], v[128:131], v[80:83]
	v_mfma_f32_16x16x32_bf16 v[80:83], v[216:219], v[180:183], v[84:87]
	v_mfma_f32_16x16x32_bf16 v[152:155], v[220:223], v[128:131], v[136:139]
	v_mfma_f32_16x16x32_bf16 v[136:139], v[220:223], v[184:187], v[80:83]
	v_mfma_f32_16x16x32_bf16 v[80:83], v[224:227], v[180:183], v[88:91]
	v_mfma_f32_16x16x32_bf16 v[128:131], v[228:231], v[184:187], v[80:83]
	v_mfma_f32_16x16x32_bf16 v[80:83], v[216:219], v[188:191], v[92:95]
	v_mfma_f32_16x16x32_bf16 v[120:123], v[220:223], v[192:195], v[80:83]
	v_mfma_f32_16x16x32_bf16 v[80:83], v[224:227], v[188:191], v[104:107]
	v_mfma_f32_16x16x32_bf16 v[104:107], v[228:231], v[192:195], v[80:83]
	v_mfma_f32_16x16x32_bf16 v[80:83], v[216:219], v[206:209], v[100:103]
	v_mfma_f32_16x16x32_bf16 v[100:103], v[220:223], v[212:215], v[80:83]
	v_mfma_f32_16x16x32_bf16 v[80:83], v[224:227], v[206:209], v[96:99]
	v_mfma_f32_16x16x32_bf16 v[96:99], v[228:231], v[212:215], v[80:83]
	s_barrier
	s_setprio 0
	s_add_i32 s51, s59, s62
	s_mov_b32 m0, s51
	s_nop 0
	global_load_lds_dwordx4 v164, s[98:99]
	s_add_i32 m0, s51, 0x2000
	s_nop 0
	global_load_lds_dwordx4 v160, s[98:99]
	s_mov_b32 m0, s55
	s_nop 0
	global_load_lds_dwordx4 v166, s[100:101]
	s_mov_b32 m0, s68
	s_nop 0
	global_load_lds_dwordx4 v162, s[100:101]
	s_nop 2
	ds_read_b128 v[80:83], v202 offset:49152
	ds_read_b128 v[84:87], v202 offset:50176
	ds_read_b128 v[88:91], v202 offset:51200
	ds_read_b128 v[92:95], v202 offset:52224
	ds_read_b128 v[180:183], v202 offset:53248
	ds_read_b128 v[184:187], v202 offset:54272
	ds_read_b128 v[188:191], v202 offset:55296
	ds_read_b128 v[192:195], v202 offset:56320
	s_add_u32 s48, s48, 0x80080
	s_addc_u32 s49, s49, 0
	s_add_i32 s50, s50, s62
	s_add_i32 s58, s58, 2
	s_add_u32 s14, s14, 0x100
	s_addc_u32 s15, s15, 0
	s_add_u32 s52, s52, 0x100
	s_addc_u32 s53, s53, 0
	s_cmp_gt_u32 s58, 29
	s_waitcnt vmcnt(6)
	s_waitcnt lgkmcnt(0)
	s_setprio 1
	s_barrier
	v_mfma_f32_16x16x32_bf16 v[60:63], v[64:67], v[80:83], v[60:63]
	s_mov_b32 m0, s50
	v_mfma_f32_16x16x32_bf16 v[48:51], v[72:75], v[80:83], v[48:51]
	global_load_lds_dwordx4 v164, s[48:49]
	v_mfma_f32_16x16x32_bf16 v[44:47], v[64:67], v[88:91], v[44:47]
	s_bitset1_b32 m0, 13
	v_mfma_f32_16x16x32_bf16 v[36:39], v[72:75], v[88:91], v[36:39]
	global_load_lds_dwordx4 v160, s[48:49]
	v_mfma_f32_16x16x32_bf16 v[28:31], v[64:67], v[180:183], v[28:31]
	v_mfma_f32_16x16x32_bf16 v[20:23], v[72:75], v[180:183], v[20:23]
	v_mfma_f32_16x16x32_bf16 v[16:19], v[64:67], v[188:191], v[16:19]
	v_mfma_f32_16x16x32_bf16 v[12:15], v[72:75], v[188:191], v[12:15]
	v_mfma_f32_16x16x32_bf16 v[60:63], v[68:71], v[84:87], v[60:63]
	v_mfma_f32_16x16x32_bf16 v[48:51], v[76:79], v[84:87], v[48:51]
	v_mfma_f32_16x16x32_bf16 v[44:47], v[68:71], v[92:95], v[44:47]
	v_mfma_f32_16x16x32_bf16 v[36:39], v[76:79], v[92:95], v[36:39]
	v_mfma_f32_16x16x32_bf16 v[28:31], v[68:71], v[184:187], v[28:31]
	v_mfma_f32_16x16x32_bf16 v[20:23], v[76:79], v[184:187], v[20:23]
	v_mfma_f32_16x16x32_bf16 v[16:19], v[68:71], v[192:195], v[16:19]
	v_mfma_f32_16x16x32_bf16 v[12:15], v[76:79], v[192:195], v[12:15]
	v_mfma_f32_16x16x32_bf16 v[56:59], v[216:219], v[80:83], v[56:59]
	v_mfma_f32_16x16x32_bf16 v[52:55], v[224:227], v[80:83], v[52:55]
	v_mfma_f32_16x16x32_bf16 v[40:43], v[216:219], v[88:91], v[40:43]
	v_mfma_f32_16x16x32_bf16 v[32:35], v[224:227], v[88:91], v[32:35]
	v_mfma_f32_16x16x32_bf16 v[24:27], v[216:219], v[180:183], v[24:27]
	v_mfma_f32_16x16x32_bf16 v[8:11], v[224:227], v[180:183], v[8:11]
	v_mfma_f32_16x16x32_bf16 v[4:7], v[216:219], v[188:191], v[4:7]
	v_mfma_f32_16x16x32_bf16 v[0:3], v[224:227], v[188:191], v[0:3]
	v_mfma_f32_16x16x32_bf16 v[56:59], v[220:223], v[84:87], v[56:59]
	v_mfma_f32_16x16x32_bf16 v[52:55], v[228:231], v[84:87], v[52:55]
	v_mfma_f32_16x16x32_bf16 v[40:43], v[220:223], v[92:95], v[40:43]
	v_mfma_f32_16x16x32_bf16 v[32:35], v[228:231], v[92:95], v[32:35]
	v_mfma_f32_16x16x32_bf16 v[24:27], v[220:223], v[184:187], v[24:27]
	v_mfma_f32_16x16x32_bf16 v[8:11], v[228:231], v[184:187], v[8:11]
	v_mfma_f32_16x16x32_bf16 v[4:7], v[220:223], v[192:195], v[4:7]
	v_mfma_f32_16x16x32_bf16 v[0:3], v[228:231], v[192:195], v[0:3]
	s_barrier
; DI float dpp_ror1(float v) { return __int_as_float(__builtin_amdgcn_update_dpp(0, __float_as_int(v), 0x121, 0xf, 0xf, false)); }
; DI float dpp_ror2(float v) { return __int_as_float(__builtin_amdgcn_update_dpp(0, __float_as_int(v), 0x122, 0xf, 0xf, false)); }
; DI float row_rstd(const float* ssq, int row, int fq) {
;   const f32x4 a = *(const f32x4*)(ssq + (size_t)row * 32 + fq * 8), b = *(const f32x4*)(ssq + (size_t)row * 32 + fq * 8 + 4);
;   float sm = ((a[0] + a[1]) + (a[2] + a[3])) + ((b[0] + b[1]) + (b[2] + b[3]));
;   sm += __shfl_xor(sm, 16); sm += __shfl_xor(sm, 32);
;   return rsqrtf(sm * (1.0f / 2048.f) + 1e-6f);
;   DI void operator()(const f32x4 (&acc)[2][2][4][2], const Unit& u, int wr, int wc, int fr, int fq) const {
;     const int col = u.pn * 128 + wc * 32 + 8 * fq;
;     float w0[8], w1[8], w2[8], bb[8];
; #pragma unroll
;     for (int e = 0; e < 8; ++e) { w0[e] = cw[col + e]; w1[e] = cw[5632 + col + e]; w2[e] = cw[2 * 5632 + col + e]; bb[e] = cb[col + e]; }
; #pragma unroll
;     for (int ai = 0; ai < 2; ++ai) {
;       const int row0 = u.pm * BM + ai * HALF + wr * 64, span = row0 >> 6;
;       float rsv[4];
; #pragma unroll
;       for (int m = 0; m < 4; ++m) rsv[m] = row_rstd(ssq, row0 + 16 * m + fr, fq);
;       float p1[8], p2[8];
; #pragma unroll
;       for (int e = 0; e < 8; ++e) { p1[e] = 0.f; p2[e] = 0.f; }
; #pragma unroll
;       for (int m = 0; m < 4; ++m) {
;         float g[8], uu[8], a[8];
;         const float rs = rsv[m];
; #pragma unroll
;         for (int e = 0; e < 4; ++e) { g[e] = acc[ai][0][m][0][e] * rs; g[4 + e] = acc[ai][0][m][1][e] * rs; uu[e] = acc[ai][1][m][0][e] * rs; uu[4 + e] = acc[ai][1][m][1][e] * rs; }
; #pragma unroll
;         for (int e = 0; e < 8; ++e) {
;           const float x1 = dpp_ror1(g[e]), x2 = dpp_ror2(g[e]);
;           const float pr1 = (fr == 0) ? p1[e] : x1, pr2 = (fr < 2) ? p2[e] : x2;
;           a[e] = w2[e] * g[e] + w1[e] * pr1 + w0[e] * pr2 + bb[e];
;           p1[e] = x1; p2[e] = x2;
	s_setprio 0
	s_cbranch_scc0 .LBB0_1277
	s_lshl_b32 s39, s12, 8
	s_add_i32 s39, s39, s54
	v_or_b32_e32 v190, s39, v179
	v_ashrrev_i32_e32 v191, 31, v190
	v_lshlrev_b64 v[64:65], 7, v[190:191]
	v_or_b32_e32 v188, 16, v190
	v_lshl_add_u64 v[64:65], v[168:169], 0, v[64:65]
	v_ashrrev_i32_e32 v189, 31, v188
	global_load_dwordx4 v[192:195], v[64:65], off
	global_load_dwordx4 v[206:209], v[64:65], off offset:16
	v_lshlrev_b64 v[64:65], 7, v[188:189]
	v_lshl_add_u64 v[64:65], v[168:169], 0, v[64:65]
	global_load_dwordx4 v[212:215], v[64:65], off
	global_load_dwordx4 v[216:219], v[64:65], off offset:16
	v_or_b32_e32 v186, 32, v190
	v_ashrrev_i32_e32 v187, 31, v186
	v_lshlrev_b64 v[64:65], 7, v[186:187]
	v_or_b32_e32 v184, 48, v190
	v_lshl_add_u64 v[64:65], v[168:169], 0, v[64:65]
	v_ashrrev_i32_e32 v185, 31, v184
	global_load_dwordx4 v[220:223], v[64:65], off
	global_load_dwordx4 v[224:227], v[64:65], off offset:16
	v_lshlrev_b64 v[64:65], 7, v[184:185]
	v_lshl_add_u64 v[64:65], v[168:169], 0, v[64:65]
	global_load_dwordx4 v[228:231], v[64:65], off
	global_load_dwordx4 v[232:235], v[64:65], off offset:16
	v_lshl_or_b32 v180, s13, 7, v200
	v_and_b32_e32 v65, 64, v204
	v_xor_b32_e32 v64, 16, v204
	v_ashrrev_i32_e32 v181, 31, v180
	v_add_u32_e32 v65, 64, v65
	v_xor_b32_e32 v66, 32, v204
	v_lshlrev_b64 v[182:183], 2, v[180:181]
	v_cmp_lt_i32_e32 vcc, v64, v65
	v_lshl_add_u64 v[88:89], s[16:17], 0, v[182:183]
	v_lshl_add_u64 v[72:73], s[18:19], 0, v[182:183]
	v_cndmask_b32_e32 v64, v204, v64, vcc
	v_cmp_lt_i32_e32 vcc, v66, v65
	v_lshl_add_u64 v[74:75], v[88:89], 0, s[30:31]
	v_lshl_add_u64 v[76:77], v[88:89], 0, s[34:35]
	v_cndmask_b32_e32 v65, v204, v66, vcc
	v_add_co_u32_e32 v90, vcc, 0x5000, v88
	v_lshlrev_b32_e32 v187, 2, v64
	s_nop 0
	v_addc_co_u32_e32 v91, vcc, 0, v89, vcc
	v_add_co_u32_e32 v92, vcc, 0xb000, v88
	v_lshlrev_b32_e32 v185, 2, v65
	s_nop 0
	v_addc_co_u32_e32 v93, vcc, 0, v89, vcc
	global_load_dwordx4 v[64:67], v[88:89], off offset:16
	global_load_dwordx4 v[80:83], v[88:89], off
	global_load_dwordx4 v[68:71], v[72:73], off offset:16
	global_load_dwordx4 v[84:87], v[72:73], off
	s_nop 0
	global_load_dwordx4 v[72:75], v[74:75], off offset:16
	s_nop 0
	global_load_dwordx4 v[76:79], v[76:77], off offset:16
	s_nop 0
	global_load_dwordx4 v[88:91], v[90:91], off offset:2048
	s_nop 0
	global_load_dwordx4 v[92:95], v[92:93], off
	v_mov_b32_e32 v211, 0
	v_mov_b32_e32 v205, 0
	s_waitcnt vmcnt(0)
	v_mov_b32_e32 v196, v192
	v_mov_b32_e32 v197, v206
	v_mov_b32_e32 v206, v193
	v_mov_b32_e32 v192, v194
	v_mov_b32_e32 v193, v208
	v_mov_b32_e32 v208, v195
	v_pk_add_f32 v[194:195], v[196:197], v[206:207]
	v_pk_add_f32 v[192:193], v[192:193], v[208:209]
	v_mov_b32_e32 v196, v212
	v_mov_b32_e32 v197, v216
	v_mov_b32_e32 v216, v213
	v_mov_b32_e32 v206, v214
	v_mov_b32_e32 v207, v218
	v_mov_b32_e32 v218, v215
	v_pk_add_f32 v[192:193], v[194:195], v[192:193]
	v_pk_add_f32 v[194:195], v[196:197], v[216:217]
	v_pk_add_f32 v[196:197], v[206:207], v[218:219]
	v_mov_b32_e32 v208, v220
	v_pk_add_f32 v[194:195], v[194:195], v[196:197]
	v_mov_b32_e32 v197, v192
	v_mov_b32_e32 v196, v194
	v_mov_b32_e32 v192, v195
	v_pk_add_f32 v[192:193], v[196:197], v[192:193]
	ds_bpermute_b32 v195, v187, v193
	ds_bpermute_b32 v194, v187, v192
	v_mov_b32_e32 v209, v224
	v_mov_b32_e32 v224, v221
	v_mov_b32_e32 v212, v222
	v_mov_b32_e32 v213, v226
	s_waitcnt lgkmcnt(0)
	v_pk_add_f32 v[192:193], v[192:193], v[194:195]
	ds_bpermute_b32 v195, v185, v193
	ds_bpermute_b32 v194, v185, v192
	v_mov_b32_e32 v226, v223
	v_mov_b32_e32 v196, v228
	v_mov_b32_e32 v197, v232
	v_mov_b32_e32 v232, v229
	s_waitcnt lgkmcnt(0)
	v_pk_add_f32 v[192:193], v[192:193], v[194:195]
	v_mov_b32_e32 v206, v230
	v_pk_fma_f32 v[192:193], v[192:193], s[36:37], v[178:179] op_sel_hi:[1,0,0]
	v_mov_b32_e32 v207, v234
	v_mul_f32_e32 v189, 0x4b800000, v193
	v_cmp_gt_f32_e64 s[12:13], s74, v193
	v_mov_b32_e32 v234, v231
	v_pk_add_f32 v[208:209], v[208:209], v[224:225]
	v_cndmask_b32_e64 v189, v193, v189, s[12:13]
	v_rsq_f32_e32 v189, v189
	v_pk_add_f32 v[212:213], v[212:213], v[226:227]
	v_pk_add_f32 v[196:197], v[196:197], v[232:233]
	v_pk_add_f32 v[194:195], v[206:207], v[234:235]
	v_mul_f32_e32 v191, 0x45800000, v189
	v_cndmask_b32_e64 v220, v189, v191, s[12:13]
	v_pk_add_f32 v[208:209], v[208:209], v[212:213]
	v_pk_add_f32 v[194:195], v[196:197], v[194:195]
	v_pk_mul_f32 v[156:157], v[156:157], v[220:221] op_sel_hi:[1,0]
	v_mov_b32_e32 v216, 0
	v_mov_b32_e32 v218, 0
	v_mov_b32_e32 v196, v194
	v_mov_b32_e32 v197, v208
	v_mov_b32_e32 v208, v195
	v_mov_b32_dpp v216, v156 row_ror:1 row_mask:0xf bank_mask:0xf
	v_mov_b32_dpp v218, v157 row_ror:1 row_mask:0xf bank_mask:0xf
	v_pk_add_f32 v[194:195], v[196:197], v[208:209]
	v_cndmask_b32_e64 v207, v218, 0, s[0:1]
	v_cndmask_b32_e64 v206, v216, 0, s[0:1]
	v_pk_mul_f32 v[158:159], v[158:159], v[220:221] op_sel_hi:[1,0]
	v_mov_b32_e32 v212, 0
	v_mov_b32_e32 v214, 0
	ds_bpermute_b32 v197, v187, v195
	ds_bpermute_b32 v196, v187, v194
	v_mov_b32_e32 v215, 0
	v_mov_b32_e32 v217, 0
	v_pk_mul_f32 v[206:207], v[88:89], v[206:207]
	v_mov_b32_dpp v212, v158 row_ror:1 row_mask:0xf bank_mask:0xf
	v_mov_b32_dpp v214, v159 row_ror:1 row_mask:0xf bank_mask:0xf
	v_mov_b32_dpp v215, v156 row_ror:2 row_mask:0xf bank_mask:0xf
	v_mov_b32_dpp v217, v157 row_ror:2 row_mask:0xf bank_mask:0xf
	v_pk_fma_f32 v[156:157], v[92:93], v[156:157], v[206:207]
	v_mov_b32_e32 v213, 0
	v_cndmask_b32_e64 v207, v214, 0, s[0:1]
	v_cndmask_b32_e64 v206, v212, 0, s[0:1]
	v_cndmask_b32_e64 v209, v217, 0, s[4:5]
	v_cndmask_b32_e64 v208, v215, 0, s[4:5]
	v_mov_b32_dpp v211, v158 row_ror:2 row_mask:0xf bank_mask:0xf
	v_mov_b32_dpp v213, v159 row_ror:2 row_mask:0xf bank_mask:0xf
	v_pk_mul_f32 v[206:207], v[90:91], v[206:207]
	v_pk_fma_f32 v[156:157], v[80:81], v[208:209], v[156:157]
	v_cndmask_b32_e64 v209, v213, 0, s[4:5]
	v_cndmask_b32_e64 v208, v211, 0, s[4:5]
	v_pk_fma_f32 v[158:159], v[94:95], v[158:159], v[206:207]
	v_pk_mul_f32 v[144:145], v[144:145], v[220:221] op_sel_hi:[1,0]
	v_pk_fma_f32 v[158:159], v[82:83], v[208:209], v[158:159]
	v_mov_b32_e32 v207, 0
	v_mov_b32_e32 v209, 0
	v_pk_mul_f32 v[146:147], v[146:147], v[220:221] op_sel_hi:[1,0]
	v_mov_b32_e32 v191, 0
	s_waitcnt lgkmcnt(0)
; DI unsigned pack2(float lo, float hi) { f32x2 v = {lo, hi}; bf16v2 r = __builtin_convertvector(v, bf16v2); return __builtin_bit_cast(unsigned, r); }
; DI float silu_f(float x) { return x * sigmoid_f(x); }
; DI float dpp_ror1(float v) { return __int_as_float(__builtin_amdgcn_update_dpp(0, __float_as_int(v), 0x121, 0xf, 0xf, false)); }
; DI float dpp_ror2(float v) { return __int_as_float(__builtin_amdgcn_update_dpp(0, __float_as_int(v), 0x122, 0xf, 0xf, false)); }
;   DI void operator()(const f32x4 (&acc)[2][2][4][2], const Unit& u, int wr, int wc, int fr, int fq) const {
;     ...
;         for (int e = 0; e < 4; ++e) { g[e] = acc[ai][0][m][0][e] * rs; g[4 + e] = acc[ai][0][m][1][e] * rs; uu[e] = acc[ai][1][m][0][e] * rs; uu[4 + e] = acc[ai][1][m][1][e] * rs; }
; #pragma unroll
;         for (int e = 0; e < 8; ++e) {
;           const float x1 = dpp_ror1(g[e]), x2 = dpp_ror2(g[e]);
;           const float pr1 = (fr == 0) ? p1[e] : x1, pr2 = (fr < 2) ? p2[e] : x2;
;           a[e] = w2[e] * g[e] + w1[e] * pr1 + w0[e] * pr2 + bb[e];
;           p1[e] = x1; p2[e] = x2;
;         }
;         if (m == 0 && fr < 2) {
;           float* ha = headA + (size_t)(span * 2 + fr) * 5632 + col; float* hu = headU + (size_t)(span * 2 + fr) * 5632 + col;
;           *(f32x4*)ha = (f32x4){a[0], a[1], a[2], a[3]}; *(f32x4*)(ha + 4) = (f32x4){a[4], a[5], a[6], a[7]};
;           *(f32x4*)hu = (f32x4){uu[0], uu[1], uu[2], uu[3]}; *(f32x4*)(hu + 4) = (f32x4){uu[4], uu[5], uu[6], uu[7]};
;         } else {
;           u32x4 w;
;           w.x = pack2(silu_f(a[0]) * uu[0], silu_f(a[1]) * uu[1]);
;           w.y = pack2(silu_f(a[2]) * uu[2], silu_f(a[3]) * uu[3]);
;           w.z = pack2(silu_f(a[4]) * uu[4], silu_f(a[5]) * uu[5]);
;           w.w = pack2(silu_f(a[6]) * uu[6], silu_f(a[7]) * uu[7]);
;           *(u32x4*)(H + (size_t)(row0 + 16 * m + fr) * 5632 + col) = w;
	v_pk_add_f32 v[194:195], v[194:195], v[196:197]
	v_mov_b32_dpp v207, v144 row_ror:1 row_mask:0xf bank_mask:0xf
	v_mov_b32_dpp v209, v145 row_ror:1 row_mask:0xf bank_mask:0xf
	v_mov_b32_dpp v191, v146 row_ror:1 row_mask:0xf bank_mask:0xf
	v_mov_b32_dpp v205, v147 row_ror:1 row_mask:0xf bank_mask:0xf
	ds_bpermute_b32 v197, v185, v195
	ds_bpermute_b32 v196, v185, v194
	v_pk_mul_f32 v[152:153], v[152:153], v[220:221] op_sel_hi:[1,0]
	v_pk_mul_f32 v[148:149], v[148:149], v[220:221] op_sel_hi:[1,0]
	v_pk_mul_f32 v[154:155], v[154:155], v[220:221] op_sel_hi:[1,0]
	v_pk_mul_f32 v[150:151], v[150:151], v[220:221] op_sel_hi:[1,0]
	v_mov_b32_e32 v206, 0
	v_mov_b32_e32 v208, 0
	v_cndmask_b32_e64 v223, v209, 0, s[0:1]
	v_cndmask_b32_e64 v222, v207, 0, s[0:1]
	v_mov_b32_e32 v189, 0
	v_mov_b32_e32 v193, 0
	v_cndmask_b32_e64 v221, v205, 0, s[0:1]
	v_cndmask_b32_e64 v220, v191, 0, s[0:1]
	v_mov_b32_dpp v206, v144 row_ror:2 row_mask:0xf bank_mask:0xf
	v_mov_b32_dpp v208, v145 row_ror:2 row_mask:0xf bank_mask:0xf
	v_pk_mul_f32 v[222:223], v[72:73], v[222:223]
	v_mov_b32_dpp v189, v146 row_ror:2 row_mask:0xf bank_mask:0xf
	v_mov_b32_dpp v193, v147 row_ror:2 row_mask:0xf bank_mask:0xf
	v_pk_mul_f32 v[220:221], v[74:75], v[220:221]
	v_cndmask_b32_e64 v225, v208, 0, s[4:5]
	v_cndmask_b32_e64 v224, v206, 0, s[4:5]
	v_pk_fma_f32 v[144:145], v[76:77], v[144:145], v[222:223]
	v_cndmask_b32_e64 v223, v193, 0, s[4:5]
	v_cndmask_b32_e64 v222, v189, 0, s[4:5]
	v_pk_fma_f32 v[146:147], v[78:79], v[146:147], v[220:221]
	v_pk_fma_f32 v[144:145], v[64:65], v[224:225], v[144:145]
	v_pk_fma_f32 v[146:147], v[66:67], v[222:223], v[146:147]
	v_cmp_gt_f32_e32 vcc, s74, v192
	v_pk_add_f32 v[156:157], v[84:85], v[156:157]
	v_pk_add_f32 v[158:159], v[86:87], v[158:159]
	v_pk_add_f32 v[144:145], v[68:69], v[144:145]
	v_pk_add_f32 v[146:147], v[70:71], v[146:147]
	s_and_saveexec_b64 s[12:13], s[10:11]
	s_xor_b64 s[12:13], exec, s[12:13]
	s_cbranch_execz .LBB0_1280
	v_mul_f32_e32 v219, 0xbfb8aa3b, v156
	v_exp_f32_e32 v219, v219
	v_mul_f32_e32 v220, 0xbfb8aa3b, v157
	v_exp_f32_e32 v220, v220
	v_mul_f32_e32 v222, 0xbfb8aa3b, v159
	v_add_f32_e32 v219, 1.0, v219
	v_exp_f32_e32 v223, v222
	v_add_f32_e32 v221, 1.0, v220
	v_rcp_f32_e32 v220, v219
	v_mul_f32_e32 v219, 0xbfb8aa3b, v158
	v_exp_f32_e32 v219, v219
	v_rcp_f32_e32 v221, v221
	v_add_f32_e32 v219, 1.0, v219
	v_rcp_f32_e32 v222, v219
	v_add_f32_e32 v219, 1.0, v223
	v_rcp_f32_e32 v223, v219
	v_pk_mul_f32 v[156:157], v[156:157], v[220:221]
	s_nop 0
	v_pk_mul_f32 v[152:153], v[152:153], v[156:157]
	v_pk_mul_f32 v[156:157], v[158:159], v[222:223]
	v_cvt_pk_bf16_f32 v152, v152, v153
	v_mul_f32_e32 v153, 0xbfb8aa3b, v144
	v_pk_mul_f32 v[154:155], v[154:155], v[156:157]
	v_exp_f32_e32 v156, v153
	v_mul_f32_e32 v153, 0xbfb8aa3b, v145
	v_exp_f32_e32 v157, v153
	v_cvt_pk_bf16_f32 v153, v154, v155
	v_add_f32_e32 v154, 1.0, v156
	v_mul_f32_e32 v156, 0xbfb8aa3b, v146
	v_add_f32_e32 v155, 1.0, v157
	v_mul_f32_e32 v157, 0xbfb8aa3b, v147
	v_exp_f32_e32 v156, v156
	v_exp_f32_e32 v157, v157
	v_rcp_f32_e32 v154, v154
	v_rcp_f32_e32 v155, v155
	v_add_f32_e32 v156, 1.0, v156
	v_add_f32_e32 v157, 1.0, v157
	v_rcp_f32_e32 v156, v156
	v_rcp_f32_e32 v157, v157
	v_pk_mul_f32 v[144:145], v[144:145], v[154:155]
	s_nop 0
	v_pk_mul_f32 v[144:145], v[148:149], v[144:145]
	s_nop 0
	v_cvt_pk_bf16_f32 v154, v144, v145
	v_pk_mul_f32 v[144:145], v[146:147], v[156:157]
	s_nop 0
	v_pk_mul_f32 v[144:145], v[150:151], v[144:145]
	s_nop 0
	v_cvt_pk_bf16_f32 v155, v144, v145
	v_mov_b64_e32 v[144:145], s[20:21]
	v_mad_i64_i32 v[144:145], s[14:15], v190, s75, v[144:145]
	v_lshl_add_u64 v[144:145], v[180:181], 1, v[144:145]
	global_store_dwordx4 v[144:145], v[152:155], off

; #define PG8_STAGE(bufoff, gbase, voff) do { _Pragma("unroll") for (int _i = 0; _i < 2; ++_i) \
;     __builtin_amdgcn_global_load_lds((const unsigned*)((const char*)(gbase) + (voff)[_i]), (LAS unsigned*)(lds + (bufoff) + ldsw + _i * 8192), 16, 0, 0); } while (0)
; #define PG8_LDA(dst, b, h) do { _Pragma("unroll") for (int m = 0; m < 4; ++m) _Pragma("unroll") for (int k = 0; k < 2; ++k) dst[m][k] = *(const LAS bf16x8*)(lds + PG8_SA(b, h) + aoff + m * 2048 + k * 1024); } while (0)
; #define PG8_LDB(dst, b, h) do { _Pragma("unroll") for (int n = 0; n < 2; ++n) _Pragma("unroll") for (int k = 0; k < 2; ++k) dst[n][k] = *(const LAS bf16x8*)(lds + PG8_SB(b, h) + boff + n * 2048 + k * 1024); } while (0)
; #define PG8_MMA(ai, bj, At, Bt) do { __builtin_amdgcn_s_setprio(1); _Pragma("unroll") for (int m = 0; m < 4; ++m) _Pragma("unroll") for (int n = 0; n < 2; ++n) _Pragma("unroll") for (int k = 0; k < 2; ++k) \
;     acc[ai][bj][m][n] = __builtin_amdgcn_mfma_f32_16x16x32_bf16(Bt[n][k], At[m][k], acc[ai][bj][m][n], 0, 0, 0); __builtin_amdgcn_s_setprio(0); } while (0)
; #define PG8_WAIT_V(n) asm volatile("s_waitcnt vmcnt(" #n ")" ::: "memory")
; #define PG8_WAIT_L(n) asm volatile("s_waitcnt lgkmcnt(" #n ")" ::: "memory")
; #define PG8_BAR __builtin_amdgcn_s_barrier()
; #define PG8_SCHED __builtin_amdgcn_sched_barrier(0)
; template <class Epi, class Sched = StaticOrder>
; DI void gemm_phase(LAS unsigned char* lds, const Gemm g, const Sched& S, const Epi& E) {
;     ...
;       PG8_LDB(B0, 0, 0); PG8_SCHED; PG8_LDA(At, 0, 0); PG8_STAGE(PG8_SA(1, 1), a1 + hstep, voffA);
;       PG8_WAIT_L(8); PG8_BAR; PG8_WAIT_L(0); PG8_MMA(0, 0, At, B0); PG8_BAR; PG8_SCHED;
;       PG8_LDB(B1, 0, 1); PG8_STAGE(PG8_SB(0, 0), b2, voffB);
;       PG8_BAR; PG8_WAIT_L(0); PG8_MMA(0, 1, At, B1); PG8_BAR;
;       PG8_LDA(At, 0, 1); PG8_STAGE(PG8_SA(0, 0), a2, voffA);
;       PG8_BAR; PG8_WAIT_L(0); PG8_MMA(1, 0, At, B0); PG8_BAR; PG8_SCHED;
;       PG8_STAGE(PG8_SB(0, 1), b2 + hstep, voffB);
;       PG8_WAIT_V(6); PG8_BAR; PG8_MMA(1, 1, At, B1); PG8_BAR;
.LBB0_1424:
	ds_read_b128 v[144:147], v159
	ds_read_b128 v[148:151], v159 offset:1024
	ds_read_b128 v[152:155], v159 offset:2048
	ds_read_b128 v[162:165], v159 offset:3072
	s_add_u32 s18, s16, 0xffea0080
	s_addc_u32 s19, s17, -1
	s_cmpk_eq_i32 s47, 0x54
	s_cselect_b32 s21, s3, s19
	s_cselect_b32 s20, s2, s18
	s_cselect_b32 s19, s5, s46
	s_cselect_b32 s18, s4, s45
	s_add_i32 m0, s30, 0xc000
	ds_read_b128 v[166:169], v160
	ds_read_b128 v[170:173], v160 offset:1024
	ds_read_b128 v[174:177], v160 offset:2048
	ds_read_b128 v[178:181], v160 offset:3072
	ds_read_b128 v[182:185], v160 offset:4096
	ds_read_b128 v[186:189], v160 offset:5120
	ds_read_b128 v[190:193], v160 offset:6144
	ds_read_b128 v[194:197], v160 offset:7168
	global_load_lds_dwordx4 v136, s[16:17]
	s_add_i32 m0, s30, 0xe000
	s_nop 0
	global_load_lds_dwordx4 v138, s[16:17]
	ds_read_b128 v[198:201], v161
	ds_read_b128 v[202:205], v161 offset:1024
	ds_read_b128 v[206:209], v161 offset:2048
	ds_read_b128 v[210:213], v161 offset:3072
	s_waitcnt vmcnt(8)
	s_waitcnt lgkmcnt(4)
	s_setprio 1
	s_barrier
	v_mfma_f32_16x16x32_bf16 v[124:127], v[144:147], v[166:169], v[124:127]
	v_mfma_f32_16x16x32_bf16 v[120:123], v[152:155], v[166:169], v[120:123]
	v_mfma_f32_16x16x32_bf16 v[116:119], v[144:147], v[174:177], v[116:119]
	v_mfma_f32_16x16x32_bf16 v[112:115], v[152:155], v[174:177], v[112:115]
	v_mfma_f32_16x16x32_bf16 v[104:107], v[144:147], v[182:185], v[104:107]
	v_mfma_f32_16x16x32_bf16 v[96:99], v[152:155], v[182:185], v[96:99]
	v_mfma_f32_16x16x32_bf16 v[88:91], v[144:147], v[190:193], v[88:91]
	v_mfma_f32_16x16x32_bf16 v[80:83], v[152:155], v[190:193], v[80:83]
	v_mfma_f32_16x16x32_bf16 v[124:127], v[148:151], v[170:173], v[124:127]
	v_mfma_f32_16x16x32_bf16 v[120:123], v[162:165], v[170:173], v[120:123]
	v_mfma_f32_16x16x32_bf16 v[116:119], v[148:151], v[178:181], v[116:119]
	v_mfma_f32_16x16x32_bf16 v[112:115], v[162:165], v[178:181], v[112:115]
	v_mfma_f32_16x16x32_bf16 v[104:107], v[148:151], v[186:189], v[104:107]
	v_mfma_f32_16x16x32_bf16 v[96:99], v[162:165], v[186:189], v[96:99]
	v_mfma_f32_16x16x32_bf16 v[88:91], v[148:151], v[194:197], v[88:91]
	v_mfma_f32_16x16x32_bf16 v[80:83], v[162:165], v[194:197], v[80:83]
	s_waitcnt lgkmcnt(0)
	v_mfma_f32_16x16x32_bf16 v[108:111], v[198:201], v[166:169], v[108:111]
	v_mfma_f32_16x16x32_bf16 v[100:103], v[206:209], v[166:169], v[100:103]
	v_mfma_f32_16x16x32_bf16 v[92:95], v[198:201], v[174:177], v[92:95]
	v_mfma_f32_16x16x32_bf16 v[84:87], v[206:209], v[174:177], v[84:87]
	v_mfma_f32_16x16x32_bf16 v[76:79], v[198:201], v[182:185], v[76:79]
	v_mfma_f32_16x16x32_bf16 v[72:75], v[206:209], v[182:185], v[72:75]
	v_mfma_f32_16x16x32_bf16 v[68:71], v[198:201], v[190:193], v[68:71]
	v_mfma_f32_16x16x32_bf16 v[64:67], v[206:209], v[190:193], v[64:67]
	v_mfma_f32_16x16x32_bf16 v[108:111], v[202:205], v[170:173], v[108:111]
	v_mfma_f32_16x16x32_bf16 v[100:103], v[210:213], v[170:173], v[100:103]
	v_mfma_f32_16x16x32_bf16 v[92:95], v[202:205], v[178:181], v[92:95]
	v_mfma_f32_16x16x32_bf16 v[84:87], v[210:213], v[178:181], v[84:87]
	v_mfma_f32_16x16x32_bf16 v[76:79], v[202:205], v[186:189], v[76:79]
	v_mfma_f32_16x16x32_bf16 v[72:75], v[210:213], v[186:189], v[72:75]
	v_mfma_f32_16x16x32_bf16 v[68:71], v[202:205], v[194:197], v[68:71]
	v_mfma_f32_16x16x32_bf16 v[64:67], v[210:213], v[194:197], v[64:67]
	s_barrier
	s_setprio 0
	s_add_i32 s48, s39, s28
	s_add_u32 s98, s18, 0x80
	s_addc_u32 s99, s19, 0
	s_add_u32 s100, s20, 0x80
	s_addc_u32 s101, s21, 0
	s_mov_b32 m0, s48
	s_nop 0
	global_load_lds_dwordx4 v132, s[18:19]
	s_add_i32 m0, s48, 0x2000
	s_nop 0
	global_load_lds_dwordx4 v128, s[18:19]
	s_mov_b32 m0, s30
	s_nop 0
	global_load_lds_dwordx4 v134, s[20:21]
	s_mov_b32 m0, s31
	s_nop 0
	global_load_lds_dwordx4 v130, s[20:21]
	ds_read_b128 v[166:169], v160 offset:16384
	ds_read_b128 v[170:173], v160 offset:17408
	ds_read_b128 v[174:177], v160 offset:18432
	ds_read_b128 v[178:181], v160 offset:19456
	ds_read_b128 v[182:185], v160 offset:20480
	ds_read_b128 v[186:189], v160 offset:21504
	ds_read_b128 v[190:193], v160 offset:22528
	ds_read_b128 v[194:197], v160 offset:23552
	s_add_u32 s48, s18, 0x160000
	s_addc_u32 s49, s19, 0
	s_add_i32 s50, s40, s28
	s_waitcnt vmcnt(6)
	s_waitcnt lgkmcnt(0)
	s_setprio 1
	s_barrier
	v_mfma_f32_16x16x32_bf16 v[60:63], v[144:147], v[166:169], v[60:63]
	s_mov_b32 m0, s50
	v_mfma_f32_16x16x32_bf16 v[56:59], v[152:155], v[166:169], v[56:59]
	global_load_lds_dwordx4 v132, s[48:49]
	v_mfma_f32_16x16x32_bf16 v[52:55], v[144:147], v[174:177], v[52:55]
	s_bitset1_b32 m0, 13
	v_mfma_f32_16x16x32_bf16 v[44:47], v[152:155], v[174:177], v[44:47]
	global_load_lds_dwordx4 v128, s[48:49]
	v_mfma_f32_16x16x32_bf16 v[36:39], v[144:147], v[182:185], v[36:39]
	v_mfma_f32_16x16x32_bf16 v[28:31], v[152:155], v[182:185], v[28:31]
	v_mfma_f32_16x16x32_bf16 v[20:23], v[144:147], v[190:193], v[20:23]
	v_mfma_f32_16x16x32_bf16 v[12:15], v[152:155], v[190:193], v[12:15]
	v_mfma_f32_16x16x32_bf16 v[60:63], v[148:151], v[170:173], v[60:63]
	v_mfma_f32_16x16x32_bf16 v[56:59], v[162:165], v[170:173], v[56:59]
	v_mfma_f32_16x16x32_bf16 v[52:55], v[148:151], v[178:181], v[52:55]
	v_mfma_f32_16x16x32_bf16 v[44:47], v[162:165], v[178:181], v[44:47]
	v_mfma_f32_16x16x32_bf16 v[36:39], v[148:151], v[186:189], v[36:39]
	v_mfma_f32_16x16x32_bf16 v[28:31], v[162:165], v[186:189], v[28:31]
	v_mfma_f32_16x16x32_bf16 v[20:23], v[148:151], v[194:197], v[20:23]
	v_mfma_f32_16x16x32_bf16 v[12:15], v[162:165], v[194:197], v[12:15]
	v_mfma_f32_16x16x32_bf16 v[48:51], v[198:201], v[166:169], v[48:51]
	v_mfma_f32_16x16x32_bf16 v[40:43], v[206:209], v[166:169], v[40:43]
	v_mfma_f32_16x16x32_bf16 v[32:35], v[198:201], v[174:177], v[32:35]
	v_mfma_f32_16x16x32_bf16 v[24:27], v[206:209], v[174:177], v[24:27]
	v_mfma_f32_16x16x32_bf16 v[16:19], v[198:201], v[182:185], v[16:19]
	v_mfma_f32_16x16x32_bf16 v[8:11], v[206:209], v[182:185], v[8:11]
	v_mfma_f32_16x16x32_bf16 v[4:7], v[198:201], v[190:193], v[4:7]
	v_mfma_f32_16x16x32_bf16 v[0:3], v[206:209], v[190:193], v[0:3]
	v_mfma_f32_16x16x32_bf16 v[48:51], v[202:205], v[170:173], v[48:51]
	v_mfma_f32_16x16x32_bf16 v[40:43], v[210:213], v[170:173], v[40:43]
	v_mfma_f32_16x16x32_bf16 v[32:35], v[202:205], v[178:181], v[32:35]
	v_mfma_f32_16x16x32_bf16 v[24:27], v[210:213], v[178:181], v[24:27]
	v_mfma_f32_16x16x32_bf16 v[16:19], v[202:205], v[186:189], v[16:19]
	v_mfma_f32_16x16x32_bf16 v[8:11], v[210:213], v[186:189], v[8:11]
	v_mfma_f32_16x16x32_bf16 v[4:7], v[202:205], v[194:197], v[4:7]
	v_mfma_f32_16x16x32_bf16 v[0:3], v[210:213], v[194:197], v[0:3]
	s_barrier
; #define PG8_STAGE(bufoff, gbase, voff) do { _Pragma("unroll") for (int _i = 0; _i < 2; ++_i) \
;     __builtin_amdgcn_global_load_lds((const unsigned*)((const char*)(gbase) + (voff)[_i]), (LAS unsigned*)(lds + (bufoff) + ldsw + _i * 8192), 16, 0, 0); } while (0)
; #define PG8_LDA(dst, b, h) do { _Pragma("unroll") for (int m = 0; m < 4; ++m) _Pragma("unroll") for (int k = 0; k < 2; ++k) dst[m][k] = *(const LAS bf16x8*)(lds + PG8_SA(b, h) + aoff + m * 2048 + k * 1024); } while (0)
; #define PG8_LDB(dst, b, h) do { _Pragma("unroll") for (int n = 0; n < 2; ++n) _Pragma("unroll") for (int k = 0; k < 2; ++k) dst[n][k] = *(const LAS bf16x8*)(lds + PG8_SB(b, h) + boff + n * 2048 + k * 1024); } while (0)
; #define PG8_MMA(ai, bj, At, Bt) do { __builtin_amdgcn_s_setprio(1); _Pragma("unroll") for (int m = 0; m < 4; ++m) _Pragma("unroll") for (int n = 0; n < 2; ++n) _Pragma("unroll") for (int k = 0; k < 2; ++k) \
;     acc[ai][bj][m][n] = __builtin_amdgcn_mfma_f32_16x16x32_bf16(Bt[n][k], At[m][k], acc[ai][bj][m][n], 0, 0, 0); __builtin_amdgcn_s_setprio(0); } while (0)
; #define PG8_WAIT_V(n) asm volatile("s_waitcnt vmcnt(" #n ")" ::: "memory")
; #define PG8_WAIT_L(n) asm volatile("s_waitcnt lgkmcnt(" #n ")" ::: "memory")
; #define PG8_BAR __builtin_amdgcn_s_barrier()
; #define PG8_SCHED __builtin_amdgcn_sched_barrier(0)
; template <class Epi, class Sched = StaticOrder>
; DI void gemm_phase(LAS unsigned char* lds, const Gemm g, const Sched& S, const Epi& E) {
;     ...
;       PG8_LDB(B0, 1, 0); PG8_SCHED; PG8_LDA(At, 1, 0); PG8_STAGE(PG8_SA(0, 1), a2 + hstep, voffA);
;       PG8_WAIT_L(8); PG8_BAR; PG8_WAIT_L(0); PG8_MMA(0, 0, At, B0); PG8_BAR; PG8_SCHED;
;       PG8_LDB(B1, 1, 1); PG8_STAGE(PG8_SB(1, 0), b3, voffB);
;       PG8_BAR; PG8_WAIT_L(0); PG8_MMA(0, 1, At, B1); PG8_BAR;
;       PG8_LDA(At, 1, 1); PG8_STAGE(PG8_SA(1, 0), a3, voffA);
;       PG8_BAR; PG8_WAIT_L(0); PG8_MMA(1, 0, At, B0); PG8_BAR; PG8_SCHED;
;       PG8_STAGE(PG8_SB(1, 1), b3 + hstep, voffB);
;       PG8_WAIT_V(6); PG8_BAR; PG8_MMA(1, 1, At, B1); PG8_BAR;
	s_setprio 0
	s_add_i32 s48, 0, 0x18000
	v_add_u32_e32 v162, s48, v157
	ds_read_b128 v[144:147], v162
	ds_read_b128 v[148:151], v162 offset:1024
	ds_read_b128 v[152:155], v162 offset:2048
	ds_read_b128 v[162:165], v162 offset:3072
	s_add_u32 s20, s20, 0x160000
	s_addc_u32 s21, s21, 0
	s_mov_b32 m0, s33
	ds_read_b128 v[166:169], v160 offset:32768
	ds_read_b128 v[170:173], v160 offset:33792
	ds_read_b128 v[174:177], v160 offset:34816
	ds_read_b128 v[178:181], v160 offset:35840
	ds_read_b128 v[182:185], v160 offset:36864
	ds_read_b128 v[186:189], v160 offset:37888
	ds_read_b128 v[190:193], v160 offset:38912
	ds_read_b128 v[194:197], v160 offset:39936
	global_load_lds_dwordx4 v134, s[20:21]
	s_mov_b32 m0, s34
	s_nop 0
	global_load_lds_dwordx4 v130, s[20:21]
	s_add_i32 s20, 0, 0x1c000
	v_add_u32_e32 v210, s20, v157
	ds_read_b128 v[198:201], v210
	ds_read_b128 v[202:205], v210 offset:1024
	ds_read_b128 v[206:209], v210 offset:2048
	ds_read_b128 v[210:213], v210 offset:3072
	s_waitcnt vmcnt(8)
	s_waitcnt lgkmcnt(4)
	s_setprio 1
	s_barrier
	v_mfma_f32_16x16x32_bf16 v[124:127], v[144:147], v[166:169], v[124:127]
	v_mfma_f32_16x16x32_bf16 v[120:123], v[152:155], v[166:169], v[120:123]
	v_mfma_f32_16x16x32_bf16 v[116:119], v[144:147], v[174:177], v[116:119]
	v_mfma_f32_16x16x32_bf16 v[112:115], v[152:155], v[174:177], v[112:115]
	v_mfma_f32_16x16x32_bf16 v[104:107], v[144:147], v[182:185], v[104:107]
	v_mfma_f32_16x16x32_bf16 v[96:99], v[152:155], v[182:185], v[96:99]
	v_mfma_f32_16x16x32_bf16 v[88:91], v[144:147], v[190:193], v[88:91]
	v_mfma_f32_16x16x32_bf16 v[80:83], v[152:155], v[190:193], v[80:83]
	v_mfma_f32_16x16x32_bf16 v[124:127], v[148:151], v[170:173], v[124:127]
	v_mfma_f32_16x16x32_bf16 v[120:123], v[162:165], v[170:173], v[120:123]
	v_mfma_f32_16x16x32_bf16 v[116:119], v[148:151], v[178:181], v[116:119]
	v_mfma_f32_16x16x32_bf16 v[112:115], v[162:165], v[178:181], v[112:115]
	v_mfma_f32_16x16x32_bf16 v[104:107], v[148:151], v[186:189], v[104:107]
	v_mfma_f32_16x16x32_bf16 v[96:99], v[162:165], v[186:189], v[96:99]
	v_mfma_f32_16x16x32_bf16 v[88:91], v[148:151], v[194:197], v[88:91]
	v_mfma_f32_16x16x32_bf16 v[80:83], v[162:165], v[194:197], v[80:83]
	s_waitcnt lgkmcnt(0)
	v_mfma_f32_16x16x32_bf16 v[108:111], v[198:201], v[166:169], v[108:111]
	v_mfma_f32_16x16x32_bf16 v[100:103], v[206:209], v[166:169], v[100:103]
	v_mfma_f32_16x16x32_bf16 v[92:95], v[198:201], v[174:177], v[92:95]
	v_mfma_f32_16x16x32_bf16 v[84:87], v[206:209], v[174:177], v[84:87]
	v_mfma_f32_16x16x32_bf16 v[76:79], v[198:201], v[182:185], v[76:79]
	v_mfma_f32_16x16x32_bf16 v[72:75], v[206:209], v[182:185], v[72:75]
	v_mfma_f32_16x16x32_bf16 v[68:71], v[198:201], v[190:193], v[68:71]
	v_mfma_f32_16x16x32_bf16 v[64:67], v[206:209], v[190:193], v[64:67]
	v_mfma_f32_16x16x32_bf16 v[108:111], v[202:205], v[170:173], v[108:111]
	v_mfma_f32_16x16x32_bf16 v[100:103], v[210:213], v[170:173], v[100:103]
	v_mfma_f32_16x16x32_bf16 v[92:95], v[202:205], v[178:181], v[92:95]
	v_mfma_f32_16x16x32_bf16 v[84:87], v[210:213], v[178:181], v[84:87]
	v_mfma_f32_16x16x32_bf16 v[76:79], v[202:205], v[186:189], v[76:79]
	v_mfma_f32_16x16x32_bf16 v[72:75], v[210:213], v[186:189], v[72:75]
	v_mfma_f32_16x16x32_bf16 v[68:71], v[202:205], v[194:197], v[68:71]
	v_mfma_f32_16x16x32_bf16 v[64:67], v[210:213], v[194:197], v[64:67]
	s_barrier
	s_setprio 0
	s_add_i32 s21, s48, s28
	s_mov_b32 m0, s21
	s_nop 0
	global_load_lds_dwordx4 v132, s[98:99]
	s_add_i32 m0, s21, 0x2000
	s_nop 0
	global_load_lds_dwordx4 v128, s[98:99]
	s_mov_b32 m0, s35
	s_nop 0
	global_load_lds_dwordx4 v134, s[100:101]
	s_mov_b32 m0, s36
	s_nop 0
	global_load_lds_dwordx4 v130, s[100:101]
	ds_read_b128 v[166:169], v160 offset:49152
	ds_read_b128 v[170:173], v160 offset:50176
	ds_read_b128 v[174:177], v160 offset:51200
	ds_read_b128 v[178:181], v160 offset:52224
	ds_read_b128 v[182:185], v160 offset:53248
	ds_read_b128 v[186:189], v160 offset:54272
	ds_read_b128 v[190:193], v160 offset:55296
	ds_read_b128 v[194:197], v160 offset:56320
	s_add_u32 s18, s18, 0x160080
	s_addc_u32 s19, s19, 0
	s_add_i32 s20, s20, s28
	s_add_i32 s47, s47, 2
	s_add_u32 s16, s16, 0x100
	s_addc_u32 s17, s17, 0
	s_add_u32 s45, s45, 0x100
	s_addc_u32 s46, s46, 0
	s_cmpk_gt_u32 s47, 0x55
	s_waitcnt vmcnt(6)
	s_waitcnt lgkmcnt(0)
	s_setprio 1
	s_barrier
	v_mfma_f32_16x16x32_bf16 v[60:63], v[144:147], v[166:169], v[60:63]
	s_mov_b32 m0, s20
	v_mfma_f32_16x16x32_bf16 v[56:59], v[152:155], v[166:169], v[56:59]
	global_load_lds_dwordx4 v132, s[18:19]
	v_mfma_f32_16x16x32_bf16 v[52:55], v[144:147], v[174:177], v[52:55]
	s_bitset1_b32 m0, 13
	v_mfma_f32_16x16x32_bf16 v[44:47], v[152:155], v[174:177], v[44:47]
	global_load_lds_dwordx4 v128, s[18:19]
	v_mfma_f32_16x16x32_bf16 v[36:39], v[144:147], v[182:185], v[36:39]
	v_mfma_f32_16x16x32_bf16 v[28:31], v[152:155], v[182:185], v[28:31]
	v_mfma_f32_16x16x32_bf16 v[20:23], v[144:147], v[190:193], v[20:23]
	v_mfma_f32_16x16x32_bf16 v[12:15], v[152:155], v[190:193], v[12:15]
	v_mfma_f32_16x16x32_bf16 v[60:63], v[148:151], v[170:173], v[60:63]
	v_mfma_f32_16x16x32_bf16 v[56:59], v[162:165], v[170:173], v[56:59]
	v_mfma_f32_16x16x32_bf16 v[52:55], v[148:151], v[178:181], v[52:55]
	v_mfma_f32_16x16x32_bf16 v[44:47], v[162:165], v[178:181], v[44:47]
	v_mfma_f32_16x16x32_bf16 v[36:39], v[148:151], v[186:189], v[36:39]
	v_mfma_f32_16x16x32_bf16 v[28:31], v[162:165], v[186:189], v[28:31]
	v_mfma_f32_16x16x32_bf16 v[20:23], v[148:151], v[194:197], v[20:23]
	v_mfma_f32_16x16x32_bf16 v[12:15], v[162:165], v[194:197], v[12:15]
	v_mfma_f32_16x16x32_bf16 v[48:51], v[198:201], v[166:169], v[48:51]
	v_mfma_f32_16x16x32_bf16 v[40:43], v[206:209], v[166:169], v[40:43]
	v_mfma_f32_16x16x32_bf16 v[32:35], v[198:201], v[174:177], v[32:35]
	v_mfma_f32_16x16x32_bf16 v[24:27], v[206:209], v[174:177], v[24:27]
	v_mfma_f32_16x16x32_bf16 v[16:19], v[198:201], v[182:185], v[16:19]
	v_mfma_f32_16x16x32_bf16 v[8:11], v[206:209], v[182:185], v[8:11]
	v_mfma_f32_16x16x32_bf16 v[4:7], v[198:201], v[190:193], v[4:7]
	v_mfma_f32_16x16x32_bf16 v[0:3], v[206:209], v[190:193], v[0:3]
	v_mfma_f32_16x16x32_bf16 v[48:51], v[202:205], v[170:173], v[48:51]
	v_mfma_f32_16x16x32_bf16 v[40:43], v[210:213], v[170:173], v[40:43]
	v_mfma_f32_16x16x32_bf16 v[32:35], v[202:205], v[178:181], v[32:35]
	v_mfma_f32_16x16x32_bf16 v[24:27], v[210:213], v[178:181], v[24:27]
	v_mfma_f32_16x16x32_bf16 v[16:19], v[202:205], v[186:189], v[16:19]
	v_mfma_f32_16x16x32_bf16 v[8:11], v[210:213], v[186:189], v[8:11]
	v_mfma_f32_16x16x32_bf16 v[4:7], v[202:205], v[194:197], v[4:7]
	v_mfma_f32_16x16x32_bf16 v[0:3], v[210:213], v[194:197], v[0:3]
	s_barrier
;   DI void operator()(const f32x4 (&acc)[2][2][4][2], const Unit& u, int wr, int wc, int fr, int fq) const {
;     const int row0 = u.pm * BM + wr * 64 + fr, col0 = u.pn * BM + wc * 32 + 8 * fq;
; #pragma unroll
;     for (int ai = 0; ai < 2; ++ai) {
;       f32x4 bv[4][2][2];
; #pragma unroll
;       for (int m = 0; m < 4; ++m)
; #pragma unroll
;         for (int bj = 0; bj < 2; ++bj) {
;           const float* bp = base + (size_t)(row0 + ai * HALF + m * 16) * 2048 + col0 + bj * HALF;
;           bv[m][bj][0] = *(const f32x4*)bp; bv[m][bj][1] = *(const f32x4*)(bp + 4);
;         }
; #pragma unroll
;       for (int m = 0; m < 4; ++m) {
;         const int row = row0 + ai * HALF + m * 16;
;         const size_t off = (size_t)row * 2048 + col0;
;         float ss = 0.f;
; #pragma unroll
;         for (int bj = 0; bj < 2; ++bj) {
;           const f32x4 v0 = acc[ai][bj][m][0] + bv[m][bj][0], v1 = acc[ai][bj][m][1] + bv[m][bj][1];
;           *(f32x4*)(C + off + bj * HALF) = v0; *(f32x4*)(C + off + bj * HALF + 4) = v1;
	s_setprio 0
	s_cbranch_scc0 .LBB0_1424
	v_lshl_or_b32 v144, s44, 8, v158
	v_lshl_add_u32 v154, s43, 8, v156
	v_ashrrev_i32_e32 v145, 31, v144
	v_lshlrev_b64 v[144:145], 2, v[144:145]
	v_ashrrev_i32_e32 v155, 31, v154
	v_lshl_add_u64 v[146:147], s[54:55], 0, v[144:145]
	v_lshlrev_b64 v[148:149], 13, v[154:155]
	v_or_b32_e32 v174, 16, v154
	v_lshl_add_u64 v[170:171], v[146:147], 0, v[148:149]
	v_ashrrev_i32_e32 v175, 31, v174
	global_load_dwordx4 v[150:153], v[170:171], off offset:16
	global_load_dwordx4 v[162:165], v[170:171], off
	global_load_dwordx4 v[166:169], v[170:171], off offset:528
	s_nop 0
	global_load_dwordx4 v[170:173], v[170:171], off offset:512
	v_lshlrev_b64 v[222:223], 13, v[174:175]
	v_or_b32_e32 v190, 32, v154
	v_lshl_add_u64 v[186:187], v[146:147], 0, v[222:223]
	v_ashrrev_i32_e32 v191, 31, v190
	global_load_dwordx4 v[174:177], v[186:187], off offset:16
	global_load_dwordx4 v[178:181], v[186:187], off
	global_load_dwordx4 v[182:185], v[186:187], off offset:528
	s_nop 0
	global_load_dwordx4 v[186:189], v[186:187], off offset:512
	v_lshlrev_b64 v[224:225], 13, v[190:191]
	v_or_b32_e32 v154, 48, v154
	v_lshl_add_u64 v[202:203], v[146:147], 0, v[224:225]
	v_ashrrev_i32_e32 v155, 31, v154
	global_load_dwordx4 v[190:193], v[202:203], off offset:16
	global_load_dwordx4 v[194:197], v[202:203], off
	global_load_dwordx4 v[198:201], v[202:203], off offset:528
	s_nop 0
	global_load_dwordx4 v[202:205], v[202:203], off offset:512
	v_lshlrev_b64 v[154:155], 13, v[154:155]
	v_lshl_add_u64 v[218:219], v[146:147], 0, v[154:155]
	global_load_dwordx4 v[206:209], v[218:219], off offset:16
	global_load_dwordx4 v[210:213], v[218:219], off
	global_load_dwordx4 v[214:217], v[218:219], off offset:528
	s_nop 0
	global_load_dwordx4 v[218:221], v[218:219], off offset:512
	s_and_b64 vcc, exec, s[0:1]
	s_mov_b32 s44, s41
	s_mov_b32 s43, s42
	s_mov_b64 s[18:19], s[4:5]
	s_mov_b64 s[16:17], s[2:3]
	s_waitcnt vmcnt(0)
	v_pk_add_f32 v[120:121], v[120:121], v[150:151]
	v_lshl_add_u64 v[150:151], s[54:55], 0, v[148:149]
	v_pk_add_f32 v[126:127], v[126:127], v[164:165]
	v_pk_add_f32 v[124:125], v[124:125], v[162:163]
	v_lshl_add_u64 v[150:151], v[150:151], 0, v[144:145]
	v_pk_add_f32 v[110:111], v[110:111], v[172:173]
	v_pk_add_f32 v[108:109], v[108:109], v[170:171]
	v_pk_add_f32 v[122:123], v[122:123], v[152:153]
	global_store_dwordx4 v[150:151], v[124:127], off
	global_store_dwordx4 v[150:151], v[120:123], off offset:16
	v_pk_add_f32 v[102:103], v[102:103], v[168:169]
	v_pk_add_f32 v[100:101], v[100:101], v[166:167]
	global_store_dwordx4 v[150:151], v[108:111], off offset:512
	global_store_dwordx4 v[150:151], v[100:103], off offset:528
	v_pk_add_f32 v[94:95], v[94:95], v[188:189]
	v_pk_add_f32 v[108:109], v[112:113], v[174:175]
	v_lshl_add_u64 v[112:113], s[54:55], 0, v[222:223]
	v_pk_add_f32 v[102:103], v[118:119], v[180:181]
	v_pk_add_f32 v[100:101], v[116:117], v[178:179]
	v_lshl_add_u64 v[112:113], v[112:113], 0, v[144:145]
	v_pk_add_f32 v[92:93], v[92:93], v[186:187]
	v_pk_add_f32 v[110:111], v[114:115], v[176:177]
	global_store_dwordx4 v[112:113], v[100:103], off
	global_store_dwordx4 v[112:113], v[108:111], off offset:16
	v_pk_add_f32 v[86:87], v[86:87], v[184:185]
	v_pk_add_f32 v[84:85], v[84:85], v[182:183]
	global_store_dwordx4 v[112:113], v[92:95], off offset:512
	global_store_dwordx4 v[112:113], v[84:87], off offset:528
	v_pk_add_f32 v[78:79], v[78:79], v[204:205]
	v_pk_add_f32 v[92:93], v[96:97], v[190:191]
	v_lshl_add_u64 v[96:97], s[54:55], 0, v[224:225]
	v_pk_add_f32 v[86:87], v[106:107], v[196:197]
	v_pk_add_f32 v[84:85], v[104:105], v[194:195]
	v_lshl_add_u64 v[96:97], v[96:97], 0, v[144:145]
	v_pk_add_f32 v[76:77], v[76:77], v[202:203]
	v_pk_add_f32 v[94:95], v[98:99], v[192:193]
	global_store_dwordx4 v[96:97], v[84:87], off
	global_store_dwordx4 v[96:97], v[92:95], off offset:16
	v_pk_add_f32 v[74:75], v[74:75], v[200:201]
	v_pk_add_f32 v[72:73], v[72:73], v[198:199]
	global_store_dwordx4 v[96:97], v[76:79], off offset:512
	global_store_dwordx4 v[96:97], v[72:75], off offset:528
	v_pk_add_f32 v[70:71], v[70:71], v[220:221]
	v_pk_add_f32 v[76:77], v[80:81], v[206:207]
	v_lshl_add_u64 v[80:81], s[54:55], 0, v[154:155]
	v_pk_add_f32 v[74:75], v[90:91], v[212:213]
	v_pk_add_f32 v[72:73], v[88:89], v[210:211]
	v_lshl_add_u64 v[80:81], v[80:81], 0, v[144:145]
	v_pk_add_f32 v[68:69], v[68:69], v[218:219]
	v_pk_add_f32 v[64:65], v[64:65], v[214:215]
	v_lshl_add_u64 v[154:155], v[148:149], 0, s[10:11]
	v_pk_add_f32 v[78:79], v[82:83], v[208:209]
	global_store_dwordx4 v[80:81], v[72:75], off
	global_store_dwordx4 v[80:81], v[76:79], off offset:16
	v_pk_add_f32 v[66:67], v[66:67], v[216:217]
	global_store_dwordx4 v[80:81], v[68:71], off offset:512
	global_store_dwordx4 v[80:81], v[64:67], off offset:528
	v_lshl_add_u64 v[152:153], v[148:149], 0, s[12:13]
	v_lshl_add_u64 v[150:151], v[148:149], 0, s[14:15]
	v_lshl_add_u64 v[64:65], v[146:147], 0, v[154:155]
	global_load_dwordx4 v[108:111], v[64:65], off offset:16
	global_load_dwordx4 v[120:123], v[64:65], off
	global_load_dwordx4 v[92:95], v[64:65], off offset:528
	global_load_dwordx4 v[100:103], v[64:65], off offset:512
	v_lshl_add_u64 v[64:65], v[146:147], 0, v[152:153]
	global_load_dwordx4 v[88:91], v[64:65], off offset:16
	global_load_dwordx4 v[96:99], v[64:65], off
	global_load_dwordx4 v[76:79], v[64:65], off offset:528
	global_load_dwordx4 v[84:87], v[64:65], off offset:512
	v_lshl_add_u64 v[68:69], v[146:147], 0, v[150:151]
	global_load_dwordx4 v[72:75], v[68:69], off offset:16
	global_load_dwordx4 v[80:83], v[68:69], off
	global_load_dwordx4 v[64:67], v[68:69], off offset:528
	s_nop 0
	global_load_dwordx4 v[68:71], v[68:69], off offset:512
	v_lshl_add_u64 v[148:149], v[148:149], 0, s[6:7]
	v_lshl_add_u64 v[112:113], v[146:147], 0, v[148:149]
	global_load_dwordx4 v[116:119], v[112:113], off offset:16
	global_load_dwordx4 v[124:127], v[112:113], off
	global_load_dwordx4 v[104:107], v[112:113], off offset:528
	s_nop 0
	global_load_dwordx4 v[112:115], v[112:113], off offset:512
	s_waitcnt vmcnt(0)
; #define PG8_WAIT_V(n) asm volatile("s_waitcnt vmcnt(" #n ")" ::: "memory")
; #define PG8_BAR __builtin_amdgcn_s_barrier()
;   DI void operator()(const f32x4 (&acc)[2][2][4][2], const Unit& u, int wr, int wc, int fr, int fq) const {
;     ...
;         const size_t off = (size_t)row * 2048 + col0;
;         float ss = 0.f;
; #pragma unroll
;         for (int bj = 0; bj < 2; ++bj) {
;           const f32x4 v0 = acc[ai][bj][m][0] + bv[m][bj][0], v1 = acc[ai][bj][m][1] + bv[m][bj][1];
;           *(f32x4*)(C + off + bj * HALF) = v0; *(f32x4*)(C + off + bj * HALF + 4) = v1;
; template <class Epi, class Sched = StaticOrder>
; DI void gemm_phase(LAS unsigned char* lds, const Gemm g, const Sched& S, const Epi& E) {
;     ...
;     if (!has_next) break;
; #pragma unroll
;     for (int a = 0; a < 2; ++a)
; #pragma unroll
;       for (int b = 0; b < 2; ++b)
; #pragma unroll
;         for (int m = 0; m < 4; ++m)
; #pragma unroll
;           for (int n = 0; n < 2; ++n) acc[a][b][m][n] = (f32x4){0.f, 0.f, 0.f, 0.f};
;     cur = nxt; cA = nA; cB = nB; ++ui;
;   }
;   PG8_WAIT_V(0);
;   if (wr == 0) PG8_BAR;
;   PG8_BAR;
	v_pk_add_f32 v[56:57], v[56:57], v[108:109]
	v_lshl_add_u64 v[108:109], s[54:55], 0, v[154:155]
	v_pk_add_f32 v[62:63], v[62:63], v[122:123]
	v_pk_add_f32 v[60:61], v[60:61], v[120:121]
	v_lshl_add_u64 v[108:109], v[108:109], 0, v[144:145]
	v_pk_add_f32 v[50:51], v[50:51], v[102:103]
	v_pk_add_f32 v[48:49], v[48:49], v[100:101]
	v_pk_add_f32 v[58:59], v[58:59], v[110:111]
	global_store_dwordx4 v[108:109], v[60:63], off
	global_store_dwordx4 v[108:109], v[56:59], off offset:16
	v_pk_add_f32 v[42:43], v[42:43], v[94:95]
	v_pk_add_f32 v[40:41], v[40:41], v[92:93]
	global_store_dwordx4 v[108:109], v[48:51], off offset:512
	global_store_dwordx4 v[108:109], v[40:43], off offset:528
	v_pk_add_f32 v[34:35], v[34:35], v[86:87]
	v_lshl_add_u64 v[48:49], s[54:55], 0, v[152:153]
	v_pk_add_f32 v[42:43], v[54:55], v[98:99]
	v_pk_add_f32 v[40:41], v[52:53], v[96:97]
	v_lshl_add_u64 v[48:49], v[48:49], 0, v[144:145]
	v_pk_add_f32 v[32:33], v[32:33], v[84:85]
	v_pk_add_f32 v[46:47], v[46:47], v[90:91]
	v_pk_add_f32 v[44:45], v[44:45], v[88:89]
	global_store_dwordx4 v[48:49], v[40:43], off
	global_store_dwordx4 v[48:49], v[44:47], off offset:16
	v_pk_add_f32 v[26:27], v[26:27], v[78:79]
	v_pk_add_f32 v[24:25], v[24:25], v[76:77]
	global_store_dwordx4 v[48:49], v[32:35], off offset:512
	global_store_dwordx4 v[48:49], v[24:27], off offset:528
	v_pk_add_f32 v[18:19], v[18:19], v[70:71]
	v_lshl_add_u64 v[32:33], s[54:55], 0, v[150:151]
	v_pk_add_f32 v[26:27], v[38:39], v[82:83]
	v_pk_add_f32 v[24:25], v[36:37], v[80:81]
	v_lshl_add_u64 v[32:33], v[32:33], 0, v[144:145]
	v_pk_add_f32 v[16:17], v[16:17], v[68:69]
	v_pk_add_f32 v[30:31], v[30:31], v[74:75]
	v_pk_add_f32 v[28:29], v[28:29], v[72:73]
	global_store_dwordx4 v[32:33], v[24:27], off
	global_store_dwordx4 v[32:33], v[28:31], off offset:16
	v_pk_add_f32 v[10:11], v[10:11], v[66:67]
	v_pk_add_f32 v[8:9], v[8:9], v[64:65]
	global_store_dwordx4 v[32:33], v[16:19], off offset:512
	global_store_dwordx4 v[32:33], v[8:11], off offset:528
	v_pk_add_f32 v[6:7], v[6:7], v[114:115]
	v_lshl_add_u64 v[16:17], s[54:55], 0, v[148:149]
	v_pk_add_f32 v[10:11], v[22:23], v[126:127]
	v_pk_add_f32 v[8:9], v[20:21], v[124:125]
	v_lshl_add_u64 v[16:17], v[16:17], 0, v[144:145]
	v_pk_add_f32 v[4:5], v[4:5], v[112:113]
	v_pk_add_f32 v[14:15], v[14:15], v[118:119]
	v_pk_add_f32 v[12:13], v[12:13], v[116:117]
	global_store_dwordx4 v[16:17], v[8:11], off
	global_store_dwordx4 v[16:17], v[12:15], off offset:16
	v_pk_add_f32 v[2:3], v[2:3], v[106:107]
	v_pk_add_f32 v[0:1], v[0:1], v[104:105]
	global_store_dwordx4 v[16:17], v[4:7], off offset:512
	global_store_dwordx4 v[16:17], v[0:3], off offset:528
	s_cbranch_vccz .LBB0_1417
	s_waitcnt vmcnt(0)
	s_cmpk_gt_u32 s23, 0xff
	s_cbranch_scc1 .LBB0_1428
	s_barrier
